# GEMM k-loop LDS fragment read hoist distance of three MFMAs ahead (with the two-group NA QK read hoist)
# baseline (speedup 1.0000x reference)
.LBB0_198:
	s_setprio 1
	ds_read_b128 v[140:143], v103
	ds_read_b128 v[144:147], v104 offset:36864
	ds_read_b128 v[148:151], v104 offset:41472
	ds_read_b128 v[192:195], v103 offset:4608
	s_waitcnt lgkmcnt(2)
	v_mfma_f32_32x32x16_bf16 v[48:63], v[140:143], v[144:147], v[48:63]
	ds_read_b128 v[196:199], v103 offset:32
	ds_read_b128 v[200:203], v104 offset:36896
	global_load_dwordx4 v[108:111], v168, s[98:99] offset:3840
	global_load_dwordx4 v[112:115], v170, s[98:99] offset:3840
	s_waitcnt vmcnt(9)
	ds_write_b128 v105, v[68:71] offset:18432
	s_waitcnt lgkmcnt(4)
	v_mfma_f32_32x32x16_bf16 v[32:47], v[140:143], v[148:151], v[32:47]
	ds_read_b128 v[204:207], v104 offset:41504
	global_load_dwordx4 v[116:119], v172, s[98:99] offset:3840
	global_load_dwordx4 v[120:123], v174, s[98:99] offset:3840
	s_waitcnt lgkmcnt(4)
	v_mfma_f32_32x32x16_bf16 v[16:31], v[192:195], v[144:147], v[16:31]
	ds_read_b128 v[208:211], v103 offset:4640
	global_load_dwordx4 v[124:127], v176, s[98:99] offset:3840
	global_load_dwordx4 v[128:131], v178, s[98:99] offset:3840
	s_waitcnt vmcnt(11)
	ds_write_b128 v105, v[84:87] offset:23040
	v_mfma_f32_32x32x16_bf16 v[0:15], v[192:195], v[148:151], v[0:15]
	global_load_dwordx4 v[132:135], v180, s[98:99] offset:3840
	global_load_dwordx4 v[136:139], v182, s[98:99] offset:3840
	s_waitcnt lgkmcnt(4)
	v_mfma_f32_32x32x16_bf16 v[48:63], v[196:199], v[200:203], v[48:63]
	ds_read_b128 v[212:215], v103 offset:64
	ds_read_b128 v[216:219], v104 offset:36928
	s_waitcnt vmcnt(12)
	ds_write_b128 v105, v[88:91] offset:27648
	s_waitcnt lgkmcnt(5)
	v_mfma_f32_32x32x16_bf16 v[32:47], v[196:199], v[204:207], v[32:47]
	ds_read_b128 v[220:223], v104 offset:41536
	s_waitcnt lgkmcnt(5)
	v_mfma_f32_32x32x16_bf16 v[16:31], v[208:211], v[200:203], v[16:31]
	ds_read_b128 v[224:227], v103 offset:4672
	s_waitcnt vmcnt(11)
	ds_write_b128 v105, v[92:95] offset:32256
	v_mfma_f32_32x32x16_bf16 v[0:15], v[208:211], v[204:207], v[0:15]
	s_waitcnt lgkmcnt(4)
	v_mfma_f32_32x32x16_bf16 v[48:63], v[212:215], v[216:219], v[48:63]
	ds_read_b128 v[228:231], v103 offset:96
	ds_read_b128 v[140:143], v104 offset:36960
	ds_write_b128 v105, v[64:67] offset:55296
	s_waitcnt lgkmcnt(5)
	v_mfma_f32_32x32x16_bf16 v[32:47], v[212:215], v[220:223], v[32:47]
	ds_read_b128 v[144:147], v104 offset:41568
	s_waitcnt lgkmcnt(5)
	v_mfma_f32_32x32x16_bf16 v[16:31], v[224:227], v[216:219], v[16:31]
	ds_read_b128 v[148:151], v103 offset:4704
	s_waitcnt vmcnt(10)
	ds_write_b128 v105, v[72:75] offset:59904
	v_mfma_f32_32x32x16_bf16 v[0:15], v[224:227], v[220:223], v[0:15]
	s_waitcnt lgkmcnt(4)
	v_mfma_f32_32x32x16_bf16 v[48:63], v[228:231], v[140:143], v[48:63]
	s_waitcnt vmcnt(9)
	ds_write_b128 v105, v[76:79] offset:64512
	s_waitcnt lgkmcnt(3)
	v_mfma_f32_32x32x16_bf16 v[32:47], v[228:231], v[144:147], v[32:47]
	s_waitcnt lgkmcnt(2)
	v_mfma_f32_32x32x16_bf16 v[16:31], v[148:151], v[140:143], v[16:31]
	s_waitcnt vmcnt(8)
	ds_write_b128 v106, v[80:83] offset:13824
	v_mfma_f32_32x32x16_bf16 v[0:15], v[148:151], v[144:147], v[0:15]
	s_setprio 0
	s_waitcnt lgkmcnt(0)
	s_barrier
	s_setprio 1
	ds_read_b128 v[140:143], v103 offset:18432
	ds_read_b128 v[144:147], v104 offset:55296
	ds_read_b128 v[148:151], v104 offset:59904
	ds_read_b128 v[192:195], v103 offset:23040
	s_waitcnt lgkmcnt(2)
	v_mfma_f32_32x32x16_bf16 v[48:63], v[140:143], v[144:147], v[48:63]
	ds_read_b128 v[196:199], v103 offset:18464
	ds_read_b128 v[200:203], v104 offset:55328
	global_load_dwordx4 v[68:71], v168, s[98:99] offset:3968
	global_load_dwordx4 v[84:87], v170, s[98:99] offset:3968
	s_waitcnt vmcnt(9)
	ds_write_b128 v105, v[108:111]
	s_waitcnt lgkmcnt(4)
	v_mfma_f32_32x32x16_bf16 v[32:47], v[140:143], v[148:151], v[32:47]
	ds_read_b128 v[204:207], v104 offset:59936
	global_load_dwordx4 v[88:91], v172, s[98:99] offset:3968
	global_load_dwordx4 v[92:95], v174, s[98:99] offset:3968
	s_waitcnt lgkmcnt(4)
	v_mfma_f32_32x32x16_bf16 v[16:31], v[192:195], v[144:147], v[16:31]
	ds_read_b128 v[208:211], v103 offset:23072
	global_load_dwordx4 v[64:67], v176, s[98:99] offset:3968
	global_load_dwordx4 v[72:75], v178, s[98:99] offset:3968
	s_waitcnt vmcnt(12)
	ds_write_b128 v105, v[112:115] offset:4608
	v_mfma_f32_32x32x16_bf16 v[0:15], v[192:195], v[148:151], v[0:15]
	global_load_dwordx4 v[76:79], v180, s[98:99] offset:3968
	global_load_dwordx4 v[80:83], v182, s[98:99] offset:3968
	s_waitcnt lgkmcnt(4)
	v_mfma_f32_32x32x16_bf16 v[48:63], v[196:199], v[200:203], v[48:63]
	ds_read_b128 v[212:215], v103 offset:18496
	ds_read_b128 v[216:219], v104 offset:55360
	s_add_u32 s98, s98, 0x100
	s_addc_u32 s99, s99, 0
	s_add_i32 s6, s6, 2
	s_cmp_lt_u32 s6, 11
	s_waitcnt vmcnt(13)
	ds_write_b128 v105, v[116:119] offset:9216
	s_waitcnt lgkmcnt(5)
	v_mfma_f32_32x32x16_bf16 v[32:47], v[196:199], v[204:207], v[32:47]
	ds_read_b128 v[220:223], v104 offset:59968
	s_waitcnt lgkmcnt(5)
	v_mfma_f32_32x32x16_bf16 v[16:31], v[208:211], v[200:203], v[16:31]
	ds_read_b128 v[224:227], v103 offset:23104
	s_waitcnt vmcnt(12)
	ds_write_b128 v105, v[120:123] offset:13824
	v_mfma_f32_32x32x16_bf16 v[0:15], v[208:211], v[204:207], v[0:15]
	s_waitcnt lgkmcnt(4)
	v_mfma_f32_32x32x16_bf16 v[48:63], v[212:215], v[216:219], v[48:63]
	ds_read_b128 v[228:231], v103 offset:18528
	ds_read_b128 v[140:143], v104 offset:55392
	s_waitcnt vmcnt(11)
	ds_write_b128 v105, v[124:127] offset:36864
	s_waitcnt lgkmcnt(5)
	v_mfma_f32_32x32x16_bf16 v[32:47], v[212:215], v[220:223], v[32:47]
	ds_read_b128 v[144:147], v104 offset:60000
	s_waitcnt lgkmcnt(5)
	v_mfma_f32_32x32x16_bf16 v[16:31], v[224:227], v[216:219], v[16:31]
	ds_read_b128 v[148:151], v103 offset:23136
	s_waitcnt vmcnt(10)
	ds_write_b128 v105, v[128:131] offset:41472
	v_mfma_f32_32x32x16_bf16 v[0:15], v[224:227], v[220:223], v[0:15]
	s_waitcnt lgkmcnt(4)
	v_mfma_f32_32x32x16_bf16 v[48:63], v[228:231], v[140:143], v[48:63]
	s_waitcnt vmcnt(9)
	ds_write_b128 v105, v[132:135] offset:46080
	s_waitcnt lgkmcnt(3)
	v_mfma_f32_32x32x16_bf16 v[32:47], v[228:231], v[144:147], v[32:47]
	s_waitcnt lgkmcnt(2)
	v_mfma_f32_32x32x16_bf16 v[16:31], v[148:151], v[140:143], v[16:31]
	s_waitcnt vmcnt(8)
	ds_write_b128 v105, v[136:139] offset:50688
	v_mfma_f32_32x32x16_bf16 v[0:15], v[148:151], v[144:147], v[0:15]
	s_setprio 0
	s_waitcnt lgkmcnt(0)
	s_barrier
	s_cbranch_scc1 .LBB0_198
	s_setprio 1
	ds_read_b128 v[98:101], v103
	ds_read_b128 v[108:111], v104 offset:36864
	ds_read_b128 v[112:115], v104 offset:41472
	ds_read_b128 v[192:195], v103 offset:4608
	s_waitcnt lgkmcnt(2)
	v_mfma_f32_32x32x16_bf16 v[48:63], v[98:101], v[108:111], v[48:63]
	ds_read_b128 v[196:199], v103 offset:32
	ds_read_b128 v[200:203], v104 offset:36896
	s_waitcnt vmcnt(7)
	ds_write_b128 v105, v[68:71] offset:18432
	s_waitcnt lgkmcnt(4)
	v_mfma_f32_32x32x16_bf16 v[32:47], v[98:101], v[112:115], v[32:47]
	ds_read_b128 v[204:207], v104 offset:41504
	s_waitcnt lgkmcnt(4)
	v_mfma_f32_32x32x16_bf16 v[16:31], v[192:195], v[108:111], v[16:31]
	ds_read_b128 v[208:211], v103 offset:4640
	s_waitcnt vmcnt(6)
	ds_write_b128 v105, v[84:87] offset:23040
	v_mfma_f32_32x32x16_bf16 v[0:15], v[192:195], v[112:115], v[0:15]
	s_waitcnt lgkmcnt(4)
	v_mfma_f32_32x32x16_bf16 v[48:63], v[196:199], v[200:203], v[48:63]
	ds_read_b128 v[212:215], v103 offset:64
	ds_read_b128 v[216:219], v104 offset:36928
	s_waitcnt vmcnt(5)
	ds_write_b128 v105, v[88:91] offset:27648
	s_waitcnt lgkmcnt(5)
	v_mfma_f32_32x32x16_bf16 v[32:47], v[196:199], v[204:207], v[32:47]
	ds_read_b128 v[220:223], v104 offset:41536
	s_waitcnt lgkmcnt(5)
	v_mfma_f32_32x32x16_bf16 v[16:31], v[208:211], v[200:203], v[16:31]
	ds_read_b128 v[224:227], v103 offset:4672
	s_waitcnt vmcnt(4)
	ds_write_b128 v105, v[92:95] offset:32256
	v_mfma_f32_32x32x16_bf16 v[0:15], v[208:211], v[204:207], v[0:15]
	s_waitcnt lgkmcnt(4)
	v_mfma_f32_32x32x16_bf16 v[48:63], v[212:215], v[216:219], v[48:63]
	ds_read_b128 v[228:231], v103 offset:96
	ds_read_b128 v[98:101], v104 offset:36960
	s_waitcnt vmcnt(3)
	ds_write_b128 v105, v[64:67] offset:55296
	s_waitcnt lgkmcnt(5)
	v_mfma_f32_32x32x16_bf16 v[32:47], v[212:215], v[220:223], v[32:47]
	ds_read_b128 v[108:111], v104 offset:41568
	s_waitcnt lgkmcnt(5)
	v_mfma_f32_32x32x16_bf16 v[16:31], v[224:227], v[216:219], v[16:31]
	ds_read_b128 v[112:115], v103 offset:4704
	s_waitcnt vmcnt(2)
	ds_write_b128 v105, v[72:75] offset:59904
	v_mfma_f32_32x32x16_bf16 v[0:15], v[224:227], v[220:223], v[0:15]
	s_waitcnt lgkmcnt(4)
	v_mfma_f32_32x32x16_bf16 v[48:63], v[228:231], v[98:101], v[48:63]
	s_waitcnt vmcnt(1)
	ds_write_b128 v105, v[76:79] offset:64512
	s_waitcnt lgkmcnt(3)
	v_mfma_f32_32x32x16_bf16 v[32:47], v[228:231], v[108:111], v[32:47]
	s_waitcnt lgkmcnt(2)
	v_mfma_f32_32x32x16_bf16 v[16:31], v[112:115], v[98:101], v[16:31]
	s_waitcnt vmcnt(0)
	ds_write_b128 v106, v[80:83] offset:13824
	v_mfma_f32_32x32x16_bf16 v[0:15], v[112:115], v[108:111], v[0:15]
	s_setprio 0
	s_waitcnt lgkmcnt(0)
	s_barrier
	s_setprio 1
	ds_read_b128 v[64:67], v103 offset:18432
	ds_read_b128 v[68:71], v104 offset:55296
	ds_read_b128 v[72:75], v104 offset:59904
	ds_read_b128 v[192:195], v103 offset:23040
	s_waitcnt lgkmcnt(2)
	v_mfma_f32_32x32x16_bf16 v[48:63], v[64:67], v[68:71], v[48:63]
	ds_read_b128 v[196:199], v103 offset:18464
	ds_read_b128 v[200:203], v104 offset:55328
	s_waitcnt lgkmcnt(3)
	v_mfma_f32_32x32x16_bf16 v[32:47], v[64:67], v[72:75], v[32:47]
	ds_read_b128 v[204:207], v104 offset:59936
	s_waitcnt lgkmcnt(3)
	v_mfma_f32_32x32x16_bf16 v[16:31], v[192:195], v[68:71], v[16:31]
	ds_read_b128 v[208:211], v103 offset:23072
	v_mfma_f32_32x32x16_bf16 v[0:15], v[192:195], v[72:75], v[0:15]
	s_waitcnt lgkmcnt(2)
	v_mfma_f32_32x32x16_bf16 v[48:63], v[196:199], v[200:203], v[48:63]
	ds_read_b128 v[212:215], v103 offset:18496
	ds_read_b128 v[216:219], v104 offset:55360
	s_waitcnt lgkmcnt(3)
	v_mfma_f32_32x32x16_bf16 v[32:47], v[196:199], v[204:207], v[32:47]
	ds_read_b128 v[220:223], v104 offset:59968
	s_waitcnt lgkmcnt(3)
	v_mfma_f32_32x32x16_bf16 v[16:31], v[208:211], v[200:203], v[16:31]
	ds_read_b128 v[224:227], v103 offset:23104
	v_mfma_f32_32x32x16_bf16 v[0:15], v[208:211], v[204:207], v[0:15]
	s_waitcnt lgkmcnt(2)
	v_mfma_f32_32x32x16_bf16 v[48:63], v[212:215], v[216:219], v[48:63]
	ds_read_b128 v[228:231], v103 offset:18528
	ds_read_b128 v[64:67], v104 offset:55392
	s_waitcnt lgkmcnt(3)
	v_mfma_f32_32x32x16_bf16 v[32:47], v[212:215], v[220:223], v[32:47]
	ds_read_b128 v[68:71], v104 offset:60000
	s_waitcnt lgkmcnt(3)
	v_mfma_f32_32x32x16_bf16 v[16:31], v[224:227], v[216:219], v[16:31]
	ds_read_b128 v[72:75], v103 offset:23136
	v_mfma_f32_32x32x16_bf16 v[0:15], v[224:227], v[220:223], v[0:15]
	s_waitcnt lgkmcnt(2)
	v_mfma_f32_32x32x16_bf16 v[48:63], v[228:231], v[64:67], v[48:63]
	s_waitcnt lgkmcnt(1)
	v_mfma_f32_32x32x16_bf16 v[32:47], v[228:231], v[68:71], v[32:47]
	s_waitcnt lgkmcnt(0)
	v_mfma_f32_32x32x16_bf16 v[16:31], v[72:75], v[64:67], v[16:31]
	v_mfma_f32_32x32x16_bf16 v[0:15], v[72:75], v[68:71], v[0:15]
	s_setprio 0
	s_cmpk_gt_u32 s24, 0xfff
	s_cselect_b64 s[12:13], -1, 0
	s_cmpk_lt_u32 s24, 0x1000
	s_cselect_b64 s[48:49], -1, 0
	s_ashr_i32 s76, s2, 2
	s_cmp_lt_i32 s76, 7
	s_barrier
	s_cbranch_scc1 .LBB0_201
	s_cmp_lg_u32 s76, 7
	s_cselect_b64 s[6:7], -1, 0
	s_cbranch_execz .LBB0_202
	s_branch .LBB0_203

.LBB0_1745:
	s_setprio 1
	ds_read_b128 v[148:151], v144
	ds_read_b128 v[152:155], v145 offset:36864
	ds_read_b128 v[156:159], v145 offset:41472
	ds_read_b128 v[192:195], v144 offset:4608
	s_waitcnt lgkmcnt(2)
	v_mfma_f32_32x32x16_bf16 v[48:63], v[148:151], v[152:155], v[48:63]
	ds_read_b128 v[196:199], v144 offset:32
	ds_read_b128 v[200:203], v145 offset:36896
	global_load_dwordx4 v[96:99], v160, s[98:99] offset:256
	global_load_dwordx4 v[100:103], v164, s[98:99] offset:256
	s_waitcnt vmcnt(9)
	ds_write_b128 v146, v[64:67] offset:18432
	s_waitcnt lgkmcnt(4)
	v_mfma_f32_32x32x16_bf16 v[32:47], v[148:151], v[156:159], v[32:47]
	ds_read_b128 v[204:207], v145 offset:41504
	global_load_dwordx4 v[104:107], v166, s[98:99] offset:256
	global_load_dwordx4 v[108:111], v168, s[98:99] offset:256
	s_waitcnt lgkmcnt(4)
	v_mfma_f32_32x32x16_bf16 v[16:31], v[192:195], v[152:155], v[16:31]
	ds_read_b128 v[208:211], v144 offset:4640
	global_load_dwordx4 v[112:115], v162, s[98:99]
	global_load_dwordx4 v[116:119], v130, s[98:99]
	s_waitcnt vmcnt(12)
	ds_write_b128 v146, v[68:71] offset:23040
	v_mfma_f32_32x32x16_bf16 v[0:15], v[192:195], v[156:159], v[0:15]
	global_load_dwordx4 v[120:123], v170, s[98:99]
	global_load_dwordx4 v[124:127], v172, s[98:99] offset:-128
	s_waitcnt lgkmcnt(4)
	v_mfma_f32_32x32x16_bf16 v[48:63], v[196:199], v[200:203], v[48:63]
	ds_read_b128 v[212:215], v144 offset:64
	ds_read_b128 v[216:219], v145 offset:36928
	s_waitcnt vmcnt(13)
	ds_write_b128 v146, v[72:75] offset:27648
	s_waitcnt lgkmcnt(5)
	v_mfma_f32_32x32x16_bf16 v[32:47], v[196:199], v[204:207], v[32:47]
	ds_read_b128 v[220:223], v145 offset:41536
	s_waitcnt lgkmcnt(5)
	v_mfma_f32_32x32x16_bf16 v[16:31], v[208:211], v[200:203], v[16:31]
	ds_read_b128 v[224:227], v144 offset:4672
	s_waitcnt vmcnt(12)
	ds_write_b128 v146, v[76:79] offset:32256
	v_mfma_f32_32x32x16_bf16 v[0:15], v[208:211], v[204:207], v[0:15]
	s_waitcnt lgkmcnt(4)
	v_mfma_f32_32x32x16_bf16 v[48:63], v[212:215], v[216:219], v[48:63]
	ds_read_b128 v[228:231], v144 offset:96
	ds_read_b128 v[148:151], v145 offset:36960
	s_waitcnt vmcnt(11)
	ds_write_b128 v146, v[80:83] offset:55296
	s_waitcnt lgkmcnt(5)
	v_mfma_f32_32x32x16_bf16 v[32:47], v[212:215], v[220:223], v[32:47]
	ds_read_b128 v[152:155], v145 offset:41568
	s_waitcnt lgkmcnt(5)
	v_mfma_f32_32x32x16_bf16 v[16:31], v[224:227], v[216:219], v[16:31]
	ds_read_b128 v[156:159], v144 offset:4704
	s_waitcnt vmcnt(10)
	ds_write_b128 v146, v[84:87] offset:59904
	v_mfma_f32_32x32x16_bf16 v[0:15], v[224:227], v[220:223], v[0:15]
	s_waitcnt lgkmcnt(4)
	v_mfma_f32_32x32x16_bf16 v[48:63], v[228:231], v[148:151], v[48:63]
	s_waitcnt vmcnt(9)
	ds_write_b128 v146, v[88:91] offset:64512
	s_waitcnt lgkmcnt(3)
	v_mfma_f32_32x32x16_bf16 v[32:47], v[228:231], v[152:155], v[32:47]
	s_waitcnt lgkmcnt(2)
	v_mfma_f32_32x32x16_bf16 v[16:31], v[156:159], v[148:151], v[16:31]
	s_waitcnt vmcnt(8)
	ds_write_b128 v147, v[92:95] offset:13824
	v_mfma_f32_32x32x16_bf16 v[0:15], v[156:159], v[152:155], v[0:15]
	s_setprio 0
	s_waitcnt lgkmcnt(0)
	s_barrier
	s_setprio 1
	ds_read_b128 v[148:151], v144 offset:18432
	ds_read_b128 v[152:155], v145 offset:55296
	ds_read_b128 v[156:159], v145 offset:59904
	ds_read_b128 v[192:195], v144 offset:23040
	s_waitcnt lgkmcnt(2)
	v_mfma_f32_32x32x16_bf16 v[48:63], v[148:151], v[152:155], v[48:63]
	ds_read_b128 v[196:199], v144 offset:18464
	ds_read_b128 v[200:203], v145 offset:55328
	global_load_dwordx4 v[64:67], v160, s[98:99] offset:384
	global_load_dwordx4 v[68:71], v164, s[98:99] offset:384
	s_waitcnt vmcnt(9)
	ds_write_b128 v146, v[96:99]
	s_waitcnt lgkmcnt(4)
	v_mfma_f32_32x32x16_bf16 v[32:47], v[148:151], v[156:159], v[32:47]
	ds_read_b128 v[204:207], v145 offset:59936
	global_load_dwordx4 v[72:75], v166, s[98:99] offset:384
	global_load_dwordx4 v[76:79], v168, s[98:99] offset:384
	s_waitcnt lgkmcnt(4)
	v_mfma_f32_32x32x16_bf16 v[16:31], v[192:195], v[152:155], v[16:31]
	ds_read_b128 v[208:211], v144 offset:23072
	global_load_dwordx4 v[80:83], v162, s[98:99] offset:128
	global_load_dwordx4 v[84:87], v131, s[98:99]
	s_waitcnt vmcnt(12)
	ds_write_b128 v146, v[100:103] offset:4608
	v_mfma_f32_32x32x16_bf16 v[0:15], v[192:195], v[156:159], v[0:15]
	global_load_dwordx4 v[88:91], v170, s[98:99] offset:128
	global_load_dwordx4 v[92:95], v172, s[98:99]
	s_waitcnt lgkmcnt(4)
	v_mfma_f32_32x32x16_bf16 v[48:63], v[196:199], v[200:203], v[48:63]
	ds_read_b128 v[212:215], v144 offset:18496
	ds_read_b128 v[216:219], v145 offset:55360
	s_add_u32 s98, s98, 0x100
	s_addc_u32 s99, s99, 0
	s_add_i32 s0, s0, 2
	s_cmp_lt_u32 s0, 3
	s_waitcnt vmcnt(13)
	ds_write_b128 v146, v[104:107] offset:9216
	s_waitcnt lgkmcnt(5)
	v_mfma_f32_32x32x16_bf16 v[32:47], v[196:199], v[204:207], v[32:47]
	ds_read_b128 v[220:223], v145 offset:59968
	s_waitcnt lgkmcnt(5)
	v_mfma_f32_32x32x16_bf16 v[16:31], v[208:211], v[200:203], v[16:31]
	ds_read_b128 v[224:227], v144 offset:23104
	s_waitcnt vmcnt(12)
	ds_write_b128 v146, v[108:111] offset:13824
	v_mfma_f32_32x32x16_bf16 v[0:15], v[208:211], v[204:207], v[0:15]
	s_waitcnt lgkmcnt(4)
	v_mfma_f32_32x32x16_bf16 v[48:63], v[212:215], v[216:219], v[48:63]
	ds_read_b128 v[228:231], v144 offset:18528
	ds_read_b128 v[148:151], v145 offset:55392
	s_waitcnt vmcnt(11)
	ds_write_b128 v146, v[112:115] offset:36864
	s_waitcnt lgkmcnt(5)
	v_mfma_f32_32x32x16_bf16 v[32:47], v[212:215], v[220:223], v[32:47]
	ds_read_b128 v[152:155], v145 offset:60000
	s_waitcnt lgkmcnt(5)
	v_mfma_f32_32x32x16_bf16 v[16:31], v[224:227], v[216:219], v[16:31]
	ds_read_b128 v[156:159], v144 offset:23136
	s_waitcnt vmcnt(10)
	ds_write_b128 v146, v[116:119] offset:41472
	v_mfma_f32_32x32x16_bf16 v[0:15], v[224:227], v[220:223], v[0:15]
	s_waitcnt lgkmcnt(4)
	v_mfma_f32_32x32x16_bf16 v[48:63], v[228:231], v[148:151], v[48:63]
	s_waitcnt vmcnt(9)
	ds_write_b128 v146, v[120:123] offset:46080
	s_waitcnt lgkmcnt(3)
	v_mfma_f32_32x32x16_bf16 v[32:47], v[228:231], v[152:155], v[32:47]
	s_waitcnt lgkmcnt(2)
	v_mfma_f32_32x32x16_bf16 v[16:31], v[156:159], v[148:151], v[16:31]
	s_waitcnt vmcnt(8)
	ds_write_b128 v146, v[124:127] offset:50688
	v_mfma_f32_32x32x16_bf16 v[0:15], v[156:159], v[152:155], v[0:15]
	s_setprio 0
	s_waitcnt lgkmcnt(0)
	s_barrier
	s_cbranch_scc1 .LBB0_1745
	s_setprio 1
	ds_read_b128 v[96:99], v144
	ds_read_b128 v[100:103], v145 offset:36864
	ds_read_b128 v[104:107], v145 offset:41472
	ds_read_b128 v[192:195], v144 offset:4608
	s_waitcnt lgkmcnt(2)
	v_mfma_f32_32x32x16_bf16 v[48:63], v[96:99], v[100:103], v[48:63]
	ds_read_b128 v[196:199], v144 offset:32
	ds_read_b128 v[200:203], v145 offset:36896
	s_waitcnt vmcnt(7)
	ds_write_b128 v146, v[64:67] offset:18432
	s_waitcnt lgkmcnt(4)
	v_mfma_f32_32x32x16_bf16 v[32:47], v[96:99], v[104:107], v[32:47]
	ds_read_b128 v[204:207], v145 offset:41504
	s_waitcnt lgkmcnt(4)
	v_mfma_f32_32x32x16_bf16 v[16:31], v[192:195], v[100:103], v[16:31]
	ds_read_b128 v[208:211], v144 offset:4640
	s_waitcnt vmcnt(6)
	ds_write_b128 v146, v[68:71] offset:23040
	v_mfma_f32_32x32x16_bf16 v[0:15], v[192:195], v[104:107], v[0:15]
	s_waitcnt lgkmcnt(4)
	v_mfma_f32_32x32x16_bf16 v[48:63], v[196:199], v[200:203], v[48:63]
	ds_read_b128 v[212:215], v144 offset:64
	ds_read_b128 v[216:219], v145 offset:36928
	s_waitcnt vmcnt(5)
	ds_write_b128 v146, v[72:75] offset:27648
	s_waitcnt lgkmcnt(5)
	v_mfma_f32_32x32x16_bf16 v[32:47], v[196:199], v[204:207], v[32:47]
	ds_read_b128 v[220:223], v145 offset:41536
	s_waitcnt lgkmcnt(5)
	v_mfma_f32_32x32x16_bf16 v[16:31], v[208:211], v[200:203], v[16:31]
	ds_read_b128 v[224:227], v144 offset:4672
	s_waitcnt vmcnt(4)
	ds_write_b128 v146, v[76:79] offset:32256
	v_mfma_f32_32x32x16_bf16 v[0:15], v[208:211], v[204:207], v[0:15]
	s_waitcnt lgkmcnt(4)
	v_mfma_f32_32x32x16_bf16 v[48:63], v[212:215], v[216:219], v[48:63]
	ds_read_b128 v[228:231], v144 offset:96
	ds_read_b128 v[96:99], v145 offset:36960
	s_waitcnt vmcnt(3)
	ds_write_b128 v146, v[80:83] offset:55296
	s_waitcnt lgkmcnt(5)
	v_mfma_f32_32x32x16_bf16 v[32:47], v[212:215], v[220:223], v[32:47]
	ds_read_b128 v[100:103], v145 offset:41568
	s_waitcnt lgkmcnt(5)
	v_mfma_f32_32x32x16_bf16 v[16:31], v[224:227], v[216:219], v[16:31]
	ds_read_b128 v[104:107], v144 offset:4704
	s_waitcnt vmcnt(2)
	ds_write_b128 v146, v[84:87] offset:59904
	v_mfma_f32_32x32x16_bf16 v[0:15], v[224:227], v[220:223], v[0:15]
	s_waitcnt lgkmcnt(4)
	v_mfma_f32_32x32x16_bf16 v[48:63], v[228:231], v[96:99], v[48:63]
	s_waitcnt vmcnt(1)
	ds_write_b128 v146, v[88:91] offset:64512
	s_waitcnt lgkmcnt(3)
	v_mfma_f32_32x32x16_bf16 v[32:47], v[228:231], v[100:103], v[32:47]
	s_waitcnt lgkmcnt(2)
	v_mfma_f32_32x32x16_bf16 v[16:31], v[104:107], v[96:99], v[16:31]
	s_waitcnt vmcnt(0)
	ds_write_b128 v147, v[92:95] offset:13824
	v_mfma_f32_32x32x16_bf16 v[0:15], v[104:107], v[100:103], v[0:15]
	s_setprio 0
	s_waitcnt lgkmcnt(0)
	s_barrier
	s_setprio 1
	ds_read_b128 v[64:67], v144 offset:18432
	ds_read_b128 v[68:71], v145 offset:55296
	ds_read_b128 v[72:75], v145 offset:59904
	ds_read_b128 v[192:195], v144 offset:23040
	s_waitcnt lgkmcnt(2)
	v_mfma_f32_32x32x16_bf16 v[48:63], v[64:67], v[68:71], v[48:63]
	ds_read_b128 v[196:199], v144 offset:18464
	ds_read_b128 v[200:203], v145 offset:55328
	s_waitcnt lgkmcnt(3)
	v_mfma_f32_32x32x16_bf16 v[32:47], v[64:67], v[72:75], v[32:47]
	ds_read_b128 v[204:207], v145 offset:59936
	s_waitcnt lgkmcnt(3)
	v_mfma_f32_32x32x16_bf16 v[16:31], v[192:195], v[68:71], v[16:31]
	ds_read_b128 v[208:211], v144 offset:23072
	v_mfma_f32_32x32x16_bf16 v[0:15], v[192:195], v[72:75], v[0:15]
	s_waitcnt lgkmcnt(2)
	v_mfma_f32_32x32x16_bf16 v[48:63], v[196:199], v[200:203], v[48:63]
	ds_read_b128 v[212:215], v144 offset:18496
	ds_read_b128 v[216:219], v145 offset:55360
	s_waitcnt lgkmcnt(3)
	v_mfma_f32_32x32x16_bf16 v[32:47], v[196:199], v[204:207], v[32:47]
	ds_read_b128 v[220:223], v145 offset:59968
	s_waitcnt lgkmcnt(3)
	v_mfma_f32_32x32x16_bf16 v[16:31], v[208:211], v[200:203], v[16:31]
	ds_read_b128 v[224:227], v144 offset:23104
	v_mfma_f32_32x32x16_bf16 v[0:15], v[208:211], v[204:207], v[0:15]
	s_waitcnt lgkmcnt(2)
	v_mfma_f32_32x32x16_bf16 v[48:63], v[212:215], v[216:219], v[48:63]
	ds_read_b128 v[228:231], v144 offset:18528
	ds_read_b128 v[64:67], v145 offset:55392
	s_waitcnt lgkmcnt(3)
	v_mfma_f32_32x32x16_bf16 v[32:47], v[212:215], v[220:223], v[32:47]
	ds_read_b128 v[68:71], v145 offset:60000
	s_waitcnt lgkmcnt(3)
	v_mfma_f32_32x32x16_bf16 v[16:31], v[224:227], v[216:219], v[16:31]
	ds_read_b128 v[72:75], v144 offset:23136
	v_mfma_f32_32x32x16_bf16 v[0:15], v[224:227], v[220:223], v[0:15]
	s_waitcnt lgkmcnt(2)
	v_mfma_f32_32x32x16_bf16 v[48:63], v[228:231], v[64:67], v[48:63]
	s_waitcnt lgkmcnt(1)
	v_mfma_f32_32x32x16_bf16 v[32:47], v[228:231], v[68:71], v[32:47]
	s_waitcnt lgkmcnt(0)
	v_mfma_f32_32x32x16_bf16 v[16:31], v[72:75], v[64:67], v[16:31]
	v_mfma_f32_32x32x16_bf16 v[0:15], v[72:75], v[68:71], v[0:15]
	s_setprio 0
	s_nop 6
	v_cvt_pk_bf16_f32 v32, v32, s0
	s_nop 2
	v_cvt_pk_bf16_f32 v0, v0, s0
	s_barrier
	ds_write_b16 v143, v32 offset:64
	v_cvt_pk_bf16_f32 v32, v49, s0
	ds_write_b16 v143, v0 offset:8768
	v_cvt_pk_bf16_f32 v0, v17, s0
	ds_write_b16 v143, v32 offset:272
	v_cvt_pk_bf16_f32 v32, v33, s0
	ds_write_b16 v143, v0 offset:8976
	v_cvt_pk_bf16_f32 v0, v1, s0
	ds_write_b16 v143, v32 offset:336
	v_cvt_pk_bf16_f32 v32, v50, s0
	ds_write_b16 v143, v0 offset:9040
	v_cvt_pk_bf16_f32 v0, v18, s0
	ds_write_b16 v143, v32 offset:544
	v_cvt_pk_bf16_f32 v32, v34, s0
	ds_write_b16 v143, v0 offset:9248
	v_cvt_pk_bf16_f32 v0, v2, s0
	ds_write_b16 v143, v32 offset:608
	v_cvt_pk_bf16_f32 v32, v51, s0
	ds_write_b16 v143, v0 offset:9312
	v_cvt_pk_bf16_f32 v0, v19, s0
	ds_write_b16 v143, v32 offset:816
	v_cvt_pk_bf16_f32 v32, v35, s0
	ds_write_b16 v143, v0 offset:9520
	v_cvt_pk_bf16_f32 v0, v3, s0
	ds_write_b16 v143, v32 offset:880
	v_cvt_pk_bf16_f32 v32, v52, s0
	ds_write_b16 v143, v0 offset:9584
	v_cvt_pk_bf16_f32 v0, v20, s0
	ds_write_b16 v143, v32 offset:2176
	v_cvt_pk_bf16_f32 v32, v36, s0
	ds_write_b16 v143, v0 offset:10880
	v_cvt_pk_bf16_f32 v0, v4, s0
	ds_write_b16 v143, v32 offset:2240
	v_cvt_pk_bf16_f32 v32, v53, s0
	ds_write_b16 v143, v0 offset:10944
	v_cvt_pk_bf16_f32 v0, v21, s0
	ds_write_b16 v143, v32 offset:2448
	v_cvt_pk_bf16_f32 v32, v37, s0
	ds_write_b16 v143, v0 offset:11152
	v_cvt_pk_bf16_f32 v0, v5, s0
	ds_write_b16 v143, v32 offset:2512
	v_cvt_pk_bf16_f32 v32, v54, s0
	ds_write_b16 v143, v0 offset:11216
	v_cvt_pk_bf16_f32 v0, v22, s0
	ds_write_b16 v143, v32 offset:2720
	v_cvt_pk_bf16_f32 v32, v38, s0
	ds_write_b16 v143, v0 offset:11424
	v_cvt_pk_bf16_f32 v0, v6, s0
	ds_write_b16 v143, v32 offset:2784
	v_cvt_pk_bf16_f32 v32, v55, s0
	ds_write_b16 v143, v0 offset:11488
	v_cvt_pk_bf16_f32 v0, v23, s0
	ds_write_b16 v143, v32 offset:2992
	v_cvt_pk_bf16_f32 v32, v39, s0
	ds_write_b16 v143, v0 offset:11696
	v_cvt_pk_bf16_f32 v0, v7, s0
	ds_write_b16 v143, v32 offset:3056
	v_cvt_pk_bf16_f32 v32, v56, s0
	ds_write_b16 v143, v0 offset:11760
	v_cvt_pk_bf16_f32 v0, v24, s0
	ds_write_b16 v143, v32 offset:4352
	v_cvt_pk_bf16_f32 v32, v40, s0
	ds_write_b16 v143, v0 offset:13056
	v_cvt_pk_bf16_f32 v0, v8, s0
	ds_write_b16 v143, v32 offset:4416
	v_cvt_pk_bf16_f32 v32, v57, s0
	ds_write_b16 v143, v0 offset:13120
	v_cvt_pk_bf16_f32 v0, v25, s0
	ds_write_b16 v143, v32 offset:4624
	v_cvt_pk_bf16_f32 v32, v41, s0
	ds_write_b16 v143, v0 offset:13328
	v_cvt_pk_bf16_f32 v0, v9, s0
	ds_write_b16 v143, v32 offset:4688
	v_cvt_pk_bf16_f32 v32, v58, s0
	ds_write_b16 v143, v0 offset:13392
	v_cvt_pk_bf16_f32 v0, v26, s0
	ds_write_b16 v143, v32 offset:4896
	v_cvt_pk_bf16_f32 v32, v42, s0
	ds_write_b16 v143, v0 offset:13600
	v_cvt_pk_bf16_f32 v0, v10, s0
	ds_write_b16 v143, v32 offset:4960
	v_cvt_pk_bf16_f32 v32, v59, s0
	ds_write_b16 v143, v0 offset:13664
	v_cvt_pk_bf16_f32 v0, v27, s0
	ds_write_b16 v143, v32 offset:5168
	v_cvt_pk_bf16_f32 v32, v43, s0
	ds_write_b16 v143, v0 offset:13872
	v_cvt_pk_bf16_f32 v0, v11, s0
	ds_write_b16 v143, v32 offset:5232
	v_cvt_pk_bf16_f32 v32, v60, s0
	ds_write_b16 v143, v0 offset:13936
	v_cvt_pk_bf16_f32 v0, v28, s0
	ds_write_b16 v143, v32 offset:6528
	v_cvt_pk_bf16_f32 v32, v44, s0
	ds_write_b16 v143, v0 offset:15232
	v_cvt_pk_bf16_f32 v0, v12, s0
	ds_write_b16 v143, v32 offset:6592
	v_cvt_pk_bf16_f32 v32, v61, s0
	ds_write_b16 v143, v0 offset:15296
	v_cvt_pk_bf16_f32 v0, v29, s0
	ds_write_b16 v143, v32 offset:6800
	v_cvt_pk_bf16_f32 v32, v45, s0
	ds_write_b16 v143, v0 offset:15504
	v_cvt_pk_bf16_f32 v0, v13, s0
	ds_write_b16 v143, v32 offset:6864
	v_cvt_pk_bf16_f32 v32, v62, s0
	ds_write_b16 v143, v0 offset:15568
	v_cvt_pk_bf16_f32 v0, v30, s0
	ds_write_b16 v143, v32 offset:7072
	v_cvt_pk_bf16_f32 v32, v46, s0
	ds_write_b16 v143, v0 offset:15776
	v_cvt_pk_bf16_f32 v0, v14, s0
	ds_write_b16 v143, v32 offset:7136
	v_cvt_pk_bf16_f32 v32, v63, s0
	ds_write_b16 v143, v0 offset:15840
	v_cvt_pk_bf16_f32 v0, v31, s0
	v_cvt_pk_bf16_f32 v48, v48, s0
	ds_write_b16 v143, v32 offset:7344
	v_cvt_pk_bf16_f32 v32, v47, s0
	v_cvt_pk_bf16_f32 v16, v16, s0
	ds_write_b16 v143, v0 offset:16048
	v_cvt_pk_bf16_f32 v0, v15, s0
	v_mov_b32_e32 v15, v142
	ds_write_b16 v143, v48
	ds_write_b16 v143, v32 offset:7408
	ds_write_b16 v143, v16 offset:8704
	ds_write_b16 v143, v0 offset:16112
	s_waitcnt lgkmcnt(0)
	s_barrier
	v_mov_b64_e32 v[2:3], s[4:5]
	v_lshlrev_b32_e32 v0, 3, v15
	v_and_b32_e32 v0, 0x78, v0
	v_ashrrev_i32_e32 v1, 4, v15
	v_lshlrev_b32_e32 v128, 1, v0
	v_add_u32_e32 v0, s69, v1
	s_lshl_b32 s16, s26, 10
	v_mad_i64_i32 v[2:3], s[0:1], v0, s66, v[2:3]
	v_lshl_add_u64 v[2:3], s[16:17], 1, v[2:3]
	v_lshl_add_u64 v[2:3], s[22:23], 1, v[2:3]
	v_lshl_add_u64 v[2:3], v[2:3], 0, v[128:129]
	global_load_dwordx4 v[6:9], v[2:3], off
	v_add_co_u32_e32 v80, vcc, 0x18000, v2
	s_nop 1
	v_addc_co_u32_e32 v81, vcc, 0, v3, vcc
	global_load_dwordx4 v[24:27], v[80:81], off
	v_add_co_u32_e32 v80, vcc, 0x30000, v2
	s_nop 1
	v_addc_co_u32_e32 v81, vcc, 0, v3, vcc
	global_load_dwordx4 v[28:31], v[80:81], off
	v_add_co_u32_e32 v80, vcc, 0x48000, v2
	s_nop 1
	v_addc_co_u32_e32 v81, vcc, 0, v3, vcc
	global_load_dwordx4 v[32:35], v[80:81], off
	v_add_co_u32_e32 v80, vcc, 0x60000, v2
	s_nop 1
	v_addc_co_u32_e32 v81, vcc, 0, v3, vcc
	global_load_dwordx4 v[36:39], v[80:81], off
	v_add_co_u32_e32 v80, vcc, 0x78000, v2
	s_nop 1
	v_addc_co_u32_e32 v81, vcc, 0, v3, vcc
	global_load_dwordx4 v[40:43], v[80:81], off
	v_add_co_u32_e32 v80, vcc, 0x90000, v2
	s_nop 1
	v_addc_co_u32_e32 v81, vcc, 0, v3, vcc
	global_load_dwordx4 v[44:47], v[80:81], off
	v_add_co_u32_e32 v80, vcc, 0xa8000, v2
	s_nop 1
	v_addc_co_u32_e32 v81, vcc, 0, v3, vcc
	global_load_dwordx4 v[48:51], v[80:81], off
	v_add_u32_e32 v14, 32, v128
	v_mad_u64_u32 v[2:3], s[0:1], v1, s60, v[14:15]
	ds_read_b128 v[2:5], v2
	v_ashrrev_i32_e32 v1, 31, v0
	v_lshlrev_b64 v[0:1], 11, v[0:1]
	v_lshl_add_u64 v[0:1], s[24:25], 0, v[0:1]
	v_lshl_add_u64 v[16:17], v[0:1], 0, v[128:129]
	v_cndmask_b32_e64 v1, 0, 1, s[50:51]
	v_mov_b32_e32 v0, 0
	v_cmp_ne_u32_e64 s[0:1], 1, v1
	s_andn2_b64 vcc, exec, s[50:51]
	v_mov_b32_e32 v10, 0
	v_mov_b32_e32 v11, 0
	v_mov_b32_e32 v12, 0
	v_mov_b32_e32 v13, 0
	s_cbranch_vccnz .LBB0_1748
	global_load_dwordx4 v[10:13], v[16:17], off
	v_add_co_u32_e32 v80, vcc, 0x8000, v16
	s_nop 1
	v_addc_co_u32_e32 v81, vcc, 0, v17, vcc
	global_load_dwordx4 v[52:55], v[80:81], off
	v_add_co_u32_e32 v80, vcc, 0x10000, v16
	s_nop 1
	v_addc_co_u32_e32 v81, vcc, 0, v17, vcc
	global_load_dwordx4 v[56:59], v[80:81], off
	v_add_co_u32_e32 v80, vcc, 0x18000, v16
	s_nop 1
	v_addc_co_u32_e32 v81, vcc, 0, v17, vcc
	global_load_dwordx4 v[60:63], v[80:81], off
	v_add_co_u32_e32 v80, vcc, 0x20000, v16
	s_nop 1
	v_addc_co_u32_e32 v81, vcc, 0, v17, vcc
	global_load_dwordx4 v[64:67], v[80:81], off
	v_add_co_u32_e32 v80, vcc, 0x28000, v16
	s_nop 1
	v_addc_co_u32_e32 v81, vcc, 0, v17, vcc
	global_load_dwordx4 v[68:71], v[80:81], off
	v_add_co_u32_e32 v80, vcc, 0x30000, v16
	s_nop 1
	v_addc_co_u32_e32 v81, vcc, 0, v17, vcc
	global_load_dwordx4 v[72:75], v[80:81], off
	v_add_co_u32_e32 v80, vcc, 0x38000, v16
	s_nop 1
	v_addc_co_u32_e32 v81, vcc, 0, v17, vcc
	global_load_dwordx4 v[76:79], v[80:81], off

.LBB0_1817:
	s_setprio 1
	ds_read_b128 v[140:143], v103
	ds_read_b128 v[144:147], v104 offset:36864
	ds_read_b128 v[148:151], v104 offset:41472
	ds_read_b128 v[192:195], v103 offset:4608
	s_waitcnt lgkmcnt(2)
	v_mfma_f32_32x32x16_bf16 v[48:63], v[140:143], v[144:147], v[48:63]
	ds_read_b128 v[196:199], v103 offset:32
	ds_read_b128 v[200:203], v104 offset:36896
	global_load_dwordx4 v[108:111], v168, s[98:99] offset:3840
	global_load_dwordx4 v[112:115], v170, s[98:99] offset:3840
	s_waitcnt vmcnt(9)
	ds_write_b128 v105, v[68:71] offset:18432
	s_waitcnt lgkmcnt(4)
	v_mfma_f32_32x32x16_bf16 v[32:47], v[140:143], v[148:151], v[32:47]
	ds_read_b128 v[204:207], v104 offset:41504
	global_load_dwordx4 v[116:119], v172, s[98:99] offset:3840
	global_load_dwordx4 v[120:123], v174, s[98:99] offset:3840
	s_waitcnt lgkmcnt(4)
	v_mfma_f32_32x32x16_bf16 v[16:31], v[192:195], v[144:147], v[16:31]
	ds_read_b128 v[208:211], v103 offset:4640
	global_load_dwordx4 v[124:127], v176, s[98:99] offset:3840
	global_load_dwordx4 v[128:131], v178, s[98:99] offset:3840
	s_waitcnt vmcnt(11)
	ds_write_b128 v105, v[84:87] offset:23040
	v_mfma_f32_32x32x16_bf16 v[0:15], v[192:195], v[148:151], v[0:15]
	global_load_dwordx4 v[132:135], v180, s[98:99] offset:3840
	global_load_dwordx4 v[136:139], v182, s[98:99] offset:3840
	s_waitcnt lgkmcnt(4)
	v_mfma_f32_32x32x16_bf16 v[48:63], v[196:199], v[200:203], v[48:63]
	ds_read_b128 v[212:215], v103 offset:64
	ds_read_b128 v[216:219], v104 offset:36928
	s_waitcnt vmcnt(12)
	ds_write_b128 v105, v[88:91] offset:27648
	s_waitcnt lgkmcnt(5)
	v_mfma_f32_32x32x16_bf16 v[32:47], v[196:199], v[204:207], v[32:47]
	ds_read_b128 v[220:223], v104 offset:41536
	s_waitcnt lgkmcnt(5)
	v_mfma_f32_32x32x16_bf16 v[16:31], v[208:211], v[200:203], v[16:31]
	ds_read_b128 v[224:227], v103 offset:4672
	s_waitcnt vmcnt(11)
	ds_write_b128 v105, v[92:95] offset:32256
	v_mfma_f32_32x32x16_bf16 v[0:15], v[208:211], v[204:207], v[0:15]
	s_waitcnt lgkmcnt(4)
	v_mfma_f32_32x32x16_bf16 v[48:63], v[212:215], v[216:219], v[48:63]
	ds_read_b128 v[228:231], v103 offset:96
	ds_read_b128 v[140:143], v104 offset:36960
	ds_write_b128 v105, v[64:67] offset:55296
	s_waitcnt lgkmcnt(5)
	v_mfma_f32_32x32x16_bf16 v[32:47], v[212:215], v[220:223], v[32:47]
	ds_read_b128 v[144:147], v104 offset:41568
	s_waitcnt lgkmcnt(5)
	v_mfma_f32_32x32x16_bf16 v[16:31], v[224:227], v[216:219], v[16:31]
	ds_read_b128 v[148:151], v103 offset:4704
	s_waitcnt vmcnt(10)
	ds_write_b128 v105, v[72:75] offset:59904
	v_mfma_f32_32x32x16_bf16 v[0:15], v[224:227], v[220:223], v[0:15]
	s_waitcnt lgkmcnt(4)
	v_mfma_f32_32x32x16_bf16 v[48:63], v[228:231], v[140:143], v[48:63]
	s_waitcnt vmcnt(9)
	ds_write_b128 v105, v[76:79] offset:64512
	s_waitcnt lgkmcnt(3)
	v_mfma_f32_32x32x16_bf16 v[32:47], v[228:231], v[144:147], v[32:47]
	s_waitcnt lgkmcnt(2)
	v_mfma_f32_32x32x16_bf16 v[16:31], v[148:151], v[140:143], v[16:31]
	s_waitcnt vmcnt(8)
	ds_write_b128 v106, v[80:83] offset:13824
	v_mfma_f32_32x32x16_bf16 v[0:15], v[148:151], v[144:147], v[0:15]
	s_setprio 0
	s_waitcnt lgkmcnt(0)
	s_barrier
	s_setprio 1
	ds_read_b128 v[140:143], v103 offset:18432
	ds_read_b128 v[144:147], v104 offset:55296
	ds_read_b128 v[148:151], v104 offset:59904
	ds_read_b128 v[192:195], v103 offset:23040
	s_waitcnt lgkmcnt(2)
	v_mfma_f32_32x32x16_bf16 v[48:63], v[140:143], v[144:147], v[48:63]
	ds_read_b128 v[196:199], v103 offset:18464
	ds_read_b128 v[200:203], v104 offset:55328
	global_load_dwordx4 v[68:71], v168, s[98:99] offset:3968
	global_load_dwordx4 v[84:87], v170, s[98:99] offset:3968
	s_waitcnt vmcnt(9)
	ds_write_b128 v105, v[108:111]
	s_waitcnt lgkmcnt(4)
	v_mfma_f32_32x32x16_bf16 v[32:47], v[140:143], v[148:151], v[32:47]
	ds_read_b128 v[204:207], v104 offset:59936
	global_load_dwordx4 v[88:91], v172, s[98:99] offset:3968
	global_load_dwordx4 v[92:95], v174, s[98:99] offset:3968
	s_waitcnt lgkmcnt(4)
	v_mfma_f32_32x32x16_bf16 v[16:31], v[192:195], v[144:147], v[16:31]
	ds_read_b128 v[208:211], v103 offset:23072
	global_load_dwordx4 v[64:67], v176, s[98:99] offset:3968
	global_load_dwordx4 v[72:75], v178, s[98:99] offset:3968
	s_waitcnt vmcnt(12)
	ds_write_b128 v105, v[112:115] offset:4608
	v_mfma_f32_32x32x16_bf16 v[0:15], v[192:195], v[148:151], v[0:15]
	global_load_dwordx4 v[76:79], v180, s[98:99] offset:3968
	global_load_dwordx4 v[80:83], v182, s[98:99] offset:3968
	s_waitcnt lgkmcnt(4)
	v_mfma_f32_32x32x16_bf16 v[48:63], v[196:199], v[200:203], v[48:63]
	ds_read_b128 v[212:215], v103 offset:18496
	ds_read_b128 v[216:219], v104 offset:55360
	s_add_u32 s98, s98, 0x100
	s_addc_u32 s99, s99, 0
	s_add_i32 s10, s10, 2
	s_cmp_lt_u32 s10, 11
	s_waitcnt vmcnt(13)
	ds_write_b128 v105, v[116:119] offset:9216
	s_waitcnt lgkmcnt(5)
	v_mfma_f32_32x32x16_bf16 v[32:47], v[196:199], v[204:207], v[32:47]
	ds_read_b128 v[220:223], v104 offset:59968
	s_waitcnt lgkmcnt(5)
	v_mfma_f32_32x32x16_bf16 v[16:31], v[208:211], v[200:203], v[16:31]
	ds_read_b128 v[224:227], v103 offset:23104
	s_waitcnt vmcnt(12)
	ds_write_b128 v105, v[120:123] offset:13824
	v_mfma_f32_32x32x16_bf16 v[0:15], v[208:211], v[204:207], v[0:15]
	s_waitcnt lgkmcnt(4)
	v_mfma_f32_32x32x16_bf16 v[48:63], v[212:215], v[216:219], v[48:63]
	ds_read_b128 v[228:231], v103 offset:18528
	ds_read_b128 v[140:143], v104 offset:55392
	s_waitcnt vmcnt(11)
	ds_write_b128 v105, v[124:127] offset:36864
	s_waitcnt lgkmcnt(5)
	v_mfma_f32_32x32x16_bf16 v[32:47], v[212:215], v[220:223], v[32:47]
	ds_read_b128 v[144:147], v104 offset:60000
	s_waitcnt lgkmcnt(5)
	v_mfma_f32_32x32x16_bf16 v[16:31], v[224:227], v[216:219], v[16:31]
	ds_read_b128 v[148:151], v103 offset:23136
	s_waitcnt vmcnt(10)
	ds_write_b128 v105, v[128:131] offset:41472
	v_mfma_f32_32x32x16_bf16 v[0:15], v[224:227], v[220:223], v[0:15]
	s_waitcnt lgkmcnt(4)
	v_mfma_f32_32x32x16_bf16 v[48:63], v[228:231], v[140:143], v[48:63]
	s_waitcnt vmcnt(9)
	ds_write_b128 v105, v[132:135] offset:46080
	s_waitcnt lgkmcnt(3)
	v_mfma_f32_32x32x16_bf16 v[32:47], v[228:231], v[144:147], v[32:47]
	s_waitcnt lgkmcnt(2)
	v_mfma_f32_32x32x16_bf16 v[16:31], v[148:151], v[140:143], v[16:31]
	s_waitcnt vmcnt(8)
	ds_write_b128 v105, v[136:139] offset:50688
	v_mfma_f32_32x32x16_bf16 v[0:15], v[148:151], v[144:147], v[0:15]
	s_setprio 0
	s_waitcnt lgkmcnt(0)
	s_barrier
	s_cbranch_scc1 .LBB0_1817
	s_setprio 1
	ds_read_b128 v[98:101], v103
	ds_read_b128 v[108:111], v104 offset:36864
	ds_read_b128 v[112:115], v104 offset:41472
	ds_read_b128 v[192:195], v103 offset:4608
	s_waitcnt lgkmcnt(2)
	v_mfma_f32_32x32x16_bf16 v[48:63], v[98:101], v[108:111], v[48:63]
	ds_read_b128 v[196:199], v103 offset:32
	ds_read_b128 v[200:203], v104 offset:36896
	s_waitcnt vmcnt(7)
	ds_write_b128 v105, v[68:71] offset:18432
	s_waitcnt lgkmcnt(4)
	v_mfma_f32_32x32x16_bf16 v[32:47], v[98:101], v[112:115], v[32:47]
	ds_read_b128 v[204:207], v104 offset:41504
	s_waitcnt lgkmcnt(4)
	v_mfma_f32_32x32x16_bf16 v[16:31], v[192:195], v[108:111], v[16:31]
	ds_read_b128 v[208:211], v103 offset:4640
	s_waitcnt vmcnt(6)
	ds_write_b128 v105, v[84:87] offset:23040
	v_mfma_f32_32x32x16_bf16 v[0:15], v[192:195], v[112:115], v[0:15]
	s_waitcnt lgkmcnt(4)
	v_mfma_f32_32x32x16_bf16 v[48:63], v[196:199], v[200:203], v[48:63]
	ds_read_b128 v[212:215], v103 offset:64
	ds_read_b128 v[216:219], v104 offset:36928
	s_waitcnt vmcnt(5)
	ds_write_b128 v105, v[88:91] offset:27648
	s_waitcnt lgkmcnt(5)
	v_mfma_f32_32x32x16_bf16 v[32:47], v[196:199], v[204:207], v[32:47]
	ds_read_b128 v[220:223], v104 offset:41536
	s_waitcnt lgkmcnt(5)
	v_mfma_f32_32x32x16_bf16 v[16:31], v[208:211], v[200:203], v[16:31]
	ds_read_b128 v[224:227], v103 offset:4672
	s_waitcnt vmcnt(4)
	ds_write_b128 v105, v[92:95] offset:32256
	v_mfma_f32_32x32x16_bf16 v[0:15], v[208:211], v[204:207], v[0:15]
	s_waitcnt lgkmcnt(4)
	v_mfma_f32_32x32x16_bf16 v[48:63], v[212:215], v[216:219], v[48:63]
	ds_read_b128 v[228:231], v104 offset:36960
	ds_read_b128 v[98:101], v103 offset:4704
	s_waitcnt vmcnt(3)
	ds_write_b128 v105, v[64:67] offset:55296
	s_waitcnt lgkmcnt(5)
	v_mfma_f32_32x32x16_bf16 v[32:47], v[212:215], v[220:223], v[32:47]
	ds_read_b128 v[108:111], v104 offset:41568
	s_waitcnt lgkmcnt(5)
	v_mfma_f32_32x32x16_bf16 v[16:31], v[224:227], v[216:219], v[16:31]
	ds_read_b128 v[112:115], v103 offset:96
	s_waitcnt vmcnt(2)
	ds_write_b128 v105, v[72:75] offset:59904
	v_mfma_f32_32x32x16_bf16 v[0:15], v[224:227], v[220:223], v[0:15]
	s_waitcnt lgkmcnt(4)
	v_mfma_f32_32x32x16_bf16 v[16:31], v[98:101], v[228:231], v[16:31]
	s_waitcnt vmcnt(1)
	ds_write_b128 v105, v[76:79] offset:64512
	s_waitcnt lgkmcnt(3)
	v_mfma_f32_32x32x16_bf16 v[0:15], v[98:101], v[108:111], v[0:15]
	s_waitcnt lgkmcnt(2)
	v_mfma_f32_32x32x16_bf16 v[48:63], v[112:115], v[228:231], v[48:63]
	s_waitcnt vmcnt(0)
	ds_write_b128 v106, v[80:83] offset:13824
	v_mfma_f32_32x32x16_bf16 v[32:47], v[112:115], v[108:111], v[32:47]
	s_setprio 0
	s_waitcnt lgkmcnt(0)
	s_barrier
	s_setprio 1
	ds_read_b128 v[64:67], v103 offset:18432
	ds_read_b128 v[68:71], v104 offset:55296
	ds_read_b128 v[72:75], v104 offset:59904
	ds_read_b128 v[192:195], v103 offset:23040
	s_waitcnt lgkmcnt(2)
	v_mfma_f32_32x32x16_bf16 v[48:63], v[64:67], v[68:71], v[48:63]
	ds_read_b128 v[196:199], v103 offset:18464
	ds_read_b128 v[200:203], v104 offset:55328
	s_waitcnt lgkmcnt(3)
	v_mfma_f32_32x32x16_bf16 v[32:47], v[64:67], v[72:75], v[32:47]
	ds_read_b128 v[204:207], v104 offset:59936
	s_waitcnt lgkmcnt(3)
	v_mfma_f32_32x32x16_bf16 v[16:31], v[192:195], v[68:71], v[16:31]
	ds_read_b128 v[208:211], v103 offset:23072
	v_mfma_f32_32x32x16_bf16 v[0:15], v[192:195], v[72:75], v[0:15]
	s_waitcnt lgkmcnt(2)
	v_mfma_f32_32x32x16_bf16 v[48:63], v[196:199], v[200:203], v[48:63]
	ds_read_b128 v[212:215], v103 offset:18496
	ds_read_b128 v[216:219], v104 offset:55360
	s_waitcnt lgkmcnt(3)
	v_mfma_f32_32x32x16_bf16 v[32:47], v[196:199], v[204:207], v[32:47]
	ds_read_b128 v[220:223], v104 offset:59968
	s_waitcnt lgkmcnt(3)
	v_mfma_f32_32x32x16_bf16 v[16:31], v[208:211], v[200:203], v[16:31]
	ds_read_b128 v[224:227], v103 offset:23104
	v_mfma_f32_32x32x16_bf16 v[0:15], v[208:211], v[204:207], v[0:15]
	s_waitcnt lgkmcnt(2)
	v_mfma_f32_32x32x16_bf16 v[48:63], v[212:215], v[216:219], v[48:63]
	ds_read_b128 v[228:231], v104 offset:55392
	ds_read_b128 v[64:67], v103 offset:23136
	s_waitcnt lgkmcnt(3)
	v_mfma_f32_32x32x16_bf16 v[32:47], v[212:215], v[220:223], v[32:47]
	ds_read_b128 v[68:71], v104 offset:60000
	s_waitcnt lgkmcnt(3)
	v_mfma_f32_32x32x16_bf16 v[16:31], v[224:227], v[216:219], v[16:31]
	ds_read_b128 v[72:75], v103 offset:18528
	v_mfma_f32_32x32x16_bf16 v[0:15], v[224:227], v[220:223], v[0:15]
	s_waitcnt lgkmcnt(2)
	v_mfma_f32_32x32x16_bf16 v[16:31], v[64:67], v[228:231], v[16:31]
	s_waitcnt lgkmcnt(1)
	v_mfma_f32_32x32x16_bf16 v[0:15], v[64:67], v[68:71], v[0:15]
	s_waitcnt lgkmcnt(0)
	v_mfma_f32_32x32x16_bf16 v[48:63], v[72:75], v[228:231], v[48:63]
	v_mfma_f32_32x32x16_bf16 v[32:47], v[72:75], v[68:71], v[32:47]
	s_setprio 0
	s_addk_i32 s0, 0xf000
	s_lshr_b32 s10, s0, 10
	s_mulk_i32 s10, 0x1800
	s_addk_i32 s10, 0x1800
	s_and_b64 s[22:23], s[8:9], exec
	s_cselect_b32 s10, 0, s10
	v_mov_b32_e32 v68, v234
	s_barrier
	s_lshl_b64 s[22:23], s[10:11], 2
	s_add_u32 s22, s30, s22
	v_and_b32_e32 v69, 0x5f, v68
	v_or_b32_e32 v64, s21, v69
	s_addc_u32 s23, s31, s23
	v_ashrrev_i32_e32 v65, 31, v64
	v_lshl_add_u64 v[64:65], v[64:65], 2, s[22:23]
	v_lshl_add_u64 v[66:67], v[64:65], 0, s[14:15]
	v_add_co_u32_e32 v64, vcc, s54, v64
	v_lshlrev_b32_e32 v69, 2, v69
	s_nop 0
	v_addc_co_u32_e32 v65, vcc, 0, v65, vcc
	global_load_dword v64, v[64:65], off
	s_nop 0
	global_load_dword v65, v[66:67], off offset:128
	v_lshrrev_b32_e32 v67, 3, v68
	v_lshrrev_b32_e32 v66, 1, v68
	v_and_b32_e32 v67, 4, v67
	v_and_or_b32 v66, v66, s45, v67
	v_mul_lo_u32 v66, v66, s55
	v_add3_u32 v66, 32, v69, v66
	v_add_u32_e32 v67, 0x400, v66
	v_add_u32_e32 v69, 0x1000, v66
	v_add_u32_e32 v70, 0x1400, v66
	v_add_u32_e32 v71, 0x2000, v66
	v_add_u32_e32 v72, 0x2400, v66
	v_add_u32_e32 v73, 0x3000, v66
	v_add_u32_e32 v74, 0x3200, v66
	v_add_u32_e32 v75, 0x3400, v66
	v_add_u32_e32 v76, 0x3600, v66
	v_add_u32_e32 v77, 0x4000, v66
	v_readlane_b32 s80, v251, 39
	v_readlane_b32 s81, v251, 40
	s_lshl_b32 s1, s1, 19
	v_readlane_b32 s82, v251, 41
	v_readlane_b32 s83, v251, 42
	s_mov_b64 s[36:37], s[80:81]
	s_add_u32 s10, s36, s1
	s_mov_b32 s1, s11
	s_mov_b64 s[38:39], s[82:83]
	s_addc_u32 s21, s37, 0
	s_lshl_b64 s[0:1], s[0:1], 12
	s_add_u32 s22, s38, s0
	s_addc_u32 s23, s39, s1
	s_and_b64 s[0:1], s[8:9], exec
	s_cselect_b32 s23, s21, s23
	s_cselect_b32 s22, s10, s22
	s_add_i32 s10, s20, s27
	v_readlane_b32 s84, v251, 43
	v_readlane_b32 s85, v251, 44
	v_readlane_b32 s86, v251, 45
	v_readlane_b32 s87, v251, 46
	v_readlane_b32 s88, v251, 47
	v_readlane_b32 s89, v251, 48
	v_readlane_b32 s90, v251, 49
	v_readlane_b32 s91, v251, 50
	v_readlane_b32 s92, v251, 51
	v_readlane_b32 s93, v251, 52
	v_readlane_b32 s94, v251, 53
	v_readlane_b32 s95, v251, 54
	s_waitcnt vmcnt(1)
	v_mul_f32_e32 v48, v48, v64
	s_waitcnt vmcnt(0)
	v_mul_f32_e32 v32, v32, v65
	v_mul_f32_e32 v16, v16, v64
	v_mul_f32_e32 v0, v0, v65
	v_mul_f32_e32 v49, v49, v64
	v_mul_f32_e32 v33, v33, v65
	v_mul_f32_e32 v50, v50, v64
	v_mul_f32_e32 v34, v34, v65
	v_mul_f32_e32 v51, v51, v64
	v_mul_f32_e32 v35, v35, v65
	v_mul_f32_e32 v52, v52, v64
	v_mul_f32_e32 v36, v36, v65
	v_mul_f32_e32 v53, v53, v64
	v_mul_f32_e32 v37, v37, v65
	v_mul_f32_e32 v54, v54, v64
	v_mul_f32_e32 v38, v38, v65
	v_mul_f32_e32 v55, v55, v64
	v_mul_f32_e32 v39, v39, v65
	v_mul_f32_e32 v56, v56, v64
	v_mul_f32_e32 v40, v40, v65
	v_mul_f32_e32 v57, v57, v64
	v_mul_f32_e32 v41, v41, v65
	v_mul_f32_e32 v58, v58, v64
	v_mul_f32_e32 v42, v42, v65
	v_mul_f32_e32 v59, v59, v64
	v_mul_f32_e32 v43, v43, v65
	v_mul_f32_e32 v60, v60, v64
	v_mul_f32_e32 v44, v44, v65
	v_mul_f32_e32 v61, v61, v64
	v_mul_f32_e32 v45, v45, v65
	v_mul_f32_e32 v62, v62, v64
	v_mul_f32_e32 v46, v46, v65
	v_mul_f32_e32 v63, v63, v64
	v_mul_f32_e32 v47, v47, v65
	ds_write2_b32 v66, v48, v32 offset1:32
	ds_write2_b32 v66, v49, v33 offset0:132 offset1:164
	ds_write2_b32 v67, v50, v34 offset0:8 offset1:40
	ds_write2_b32 v67, v51, v35 offset0:140 offset1:172
	ds_write2_b32 v69, v52, v36 offset0:32 offset1:64
	ds_write2_b32 v69, v53, v37 offset0:164 offset1:196
	ds_write2_b32 v70, v54, v38 offset0:40 offset1:72
	ds_write2_b32 v70, v55, v39 offset0:172 offset1:204
	ds_write2_b32 v71, v56, v40 offset0:64 offset1:96
	ds_write2_b32 v71, v57, v41 offset0:196 offset1:228
	ds_write2_b32 v72, v58, v42 offset0:72 offset1:104
	ds_write2_b32 v72, v59, v43 offset0:204 offset1:236
	ds_write2_b32 v73, v60, v44 offset0:96 offset1:128
	ds_write2_b32 v74, v61, v45 offset0:100 offset1:132
	ds_write2_b32 v75, v62, v46 offset0:104 offset1:136
	ds_write2_b32 v76, v63, v47 offset0:108 offset1:140
	ds_write2_b32 v77, v16, v0 offset0:128 offset1:160
	v_mul_f32_e32 v0, v17, v64
	v_mul_f32_e32 v1, v1, v65
	v_add_u32_e32 v16, 0x4400, v66
	ds_write2_b32 v16, v0, v1 offset0:4 offset1:36
	v_mul_f32_e32 v0, v18, v64
	v_mul_f32_e32 v1, v2, v65
	ds_write2_b32 v16, v0, v1 offset0:136 offset1:168
	v_mul_f32_e32 v0, v19, v64
	v_mul_f32_e32 v1, v3, v65
	v_add_u32_e32 v2, 0x4800, v66
	ds_write2_b32 v2, v0, v1 offset0:12 offset1:44
	v_mul_f32_e32 v0, v20, v64
	v_mul_f32_e32 v1, v4, v65
	v_add_u32_e32 v2, 0x5000, v66
	ds_write2_b32 v2, v0, v1 offset0:160 offset1:192
	v_mul_f32_e32 v0, v21, v64
	v_mul_f32_e32 v1, v5, v65
	v_add_u32_e32 v2, 0x5400, v66
	ds_write2_b32 v2, v0, v1 offset0:36 offset1:68
	v_mul_f32_e32 v0, v22, v64
	v_mul_f32_e32 v1, v6, v65
	ds_write2_b32 v2, v0, v1 offset0:168 offset1:200
	v_mul_f32_e32 v0, v23, v64
	v_mul_f32_e32 v1, v7, v65
	v_add_u32_e32 v2, 0x5800, v66
	ds_write2_b32 v2, v0, v1 offset0:44 offset1:76
	v_mul_f32_e32 v0, v24, v64
	v_mul_f32_e32 v1, v8, v65
	v_add_u32_e32 v2, 0x6000, v66
	ds_write2_b32 v2, v0, v1 offset0:192 offset1:224
	v_mul_f32_e32 v0, v25, v64
	v_mul_f32_e32 v1, v9, v65
	v_add_u32_e32 v2, 0x6400, v66
	ds_write2_b32 v2, v0, v1 offset0:68 offset1:100
	v_mul_f32_e32 v0, v26, v64
	v_mul_f32_e32 v1, v10, v65
	ds_write2_b32 v2, v0, v1 offset0:200 offset1:232
	v_mul_f32_e32 v0, v27, v64
	v_mul_f32_e32 v1, v11, v65
	v_add_u32_e32 v2, 0x6800, v66
	ds_write2_b32 v2, v0, v1 offset0:76 offset1:108
	v_mul_f32_e32 v0, v28, v64
	v_mul_f32_e32 v1, v12, v65
	v_add_u32_e32 v2, 0x7200, v66
	ds_write2_b32 v2, v0, v1 offset0:96 offset1:128
	v_mul_f32_e32 v0, v29, v64
	v_mul_f32_e32 v1, v13, v65
	v_add_u32_e32 v2, 0x7400, v66
	ds_write2_b32 v2, v0, v1 offset0:100 offset1:132
	v_mul_f32_e32 v0, v30, v64
	v_mul_f32_e32 v1, v14, v65
	v_add_u32_e32 v2, 0x7600, v66
	ds_write2_b32 v2, v0, v1 offset0:104 offset1:136
	v_mul_f32_e32 v0, v31, v64
	v_mul_f32_e32 v1, v15, v65
	v_add_u32_e32 v2, 0x7800, v66
	ds_write2_b32 v2, v0, v1 offset0:108 offset1:140
	v_and_b32_e32 v0, 64, v102
	v_add_u32_e32 v0, 64, v0
	v_xor_b32_e32 v1, 1, v102
	v_cmp_lt_i32_e32 vcc, v1, v0
	v_and_b32_e32 v4, 31, v68
	v_lshl_add_u32 v2, v4, 2, s18
	v_cndmask_b32_e32 v1, v102, v1, vcc
	v_lshlrev_b32_e32 v20, 2, v1
	v_xor_b32_e32 v1, 2, v102
	v_cmp_lt_i32_e32 vcc, v1, v0
	v_ashrrev_i32_e32 v14, 5, v68
	v_ashrrev_i32_e32 v3, 31, v2
	v_cndmask_b32_e32 v1, v102, v1, vcc
	v_lshlrev_b32_e32 v21, 2, v1
	v_xor_b32_e32 v1, 4, v102
	v_cmp_lt_i32_e32 vcc, v1, v0
	v_cmp_eq_u32_e64 s[0:1], 0, v4
	v_lshlrev_b64 v[16:17], 2, v[2:3]
	v_cndmask_b32_e32 v1, v102, v1, vcc
	v_lshlrev_b32_e32 v22, 2, v1
	v_xor_b32_e32 v1, 8, v102
	v_cmp_lt_i32_e32 vcc, v1, v0
	v_lshlrev_b32_e32 v3, 4, v4
	v_add_u32_e32 v4, s10, v14
	v_cndmask_b32_e32 v1, v102, v1, vcc
	v_lshlrev_b32_e32 v23, 2, v1
	v_xor_b32_e32 v1, 16, v102
	s_add_i32 s10, s20, s33
	s_add_i32 s20, s20, s34
	v_cmp_lt_i32_e32 vcc, v1, v0
	v_add_u32_e32 v8, s10, v14
	v_add_u32_e32 v12, s20, v14
	v_add_u32_e32 v18, s19, v14
	v_cndmask_b32_e32 v0, v102, v1, vcc
	v_ashrrev_i32_e32 v15, 31, v14
	v_mul_lo_u32 v2, v14, s55
	v_ashrrev_i32_e32 v5, 31, v4
	v_ashrrev_i32_e32 v9, 31, v8
	v_ashrrev_i32_e32 v13, 31, v12
	v_ashrrev_i32_e32 v19, 31, v18
	v_lshlrev_b32_e32 v24, 2, v0
	v_lshlrev_b64 v[0:1], 12, v[14:15]
	v_add3_u32 v25, v2, v3, 32
	v_lshlrev_b32_e32 v2, 1, v4
	v_lshlrev_b64 v[4:5], 12, v[4:5]
	v_lshlrev_b32_e32 v6, 1, v8
	v_lshlrev_b64 v[8:9], 12, v[8:9]
	v_lshlrev_b32_e32 v10, 1, v12
	v_lshlrev_b64 v[12:13], 12, v[12:13]
	v_lshlrev_b64 v[14:15], 12, v[18:19]
	v_lshl_add_u64 v[0:1], v[0:1], 0, v[16:17]
	v_lshl_add_u64 v[4:5], v[4:5], 0, v[16:17]
	v_lshl_add_u64 v[8:9], v[8:9], 0, v[16:17]
	v_lshl_add_u64 v[12:13], v[12:13], 0, v[16:17]
	v_lshl_add_u64 v[14:15], v[14:15], 0, v[16:17]
	v_lshlrev_b32_e32 v16, 1, v18
	v_ashrrev_i32_e32 v3, 31, v2
	v_ashrrev_i32_e32 v7, 31, v6
	v_ashrrev_i32_e32 v11, 31, v10
	v_ashrrev_i32_e32 v17, 31, v16
	v_lshl_add_u64 v[0:1], s[22:23], 0, v[0:1]
	v_lshlrev_b64 v[2:3], 2, v[2:3]
	v_lshl_add_u64 v[4:5], s[30:31], 0, v[4:5]
	v_lshlrev_b64 v[6:7], 2, v[6:7]
	v_lshl_add_u64 v[8:9], s[30:31], 0, v[8:9]
	v_lshlrev_b64 v[10:11], 2, v[10:11]
	v_lshl_add_u64 v[12:13], s[30:31], 0, v[12:13]
	v_lshl_add_u64 v[14:15], s[30:31], 0, v[14:15]
	v_lshlrev_b64 v[16:17], 2, v[16:17]
	s_mov_b64 s[18:19], 0
	s_mov_b64 s[20:21], s[30:31]
	s_waitcnt lgkmcnt(0)
	s_barrier
	s_branch .LBB0_1820

.LBB0_1940:
	s_setprio 1
	ds_read_b128 v[140:143], v103
	ds_read_b128 v[144:147], v104 offset:36864
	ds_read_b128 v[148:151], v104 offset:41472
	ds_read_b128 v[192:195], v103 offset:4608
	s_waitcnt lgkmcnt(2)
	v_mfma_f32_32x32x16_bf16 v[48:63], v[140:143], v[144:147], v[48:63]
	ds_read_b128 v[196:199], v103 offset:32
	ds_read_b128 v[200:203], v104 offset:36896
	global_load_dwordx4 v[108:111], v168, s[98:99] offset:3840
	global_load_dwordx4 v[112:115], v170, s[98:99] offset:3840
	s_waitcnt vmcnt(9)
	ds_write_b128 v105, v[68:71] offset:18432
	s_waitcnt lgkmcnt(4)
	v_mfma_f32_32x32x16_bf16 v[32:47], v[140:143], v[148:151], v[32:47]
	ds_read_b128 v[204:207], v104 offset:41504
	global_load_dwordx4 v[116:119], v172, s[98:99] offset:3840
	global_load_dwordx4 v[120:123], v174, s[98:99] offset:3840
	s_waitcnt lgkmcnt(4)
	v_mfma_f32_32x32x16_bf16 v[16:31], v[192:195], v[144:147], v[16:31]
	ds_read_b128 v[208:211], v103 offset:4640
	global_load_dwordx4 v[124:127], v176, s[98:99] offset:3840
	global_load_dwordx4 v[128:131], v178, s[98:99] offset:3840
	s_waitcnt vmcnt(11)
	ds_write_b128 v105, v[84:87] offset:23040
	v_mfma_f32_32x32x16_bf16 v[0:15], v[192:195], v[148:151], v[0:15]
	global_load_dwordx4 v[132:135], v180, s[98:99] offset:3840
	global_load_dwordx4 v[136:139], v182, s[98:99] offset:3840
	s_waitcnt lgkmcnt(4)
	v_mfma_f32_32x32x16_bf16 v[48:63], v[196:199], v[200:203], v[48:63]
	ds_read_b128 v[212:215], v103 offset:64
	ds_read_b128 v[216:219], v104 offset:36928
	s_waitcnt vmcnt(12)
	ds_write_b128 v105, v[88:91] offset:27648
	s_waitcnt lgkmcnt(5)
	v_mfma_f32_32x32x16_bf16 v[32:47], v[196:199], v[204:207], v[32:47]
	ds_read_b128 v[220:223], v104 offset:41536
	s_waitcnt lgkmcnt(5)
	v_mfma_f32_32x32x16_bf16 v[16:31], v[208:211], v[200:203], v[16:31]
	ds_read_b128 v[224:227], v103 offset:4672
	s_waitcnt vmcnt(11)
	ds_write_b128 v105, v[92:95] offset:32256
	v_mfma_f32_32x32x16_bf16 v[0:15], v[208:211], v[204:207], v[0:15]
	s_waitcnt lgkmcnt(4)
	v_mfma_f32_32x32x16_bf16 v[48:63], v[212:215], v[216:219], v[48:63]
	ds_read_b128 v[228:231], v103 offset:96
	ds_read_b128 v[140:143], v104 offset:36960
	ds_write_b128 v105, v[64:67] offset:55296
	s_waitcnt lgkmcnt(5)
	v_mfma_f32_32x32x16_bf16 v[32:47], v[212:215], v[220:223], v[32:47]
	ds_read_b128 v[144:147], v104 offset:41568
	s_waitcnt lgkmcnt(5)
	v_mfma_f32_32x32x16_bf16 v[16:31], v[224:227], v[216:219], v[16:31]
	ds_read_b128 v[148:151], v103 offset:4704
	s_waitcnt vmcnt(10)
	ds_write_b128 v105, v[72:75] offset:59904
	v_mfma_f32_32x32x16_bf16 v[0:15], v[224:227], v[220:223], v[0:15]
	s_waitcnt lgkmcnt(4)
	v_mfma_f32_32x32x16_bf16 v[48:63], v[228:231], v[140:143], v[48:63]
	s_waitcnt vmcnt(9)
	ds_write_b128 v105, v[76:79] offset:64512
	s_waitcnt lgkmcnt(3)
	v_mfma_f32_32x32x16_bf16 v[32:47], v[228:231], v[144:147], v[32:47]
	s_waitcnt lgkmcnt(2)
	v_mfma_f32_32x32x16_bf16 v[16:31], v[148:151], v[140:143], v[16:31]
	s_waitcnt vmcnt(8)
	ds_write_b128 v106, v[80:83] offset:13824
	v_mfma_f32_32x32x16_bf16 v[0:15], v[148:151], v[144:147], v[0:15]
	s_setprio 0
	s_waitcnt lgkmcnt(0)
	s_barrier
	s_setprio 1
	ds_read_b128 v[140:143], v103 offset:18432
	ds_read_b128 v[144:147], v104 offset:55296
	ds_read_b128 v[148:151], v104 offset:59904
	ds_read_b128 v[192:195], v103 offset:23040
	s_waitcnt lgkmcnt(2)
	v_mfma_f32_32x32x16_bf16 v[48:63], v[140:143], v[144:147], v[48:63]
	ds_read_b128 v[196:199], v103 offset:18464
	ds_read_b128 v[200:203], v104 offset:55328
	global_load_dwordx4 v[68:71], v168, s[98:99] offset:3968
	global_load_dwordx4 v[84:87], v170, s[98:99] offset:3968
	s_waitcnt vmcnt(9)
	ds_write_b128 v105, v[108:111]
	s_waitcnt lgkmcnt(4)
	v_mfma_f32_32x32x16_bf16 v[32:47], v[140:143], v[148:151], v[32:47]
	ds_read_b128 v[204:207], v104 offset:59936
	global_load_dwordx4 v[88:91], v172, s[98:99] offset:3968
	global_load_dwordx4 v[92:95], v174, s[98:99] offset:3968
	s_waitcnt lgkmcnt(4)
	v_mfma_f32_32x32x16_bf16 v[16:31], v[192:195], v[144:147], v[16:31]
	ds_read_b128 v[208:211], v103 offset:23072
	global_load_dwordx4 v[64:67], v176, s[98:99] offset:3968
	global_load_dwordx4 v[72:75], v178, s[98:99] offset:3968
	s_waitcnt vmcnt(12)
	ds_write_b128 v105, v[112:115] offset:4608
	v_mfma_f32_32x32x16_bf16 v[0:15], v[192:195], v[148:151], v[0:15]
	global_load_dwordx4 v[76:79], v180, s[98:99] offset:3968
	global_load_dwordx4 v[80:83], v182, s[98:99] offset:3968
	s_waitcnt lgkmcnt(4)
	v_mfma_f32_32x32x16_bf16 v[48:63], v[196:199], v[200:203], v[48:63]
	ds_read_b128 v[212:215], v103 offset:18496
	ds_read_b128 v[216:219], v104 offset:55360
	s_add_u32 s98, s98, 0x100
	s_addc_u32 s99, s99, 0
	s_add_i32 s41, s41, 2
	s_cmp_lt_u32 s41, 11
	s_waitcnt vmcnt(13)
	ds_write_b128 v105, v[116:119] offset:9216
	s_waitcnt lgkmcnt(5)
	v_mfma_f32_32x32x16_bf16 v[32:47], v[196:199], v[204:207], v[32:47]
	ds_read_b128 v[220:223], v104 offset:59968
	s_waitcnt lgkmcnt(5)
	v_mfma_f32_32x32x16_bf16 v[16:31], v[208:211], v[200:203], v[16:31]
	ds_read_b128 v[224:227], v103 offset:23104
	s_waitcnt vmcnt(12)
	ds_write_b128 v105, v[120:123] offset:13824
	v_mfma_f32_32x32x16_bf16 v[0:15], v[208:211], v[204:207], v[0:15]
	s_waitcnt lgkmcnt(4)
	v_mfma_f32_32x32x16_bf16 v[48:63], v[212:215], v[216:219], v[48:63]
	ds_read_b128 v[228:231], v103 offset:18528
	ds_read_b128 v[140:143], v104 offset:55392
	s_waitcnt vmcnt(11)
	ds_write_b128 v105, v[124:127] offset:36864
	s_waitcnt lgkmcnt(5)
	v_mfma_f32_32x32x16_bf16 v[32:47], v[212:215], v[220:223], v[32:47]
	ds_read_b128 v[144:147], v104 offset:60000
	s_waitcnt lgkmcnt(5)
	v_mfma_f32_32x32x16_bf16 v[16:31], v[224:227], v[216:219], v[16:31]
	ds_read_b128 v[148:151], v103 offset:23136
	s_waitcnt vmcnt(10)
	ds_write_b128 v105, v[128:131] offset:41472
	v_mfma_f32_32x32x16_bf16 v[0:15], v[224:227], v[220:223], v[0:15]
	s_waitcnt lgkmcnt(4)
	v_mfma_f32_32x32x16_bf16 v[48:63], v[228:231], v[140:143], v[48:63]
	s_waitcnt vmcnt(9)
	ds_write_b128 v105, v[132:135] offset:46080
	s_waitcnt lgkmcnt(3)
	v_mfma_f32_32x32x16_bf16 v[32:47], v[228:231], v[144:147], v[32:47]
	s_waitcnt lgkmcnt(2)
	v_mfma_f32_32x32x16_bf16 v[16:31], v[148:151], v[140:143], v[16:31]
	s_waitcnt vmcnt(8)
	ds_write_b128 v105, v[136:139] offset:50688
	v_mfma_f32_32x32x16_bf16 v[0:15], v[148:151], v[144:147], v[0:15]
	s_setprio 0
	s_waitcnt lgkmcnt(0)
	s_barrier
	s_cbranch_scc1 .LBB0_1940
	s_setprio 1
	ds_read_b128 v[98:101], v103
	ds_read_b128 v[108:111], v104 offset:36864
	ds_read_b128 v[112:115], v104 offset:41472
	ds_read_b128 v[192:195], v103 offset:4608
	s_waitcnt lgkmcnt(2)
	v_mfma_f32_32x32x16_bf16 v[48:63], v[98:101], v[108:111], v[48:63]
	ds_read_b128 v[196:199], v103 offset:32
	ds_read_b128 v[200:203], v104 offset:36896
	s_waitcnt vmcnt(7)
	ds_write_b128 v105, v[68:71] offset:18432
	s_waitcnt lgkmcnt(4)
	v_mfma_f32_32x32x16_bf16 v[32:47], v[98:101], v[112:115], v[32:47]
	ds_read_b128 v[204:207], v104 offset:41504
	s_waitcnt lgkmcnt(4)
	v_mfma_f32_32x32x16_bf16 v[16:31], v[192:195], v[108:111], v[16:31]
	ds_read_b128 v[208:211], v103 offset:4640
	s_waitcnt vmcnt(6)
	ds_write_b128 v105, v[84:87] offset:23040
	v_mfma_f32_32x32x16_bf16 v[0:15], v[192:195], v[112:115], v[0:15]
	s_waitcnt lgkmcnt(4)
	v_mfma_f32_32x32x16_bf16 v[48:63], v[196:199], v[200:203], v[48:63]
	ds_read_b128 v[212:215], v103 offset:64
	ds_read_b128 v[216:219], v104 offset:36928
	s_waitcnt vmcnt(5)
	ds_write_b128 v105, v[88:91] offset:27648
	s_waitcnt lgkmcnt(5)
	v_mfma_f32_32x32x16_bf16 v[32:47], v[196:199], v[204:207], v[32:47]
	ds_read_b128 v[220:223], v104 offset:41536
	s_waitcnt lgkmcnt(5)
	v_mfma_f32_32x32x16_bf16 v[16:31], v[208:211], v[200:203], v[16:31]
	ds_read_b128 v[224:227], v103 offset:4672
	s_waitcnt vmcnt(4)
	ds_write_b128 v105, v[92:95] offset:32256
	v_mfma_f32_32x32x16_bf16 v[0:15], v[208:211], v[204:207], v[0:15]
	s_waitcnt lgkmcnt(4)
	v_mfma_f32_32x32x16_bf16 v[48:63], v[212:215], v[216:219], v[48:63]
	ds_read_b128 v[228:231], v103 offset:96
	ds_read_b128 v[98:101], v104 offset:36960
	s_waitcnt vmcnt(3)
	ds_write_b128 v105, v[64:67] offset:55296
	s_waitcnt lgkmcnt(5)
	v_mfma_f32_32x32x16_bf16 v[32:47], v[212:215], v[220:223], v[32:47]
	ds_read_b128 v[108:111], v104 offset:41568
	s_waitcnt lgkmcnt(5)
	v_mfma_f32_32x32x16_bf16 v[16:31], v[224:227], v[216:219], v[16:31]
	ds_read_b128 v[112:115], v103 offset:4704
	s_waitcnt vmcnt(2)
	ds_write_b128 v105, v[72:75] offset:59904
	v_mfma_f32_32x32x16_bf16 v[0:15], v[224:227], v[220:223], v[0:15]
	s_waitcnt lgkmcnt(4)
	v_mfma_f32_32x32x16_bf16 v[48:63], v[228:231], v[98:101], v[48:63]
	s_waitcnt vmcnt(1)
	ds_write_b128 v105, v[76:79] offset:64512
	s_waitcnt lgkmcnt(3)
	v_mfma_f32_32x32x16_bf16 v[32:47], v[228:231], v[108:111], v[32:47]
	s_waitcnt lgkmcnt(2)
	v_mfma_f32_32x32x16_bf16 v[16:31], v[112:115], v[98:101], v[16:31]
	s_waitcnt vmcnt(0)
	ds_write_b128 v106, v[80:83] offset:13824
	v_mfma_f32_32x32x16_bf16 v[0:15], v[112:115], v[108:111], v[0:15]
	s_setprio 0
	s_waitcnt lgkmcnt(0)
	s_barrier
	s_setprio 1
	ds_read_b128 v[64:67], v103 offset:18432
	ds_read_b128 v[68:71], v104 offset:55296
	ds_read_b128 v[72:75], v104 offset:59904
	ds_read_b128 v[192:195], v103 offset:23040
	s_waitcnt lgkmcnt(2)
	v_mfma_f32_32x32x16_bf16 v[48:63], v[64:67], v[68:71], v[48:63]
	ds_read_b128 v[196:199], v103 offset:18464
	ds_read_b128 v[200:203], v104 offset:55328
	s_waitcnt lgkmcnt(3)
	v_mfma_f32_32x32x16_bf16 v[32:47], v[64:67], v[72:75], v[32:47]
	ds_read_b128 v[204:207], v104 offset:59936
	s_waitcnt lgkmcnt(3)
	v_mfma_f32_32x32x16_bf16 v[16:31], v[192:195], v[68:71], v[16:31]
	ds_read_b128 v[208:211], v103 offset:23072
	v_mfma_f32_32x32x16_bf16 v[0:15], v[192:195], v[72:75], v[0:15]
	s_waitcnt lgkmcnt(2)
	v_mfma_f32_32x32x16_bf16 v[48:63], v[196:199], v[200:203], v[48:63]
	ds_read_b128 v[212:215], v103 offset:18496
	ds_read_b128 v[216:219], v104 offset:55360
	s_waitcnt lgkmcnt(3)
	v_mfma_f32_32x32x16_bf16 v[32:47], v[196:199], v[204:207], v[32:47]
	ds_read_b128 v[220:223], v104 offset:59968
	s_waitcnt lgkmcnt(3)
	v_mfma_f32_32x32x16_bf16 v[16:31], v[208:211], v[200:203], v[16:31]
	ds_read_b128 v[224:227], v103 offset:23104
	v_mfma_f32_32x32x16_bf16 v[0:15], v[208:211], v[204:207], v[0:15]
	s_waitcnt lgkmcnt(2)
	v_mfma_f32_32x32x16_bf16 v[48:63], v[212:215], v[216:219], v[48:63]
	ds_read_b128 v[228:231], v103 offset:18528
	ds_read_b128 v[64:67], v104 offset:55392
	s_waitcnt lgkmcnt(3)
	v_mfma_f32_32x32x16_bf16 v[32:47], v[212:215], v[220:223], v[32:47]
	ds_read_b128 v[68:71], v104 offset:60000
	s_waitcnt lgkmcnt(3)
	v_mfma_f32_32x32x16_bf16 v[16:31], v[224:227], v[216:219], v[16:31]
	ds_read_b128 v[72:75], v103 offset:23136
	v_mfma_f32_32x32x16_bf16 v[0:15], v[224:227], v[220:223], v[0:15]
	s_waitcnt lgkmcnt(2)
	v_mfma_f32_32x32x16_bf16 v[48:63], v[228:231], v[64:67], v[48:63]
	s_waitcnt lgkmcnt(1)
	v_mfma_f32_32x32x16_bf16 v[32:47], v[228:231], v[68:71], v[32:47]
	s_waitcnt lgkmcnt(0)
	v_mfma_f32_32x32x16_bf16 v[16:31], v[72:75], v[64:67], v[16:31]
	v_mfma_f32_32x32x16_bf16 v[0:15], v[72:75], v[68:71], v[0:15]
	s_setprio 0
	v_lshrrev_b32_e32 v65, 3, v102
	v_lshrrev_b32_e32 v64, 1, v102
	v_and_b32_e32 v65, 4, v65
	v_and_or_b32 v64, v64, s22, v65
	v_and_b32_e32 v65, 0x5f, v102
	v_lshlrev_b32_e32 v65, 1, v65
	v_mul_lo_u32 v64, v64, s36
	v_add3_u32 v64, 32, v65, v64
	s_nop 2
	v_cvt_pk_bf16_f32 v0, v0, s0
	s_barrier
	ds_write_b16 v64, v0 offset:8768
	v_cvt_pk_bf16_f32 v0, v17, s0
	ds_write_b16 v64, v0 offset:8976
	v_cvt_pk_bf16_f32 v0, v1, s0
	ds_write_b16 v64, v0 offset:9040
	v_cvt_pk_bf16_f32 v0, v18, s0
	v_cvt_pk_bf16_f32 v32, v32, s0
	ds_write_b16 v64, v0 offset:9248
	v_cvt_pk_bf16_f32 v0, v2, s0
	ds_write_b16 v64, v32 offset:64
	v_cvt_pk_bf16_f32 v32, v49, s0
	ds_write_b16 v64, v0 offset:9312
	v_cvt_pk_bf16_f32 v0, v19, s0
	ds_write_b16 v64, v32 offset:272
	v_cvt_pk_bf16_f32 v32, v33, s0
	ds_write_b16 v64, v0 offset:9520
	v_cvt_pk_bf16_f32 v0, v3, s0
	ds_write_b16 v64, v32 offset:336
	v_cvt_pk_bf16_f32 v32, v50, s0
	ds_write_b16 v64, v0 offset:9584
	v_cvt_pk_bf16_f32 v0, v20, s0
	ds_write_b16 v64, v32 offset:544
	v_cvt_pk_bf16_f32 v32, v34, s0
	ds_write_b16 v64, v0 offset:10880
	v_cvt_pk_bf16_f32 v0, v4, s0
	ds_write_b16 v64, v32 offset:608
	v_cvt_pk_bf16_f32 v32, v51, s0
	ds_write_b16 v64, v0 offset:10944
	v_cvt_pk_bf16_f32 v0, v21, s0
	ds_write_b16 v64, v32 offset:816
	v_cvt_pk_bf16_f32 v32, v35, s0
	ds_write_b16 v64, v0 offset:11152
	v_cvt_pk_bf16_f32 v0, v5, s0
	ds_write_b16 v64, v32 offset:880
	v_cvt_pk_bf16_f32 v32, v52, s0
	ds_write_b16 v64, v0 offset:11216
	v_cvt_pk_bf16_f32 v0, v22, s0
	ds_write_b16 v64, v32 offset:2176
	v_cvt_pk_bf16_f32 v32, v36, s0
	ds_write_b16 v64, v0 offset:11424
	v_cvt_pk_bf16_f32 v0, v6, s0
	ds_write_b16 v64, v32 offset:2240
	v_cvt_pk_bf16_f32 v32, v53, s0
	ds_write_b16 v64, v0 offset:11488
	v_cvt_pk_bf16_f32 v0, v23, s0
	ds_write_b16 v64, v32 offset:2448
	v_cvt_pk_bf16_f32 v32, v37, s0
	ds_write_b16 v64, v0 offset:11696
	v_cvt_pk_bf16_f32 v0, v7, s0
	ds_write_b16 v64, v32 offset:2512
	v_cvt_pk_bf16_f32 v32, v54, s0
	ds_write_b16 v64, v0 offset:11760
	v_cvt_pk_bf16_f32 v0, v24, s0
	ds_write_b16 v64, v32 offset:2720
	v_cvt_pk_bf16_f32 v32, v38, s0
	ds_write_b16 v64, v0 offset:13056
	v_cvt_pk_bf16_f32 v0, v8, s0
	ds_write_b16 v64, v32 offset:2784
	v_cvt_pk_bf16_f32 v32, v55, s0
	ds_write_b16 v64, v0 offset:13120
	v_cvt_pk_bf16_f32 v0, v25, s0
	ds_write_b16 v64, v32 offset:2992
	v_cvt_pk_bf16_f32 v32, v39, s0
	ds_write_b16 v64, v0 offset:13328
	v_cvt_pk_bf16_f32 v0, v9, s0
	ds_write_b16 v64, v32 offset:3056
	v_cvt_pk_bf16_f32 v32, v56, s0
	ds_write_b16 v64, v0 offset:13392
	v_cvt_pk_bf16_f32 v0, v26, s0
	ds_write_b16 v64, v32 offset:4352
	v_cvt_pk_bf16_f32 v32, v40, s0
	ds_write_b16 v64, v0 offset:13600
	v_cvt_pk_bf16_f32 v0, v10, s0
	ds_write_b16 v64, v32 offset:4416
	v_cvt_pk_bf16_f32 v32, v57, s0
	ds_write_b16 v64, v0 offset:13664
	v_cvt_pk_bf16_f32 v0, v27, s0
	ds_write_b16 v64, v32 offset:4624
	v_cvt_pk_bf16_f32 v32, v41, s0
	ds_write_b16 v64, v0 offset:13872
	v_cvt_pk_bf16_f32 v0, v11, s0
	ds_write_b16 v64, v32 offset:4688
	v_cvt_pk_bf16_f32 v32, v58, s0
	ds_write_b16 v64, v0 offset:13936
	v_cvt_pk_bf16_f32 v0, v28, s0
	ds_write_b16 v64, v32 offset:4896
	v_cvt_pk_bf16_f32 v32, v42, s0
	ds_write_b16 v64, v0 offset:15232
	v_cvt_pk_bf16_f32 v0, v12, s0
	ds_write_b16 v64, v32 offset:4960
	v_cvt_pk_bf16_f32 v32, v59, s0
	ds_write_b16 v64, v0 offset:15296
	v_cvt_pk_bf16_f32 v0, v29, s0
	ds_write_b16 v64, v32 offset:5168
	v_cvt_pk_bf16_f32 v32, v43, s0
	ds_write_b16 v64, v0 offset:15504
	v_cvt_pk_bf16_f32 v0, v13, s0
	ds_write_b16 v64, v32 offset:5232
	v_cvt_pk_bf16_f32 v32, v60, s0
	ds_write_b16 v64, v0 offset:15568
	v_cvt_pk_bf16_f32 v0, v30, s0
	ds_write_b16 v64, v32 offset:6528
	v_cvt_pk_bf16_f32 v32, v44, s0
	ds_write_b16 v64, v0 offset:15776
	v_cvt_pk_bf16_f32 v0, v14, s0
	s_mul_i32 s11, s11, 0x160000
	ds_write_b16 v64, v32 offset:6592
	v_cvt_pk_bf16_f32 v32, v61, s0
	ds_write_b16 v64, v0 offset:15840
	v_cvt_pk_bf16_f32 v0, v31, s0
	s_add_u32 s41, s13, s11
	ds_write_b16 v64, v32 offset:6800
	v_cvt_pk_bf16_f32 v32, v45, s0
	ds_write_b16 v64, v0 offset:16048
	v_cvt_pk_bf16_f32 v0, v15, s0
	s_addc_u32 s44, s14, 0
	s_ashr_i32 s11, s10, 31
	ds_write_b16 v64, v32 offset:6864
	v_cvt_pk_bf16_f32 v32, v62, s0
	ds_write_b16 v64, v0 offset:16112
	s_lshl_b64 s[10:11], s[10:11], 1
	v_lshlrev_b32_e32 v0, 4, v102
	ds_write_b16 v64, v32 offset:7072
	v_cvt_pk_bf16_f32 v32, v46, s0
	s_add_u32 s10, s41, s10
	v_and_b32_e32 v96, 0xf0, v0
	ds_write_b16 v64, v32 offset:7136
	v_cvt_pk_bf16_f32 v32, v63, s0
	s_addc_u32 s11, s44, s11
	v_add_u32_e32 v8, 32, v96
	v_ashrrev_i32_e32 v9, 4, v102
	v_add_u32_e32 v4, 0x100, v102
	v_cvt_pk_bf16_f32 v48, v48, s0
	ds_write_b16 v64, v32 offset:7344
	v_cvt_pk_bf16_f32 v32, v47, s0
	v_cvt_pk_bf16_f32 v16, v16, s0
	v_lshl_add_u64 v[10:11], s[10:11], 0, v[96:97]
	v_mad_u64_u32 v[0:1], s[10:11], v9, s36, v[8:9]
	v_ashrrev_i32_e32 v14, 4, v4
	ds_write_b16 v64, v48
	ds_write_b16 v64, v32 offset:7408
	ds_write_b16 v64, v16 offset:8704
	s_waitcnt lgkmcnt(0)
	s_barrier
	ds_read_b128 v[0:3], v0
	v_mad_u64_u32 v[4:5], s[10:11], v14, s36, v[8:9]
	ds_read_b128 v[4:7], v4
	v_mad_i64_i32 v[12:13], s[10:11], v9, s37, v[10:11]
	s_waitcnt lgkmcnt(1)
	global_store_dwordx4 v[12:13], v[0:3], off
	s_nop 1
	v_mad_i64_i32 v[0:1], s[10:11], v14, s37, v[10:11]
	s_waitcnt lgkmcnt(0)
	global_store_dwordx4 v[0:1], v[4:7], off
	v_add_u32_e32 v0, 0x200, v102
	v_ashrrev_i32_e32 v9, 4, v0
	v_add_u32_e32 v4, 0x300, v102
	v_mad_u64_u32 v[0:1], s[10:11], v9, s36, v[8:9]
	v_ashrrev_i32_e32 v14, 4, v4
	ds_read_b128 v[0:3], v0
	v_mad_u64_u32 v[4:5], s[10:11], v14, s36, v[8:9]
	ds_read_b128 v[4:7], v4
	v_mad_i64_i32 v[12:13], s[10:11], v9, s37, v[10:11]
	s_waitcnt lgkmcnt(1)
	global_store_dwordx4 v[12:13], v[0:3], off
	s_nop 1
	v_mad_i64_i32 v[0:1], s[10:11], v14, s37, v[10:11]
	s_waitcnt lgkmcnt(0)
	global_store_dwordx4 v[0:1], v[4:7], off
	v_add_u32_e32 v0, 0x400, v102
	v_ashrrev_i32_e32 v9, 4, v0
	v_add_u32_e32 v4, 0x500, v102
	v_mad_u64_u32 v[0:1], s[10:11], v9, s36, v[8:9]
	v_ashrrev_i32_e32 v14, 4, v4
	ds_read_b128 v[0:3], v0
	v_mad_u64_u32 v[4:5], s[10:11], v14, s36, v[8:9]
	ds_read_b128 v[4:7], v4
	v_mad_i64_i32 v[12:13], s[10:11], v9, s37, v[10:11]
	s_waitcnt lgkmcnt(1)
	global_store_dwordx4 v[12:13], v[0:3], off
	s_nop 1
	v_mad_i64_i32 v[0:1], s[10:11], v14, s37, v[10:11]
	s_waitcnt lgkmcnt(0)
	global_store_dwordx4 v[0:1], v[4:7], off
	v_add_u32_e32 v0, 0x600, v102
	v_ashrrev_i32_e32 v9, 4, v0
	v_add_u32_e32 v4, 0x700, v102
	v_mad_u64_u32 v[0:1], s[10:11], v9, s36, v[8:9]
	v_ashrrev_i32_e32 v12, 4, v4
	ds_read_b128 v[0:3], v0
	v_mad_u64_u32 v[4:5], s[10:11], v12, s36, v[8:9]
	ds_read_b128 v[4:7], v4
	v_mad_i64_i32 v[8:9], s[10:11], v9, s37, v[10:11]
	s_waitcnt lgkmcnt(1)
	global_store_dwordx4 v[8:9], v[0:3], off
	s_nop 1
	v_mad_i64_i32 v[0:1], s[10:11], v12, s37, v[10:11]
	s_waitcnt lgkmcnt(0)
	global_store_dwordx4 v[0:1], v[4:7], off
	s_branch .LBB0_1937

.LBB0_2062:
	s_setprio 1
	ds_read_b128 v[146:149], v109
	ds_read_b128 v[150:153], v110 offset:36864
	ds_read_b128 v[154:157], v110 offset:41472
	ds_read_b128 v[192:195], v109 offset:4608
	s_waitcnt lgkmcnt(2)
	v_mfma_f32_32x32x16_bf16 v[32:47], v[146:149], v[150:153], v[32:47]
	ds_read_b128 v[196:199], v109 offset:32
	ds_read_b128 v[200:203], v110 offset:36896
	global_load_dwordx4 v[114:117], v174, s[98:99] offset:3840
	global_load_dwordx4 v[118:121], v176, s[98:99] offset:3840
	s_waitcnt vmcnt(9)
	ds_write_b128 v111, v[68:71] offset:18432
	s_waitcnt lgkmcnt(4)
	v_mfma_f32_32x32x16_bf16 v[48:63], v[146:149], v[154:157], v[48:63]
	ds_read_b128 v[204:207], v110 offset:41504
	global_load_dwordx4 v[122:125], v178, s[98:99] offset:3840
	global_load_dwordx4 v[126:129], v180, s[98:99] offset:3840
	s_waitcnt lgkmcnt(4)
	v_mfma_f32_32x32x16_bf16 v[16:31], v[192:195], v[150:153], v[16:31]
	ds_read_b128 v[208:211], v109 offset:4640
	global_load_dwordx4 v[130:133], v182, s[98:99] offset:3840
	global_load_dwordx4 v[134:137], v184, s[98:99] offset:3840
	s_waitcnt vmcnt(11)
	ds_write_b128 v111, v[84:87] offset:23040
	v_mfma_f32_32x32x16_bf16 v[0:15], v[192:195], v[154:157], v[0:15]
	global_load_dwordx4 v[138:141], v186, s[98:99] offset:3840
	global_load_dwordx4 v[142:145], v188, s[98:99] offset:3840
	s_waitcnt lgkmcnt(4)
	v_mfma_f32_32x32x16_bf16 v[32:47], v[196:199], v[200:203], v[32:47]
	ds_read_b128 v[212:215], v109 offset:64
	ds_read_b128 v[216:219], v110 offset:36928
	s_waitcnt vmcnt(12)
	ds_write_b128 v111, v[88:91] offset:27648
	s_waitcnt lgkmcnt(5)
	v_mfma_f32_32x32x16_bf16 v[48:63], v[196:199], v[204:207], v[48:63]
	ds_read_b128 v[220:223], v110 offset:41536
	s_waitcnt lgkmcnt(5)
	v_mfma_f32_32x32x16_bf16 v[16:31], v[208:211], v[200:203], v[16:31]
	ds_read_b128 v[224:227], v109 offset:4672
	s_waitcnt vmcnt(11)
	ds_write_b128 v111, v[92:95] offset:32256
	v_mfma_f32_32x32x16_bf16 v[0:15], v[208:211], v[204:207], v[0:15]
	s_waitcnt lgkmcnt(4)
	v_mfma_f32_32x32x16_bf16 v[32:47], v[212:215], v[216:219], v[32:47]
	ds_read_b128 v[228:231], v109 offset:96
	ds_read_b128 v[146:149], v110 offset:36960
	ds_write_b128 v111, v[64:67] offset:55296
	s_waitcnt lgkmcnt(5)
	v_mfma_f32_32x32x16_bf16 v[48:63], v[212:215], v[220:223], v[48:63]
	ds_read_b128 v[150:153], v110 offset:41568
	s_waitcnt lgkmcnt(5)
	v_mfma_f32_32x32x16_bf16 v[16:31], v[224:227], v[216:219], v[16:31]
	ds_read_b128 v[154:157], v109 offset:4704
	s_waitcnt vmcnt(10)
	ds_write_b128 v111, v[72:75] offset:59904
	v_mfma_f32_32x32x16_bf16 v[0:15], v[224:227], v[220:223], v[0:15]
	s_waitcnt lgkmcnt(4)
	v_mfma_f32_32x32x16_bf16 v[32:47], v[228:231], v[146:149], v[32:47]
	s_waitcnt vmcnt(9)
	ds_write_b128 v111, v[76:79] offset:64512
	s_waitcnt lgkmcnt(3)
	v_mfma_f32_32x32x16_bf16 v[48:63], v[228:231], v[150:153], v[48:63]
	s_waitcnt lgkmcnt(2)
	v_mfma_f32_32x32x16_bf16 v[16:31], v[154:157], v[146:149], v[16:31]
	s_waitcnt vmcnt(8)
	ds_write_b128 v112, v[80:83] offset:13824
	v_mfma_f32_32x32x16_bf16 v[0:15], v[154:157], v[150:153], v[0:15]
	s_setprio 0
	s_waitcnt lgkmcnt(0)
	s_barrier
	s_setprio 1
	ds_read_b128 v[146:149], v109 offset:18432
	ds_read_b128 v[150:153], v110 offset:55296
	ds_read_b128 v[154:157], v110 offset:59904
	ds_read_b128 v[192:195], v109 offset:23040
	s_waitcnt lgkmcnt(2)
	v_mfma_f32_32x32x16_bf16 v[32:47], v[146:149], v[150:153], v[32:47]
	ds_read_b128 v[196:199], v109 offset:18464
	ds_read_b128 v[200:203], v110 offset:55328
	global_load_dwordx4 v[68:71], v174, s[98:99] offset:3968
	global_load_dwordx4 v[84:87], v176, s[98:99] offset:3968
	s_waitcnt vmcnt(9)
	ds_write_b128 v111, v[114:117]
	s_waitcnt lgkmcnt(4)
	v_mfma_f32_32x32x16_bf16 v[48:63], v[146:149], v[154:157], v[48:63]
	ds_read_b128 v[204:207], v110 offset:59936
	global_load_dwordx4 v[88:91], v178, s[98:99] offset:3968
	global_load_dwordx4 v[92:95], v180, s[98:99] offset:3968
	s_waitcnt lgkmcnt(4)
	v_mfma_f32_32x32x16_bf16 v[16:31], v[192:195], v[150:153], v[16:31]
	ds_read_b128 v[208:211], v109 offset:23072
	global_load_dwordx4 v[64:67], v182, s[98:99] offset:3968
	global_load_dwordx4 v[72:75], v184, s[98:99] offset:3968
	s_waitcnt vmcnt(12)
	ds_write_b128 v111, v[118:121] offset:4608
	v_mfma_f32_32x32x16_bf16 v[0:15], v[192:195], v[154:157], v[0:15]
	global_load_dwordx4 v[76:79], v186, s[98:99] offset:3968
	global_load_dwordx4 v[80:83], v188, s[98:99] offset:3968
	s_waitcnt lgkmcnt(4)
	v_mfma_f32_32x32x16_bf16 v[32:47], v[196:199], v[200:203], v[32:47]
	ds_read_b128 v[212:215], v109 offset:18496
	ds_read_b128 v[216:219], v110 offset:55360
	s_add_u32 s98, s98, 0x100
	s_addc_u32 s99, s99, 0
	s_add_i32 s8, s8, 2
	s_cmp_lt_u32 s8, 39
	s_waitcnt vmcnt(13)
	ds_write_b128 v111, v[122:125] offset:9216
	s_waitcnt lgkmcnt(5)
	v_mfma_f32_32x32x16_bf16 v[48:63], v[196:199], v[204:207], v[48:63]
	ds_read_b128 v[220:223], v110 offset:59968
	s_waitcnt lgkmcnt(5)
	v_mfma_f32_32x32x16_bf16 v[16:31], v[208:211], v[200:203], v[16:31]
	ds_read_b128 v[224:227], v109 offset:23104
	s_waitcnt vmcnt(12)
	ds_write_b128 v111, v[126:129] offset:13824
	v_mfma_f32_32x32x16_bf16 v[0:15], v[208:211], v[204:207], v[0:15]
	s_waitcnt lgkmcnt(4)
	v_mfma_f32_32x32x16_bf16 v[32:47], v[212:215], v[216:219], v[32:47]
	ds_read_b128 v[228:231], v109 offset:18528
	ds_read_b128 v[146:149], v110 offset:55392
	s_waitcnt vmcnt(11)
	ds_write_b128 v111, v[130:133] offset:36864
	s_waitcnt lgkmcnt(5)
	v_mfma_f32_32x32x16_bf16 v[48:63], v[212:215], v[220:223], v[48:63]
	ds_read_b128 v[150:153], v110 offset:60000
	s_waitcnt lgkmcnt(5)
	v_mfma_f32_32x32x16_bf16 v[16:31], v[224:227], v[216:219], v[16:31]
	ds_read_b128 v[154:157], v109 offset:23136
	s_waitcnt vmcnt(10)
	ds_write_b128 v111, v[134:137] offset:41472
	v_mfma_f32_32x32x16_bf16 v[0:15], v[224:227], v[220:223], v[0:15]
	s_waitcnt lgkmcnt(4)
	v_mfma_f32_32x32x16_bf16 v[32:47], v[228:231], v[146:149], v[32:47]
	s_waitcnt vmcnt(9)
	ds_write_b128 v111, v[138:141] offset:46080
	s_waitcnt lgkmcnt(3)
	v_mfma_f32_32x32x16_bf16 v[48:63], v[228:231], v[150:153], v[48:63]
	s_waitcnt lgkmcnt(2)
	v_mfma_f32_32x32x16_bf16 v[16:31], v[154:157], v[146:149], v[16:31]
	s_waitcnt vmcnt(8)
	ds_write_b128 v111, v[142:145] offset:50688
	v_mfma_f32_32x32x16_bf16 v[0:15], v[154:157], v[150:153], v[0:15]
	s_setprio 0
	s_waitcnt lgkmcnt(0)
	s_barrier
	s_cbranch_scc1 .LBB0_2062
	s_setprio 1
	ds_read_b128 v[104:107], v109
	ds_read_b128 v[114:117], v110 offset:36864
	ds_read_b128 v[118:121], v110 offset:41472
	ds_read_b128 v[192:195], v109 offset:4608
	s_waitcnt lgkmcnt(2)
	v_mfma_f32_32x32x16_bf16 v[32:47], v[104:107], v[114:117], v[32:47]
	ds_read_b128 v[196:199], v109 offset:32
	ds_read_b128 v[200:203], v110 offset:36896
	s_waitcnt vmcnt(7)
	ds_write_b128 v111, v[68:71] offset:18432
	s_waitcnt lgkmcnt(4)
	v_mfma_f32_32x32x16_bf16 v[48:63], v[104:107], v[118:121], v[48:63]
	ds_read_b128 v[204:207], v110 offset:41504
	s_waitcnt lgkmcnt(4)
	v_mfma_f32_32x32x16_bf16 v[16:31], v[192:195], v[114:117], v[16:31]
	ds_read_b128 v[208:211], v109 offset:4640
	s_waitcnt vmcnt(6)
	ds_write_b128 v111, v[84:87] offset:23040
	v_mfma_f32_32x32x16_bf16 v[0:15], v[192:195], v[118:121], v[0:15]
	s_waitcnt lgkmcnt(4)
	v_mfma_f32_32x32x16_bf16 v[32:47], v[196:199], v[200:203], v[32:47]
	ds_read_b128 v[212:215], v109 offset:64
	ds_read_b128 v[216:219], v110 offset:36928
	s_waitcnt vmcnt(5)
	ds_write_b128 v111, v[88:91] offset:27648
	s_waitcnt lgkmcnt(5)
	v_mfma_f32_32x32x16_bf16 v[48:63], v[196:199], v[204:207], v[48:63]
	ds_read_b128 v[220:223], v110 offset:41536
	s_waitcnt lgkmcnt(5)
	v_mfma_f32_32x32x16_bf16 v[16:31], v[208:211], v[200:203], v[16:31]
	ds_read_b128 v[224:227], v109 offset:4672
	s_waitcnt vmcnt(4)
	ds_write_b128 v111, v[92:95] offset:32256
	v_mfma_f32_32x32x16_bf16 v[0:15], v[208:211], v[204:207], v[0:15]
	s_waitcnt lgkmcnt(4)
	v_mfma_f32_32x32x16_bf16 v[32:47], v[212:215], v[216:219], v[32:47]
	ds_read_b128 v[228:231], v109 offset:96
	ds_read_b128 v[104:107], v110 offset:36960
	s_waitcnt vmcnt(3)
	ds_write_b128 v111, v[64:67] offset:55296
	s_waitcnt lgkmcnt(5)
	v_mfma_f32_32x32x16_bf16 v[48:63], v[212:215], v[220:223], v[48:63]
	ds_read_b128 v[114:117], v109 offset:4704
	s_waitcnt lgkmcnt(5)
	v_mfma_f32_32x32x16_bf16 v[16:31], v[224:227], v[216:219], v[16:31]
	ds_read_b128 v[118:121], v110 offset:41568
	s_waitcnt vmcnt(2)
	ds_write_b128 v111, v[72:75] offset:59904
	v_mfma_f32_32x32x16_bf16 v[0:15], v[224:227], v[220:223], v[0:15]
	s_waitcnt lgkmcnt(4)
	v_mfma_f32_32x32x16_bf16 v[32:47], v[228:231], v[104:107], v[32:47]
	s_waitcnt vmcnt(1)
	ds_write_b128 v111, v[76:79] offset:64512
	s_waitcnt lgkmcnt(3)
	v_mfma_f32_32x32x16_bf16 v[16:31], v[114:117], v[104:107], v[16:31]
	s_waitcnt lgkmcnt(2)
	v_mfma_f32_32x32x16_bf16 v[0:15], v[114:117], v[118:121], v[0:15]
	s_waitcnt vmcnt(0)
	ds_write_b128 v112, v[80:83] offset:13824
	v_mfma_f32_32x32x16_bf16 v[48:63], v[228:231], v[118:121], v[48:63]
	s_setprio 0
	s_waitcnt lgkmcnt(0)
	s_barrier
	s_setprio 1
	ds_read_b128 v[64:67], v109 offset:18432
	ds_read_b128 v[68:71], v110 offset:55296
	ds_read_b128 v[72:75], v110 offset:59904
	ds_read_b128 v[192:195], v109 offset:23040
	s_waitcnt lgkmcnt(2)
	v_mfma_f32_32x32x16_bf16 v[32:47], v[64:67], v[68:71], v[32:47]
	ds_read_b128 v[196:199], v109 offset:18464
	ds_read_b128 v[200:203], v110 offset:55328
	s_waitcnt lgkmcnt(3)
	v_mfma_f32_32x32x16_bf16 v[48:63], v[64:67], v[72:75], v[48:63]
	ds_read_b128 v[204:207], v110 offset:59936
	s_waitcnt lgkmcnt(3)
	v_mfma_f32_32x32x16_bf16 v[16:31], v[192:195], v[68:71], v[16:31]
	ds_read_b128 v[208:211], v109 offset:23072
	v_mfma_f32_32x32x16_bf16 v[0:15], v[192:195], v[72:75], v[0:15]
	s_waitcnt lgkmcnt(2)
	v_mfma_f32_32x32x16_bf16 v[32:47], v[196:199], v[200:203], v[32:47]
	ds_read_b128 v[212:215], v109 offset:18496
	ds_read_b128 v[216:219], v110 offset:55360
	s_waitcnt lgkmcnt(3)
	v_mfma_f32_32x32x16_bf16 v[48:63], v[196:199], v[204:207], v[48:63]
	ds_read_b128 v[220:223], v110 offset:59968
	s_waitcnt lgkmcnt(3)
	v_mfma_f32_32x32x16_bf16 v[16:31], v[208:211], v[200:203], v[16:31]
	ds_read_b128 v[224:227], v109 offset:23104
	v_mfma_f32_32x32x16_bf16 v[0:15], v[208:211], v[204:207], v[0:15]
	s_waitcnt lgkmcnt(2)
	v_mfma_f32_32x32x16_bf16 v[32:47], v[212:215], v[216:219], v[32:47]
	ds_read_b128 v[228:231], v109 offset:18528
	ds_read_b128 v[64:67], v110 offset:55392
	s_waitcnt lgkmcnt(3)
	v_mfma_f32_32x32x16_bf16 v[48:63], v[212:215], v[220:223], v[48:63]
	ds_read_b128 v[68:71], v109 offset:23136
	s_waitcnt lgkmcnt(3)
	v_mfma_f32_32x32x16_bf16 v[16:31], v[224:227], v[216:219], v[16:31]
	ds_read_b128 v[72:75], v110 offset:60000
	v_mfma_f32_32x32x16_bf16 v[0:15], v[224:227], v[220:223], v[0:15]
	s_waitcnt lgkmcnt(2)
	v_mfma_f32_32x32x16_bf16 v[32:47], v[228:231], v[64:67], v[32:47]
	s_waitcnt lgkmcnt(1)
	v_mfma_f32_32x32x16_bf16 v[16:31], v[68:71], v[64:67], v[16:31]
	s_waitcnt lgkmcnt(0)
	v_mfma_f32_32x32x16_bf16 v[0:15], v[68:71], v[72:75], v[0:15]
	v_mfma_f32_32x32x16_bf16 v[48:63], v[228:231], v[72:75], v[48:63]
	s_setprio 0
	s_addk_i32 s0, 0xf000
	s_lshr_b32 s8, s0, 10
	s_mulk_i32 s8, 0x1800
	s_addk_i32 s8, 0x1800
	s_and_b64 s[58:59], s[4:5], exec
	s_cselect_b32 s8, 0, s8
	v_mov_b32_e32 v68, v234
	s_barrier
	s_lshl_b64 s[58:59], s[8:9], 2
	s_add_u32 s58, s30, s58
	v_and_b32_e32 v69, 0x5f, v68
	v_or_b32_e32 v64, s23, v69
	s_addc_u32 s59, s31, s59
	v_ashrrev_i32_e32 v65, 31, v64
	v_lshl_add_u64 v[64:65], v[64:65], 2, s[58:59]
	v_lshl_add_u64 v[66:67], v[64:65], 0, s[12:13]
	v_add_co_u32_e32 v64, vcc, s51, v64
	global_load_dword v66, v[66:67], off offset:128
	s_nop 0
	v_addc_co_u32_e32 v65, vcc, 0, v65, vcc
	global_load_dword v64, v[64:65], off
	v_lshrrev_b32_e32 v67, 3, v68
	v_lshrrev_b32_e32 v65, 1, v68
	v_and_b32_e32 v67, 4, v67
	v_and_or_b32 v65, v65, s45, v67
	v_lshlrev_b32_e32 v69, 2, v69
	v_mul_lo_u32 v65, v65, s52
	v_add3_u32 v65, 32, v69, v65
	v_add_u32_e32 v67, 0x400, v65
	v_add_u32_e32 v69, 0x1000, v65
	v_add_u32_e32 v70, 0x1400, v65
	v_add_u32_e32 v71, 0x2000, v65
	v_add_u32_e32 v72, 0x2400, v65
	v_add_u32_e32 v73, 0x3000, v65
	v_add_u32_e32 v74, 0x3200, v65
	v_add_u32_e32 v75, 0x3400, v65
	v_add_u32_e32 v76, 0x3600, v65
	v_add_u32_e32 v77, 0x4000, v65
	v_readlane_b32 s80, v250, 6
	v_readlane_b32 s81, v250, 7
	v_readlane_b32 s82, v250, 8
	v_readlane_b32 s83, v250, 9
	s_lshl_b32 s1, s1, 19
	s_add_u32 s8, s15, s1
	s_mov_b32 s1, s9
	v_readlane_b32 s84, v250, 10
	v_readlane_b32 s85, v250, 11
	v_readlane_b32 s86, v250, 12
	v_readlane_b32 s87, v250, 13
	v_readlane_b32 s88, v250, 14
	v_readlane_b32 s89, v250, 15
	v_readlane_b32 s90, v250, 16
	v_readlane_b32 s91, v250, 17
	v_readlane_b32 s92, v250, 18
	v_readlane_b32 s93, v250, 19
	v_readlane_b32 s94, v250, 20
	v_readlane_b32 s95, v250, 21
	s_waitcnt vmcnt(1)
	v_mul_f32_e32 v48, v48, v66
	v_mul_f32_e32 v0, v0, v66
	v_mul_f32_e32 v49, v49, v66
	s_waitcnt vmcnt(0)
	v_mul_f32_e32 v32, v32, v64
	v_mul_f32_e32 v50, v50, v66
	v_mul_f32_e32 v51, v51, v66
	v_mul_f32_e32 v52, v52, v66
	v_mul_f32_e32 v53, v53, v66
	v_mul_f32_e32 v54, v54, v66
	v_mul_f32_e32 v55, v55, v66
	v_mul_f32_e32 v56, v56, v66
	v_mul_f32_e32 v57, v57, v66
	v_mul_f32_e32 v58, v58, v66
	v_mul_f32_e32 v59, v59, v66
	v_mul_f32_e32 v60, v60, v66
	v_mul_f32_e32 v61, v61, v66
	v_mul_f32_e32 v62, v62, v66
	v_mul_f32_e32 v63, v63, v66
	v_mul_f32_e32 v33, v33, v64
	v_mul_f32_e32 v34, v34, v64
	v_mul_f32_e32 v35, v35, v64
	v_mul_f32_e32 v36, v36, v64
	v_mul_f32_e32 v37, v37, v64
	v_mul_f32_e32 v38, v38, v64
	v_mul_f32_e32 v39, v39, v64
	v_mul_f32_e32 v40, v40, v64
	v_mul_f32_e32 v41, v41, v64
	v_mul_f32_e32 v42, v42, v64
	v_mul_f32_e32 v43, v43, v64
	v_mul_f32_e32 v44, v44, v64
	v_mul_f32_e32 v45, v45, v64
	v_mul_f32_e32 v46, v46, v64
	v_mul_f32_e32 v47, v47, v64
	v_mul_f32_e32 v16, v16, v64
	v_mul_f32_e32 v17, v17, v64
	ds_write2_b32 v65, v32, v48 offset1:32
	ds_write2_b32 v65, v33, v49 offset0:132 offset1:164
	ds_write2_b32 v67, v34, v50 offset0:8 offset1:40
	ds_write2_b32 v67, v35, v51 offset0:140 offset1:172
	ds_write2_b32 v69, v36, v52 offset0:32 offset1:64
	ds_write2_b32 v69, v37, v53 offset0:164 offset1:196
	ds_write2_b32 v70, v38, v54 offset0:40 offset1:72
	ds_write2_b32 v70, v39, v55 offset0:172 offset1:204
	ds_write2_b32 v71, v40, v56 offset0:64 offset1:96
	ds_write2_b32 v71, v41, v57 offset0:196 offset1:228
	ds_write2_b32 v72, v42, v58 offset0:72 offset1:104
	ds_write2_b32 v72, v43, v59 offset0:204 offset1:236
	ds_write2_b32 v73, v44, v60 offset0:96 offset1:128
	ds_write2_b32 v74, v45, v61 offset0:100 offset1:132
	ds_write2_b32 v75, v46, v62 offset0:104 offset1:136
	ds_write2_b32 v76, v47, v63 offset0:108 offset1:140
	ds_write2_b32 v77, v16, v0 offset0:128 offset1:160
	v_mul_f32_e32 v0, v1, v66
	v_add_u32_e32 v1, 0x4400, v65
	ds_write2_b32 v1, v17, v0 offset0:4 offset1:36
	v_mul_f32_e32 v0, v18, v64
	v_mul_f32_e32 v2, v2, v66
	ds_write2_b32 v1, v0, v2 offset0:136 offset1:168
	v_mul_f32_e32 v0, v19, v64
	v_mul_f32_e32 v1, v3, v66
	v_add_u32_e32 v2, 0x4800, v65
	ds_write2_b32 v2, v0, v1 offset0:12 offset1:44
	v_mul_f32_e32 v0, v20, v64
	v_mul_f32_e32 v1, v4, v66
	v_add_u32_e32 v2, 0x5000, v65
	ds_write2_b32 v2, v0, v1 offset0:160 offset1:192
	v_mul_f32_e32 v0, v21, v64
	v_mul_f32_e32 v1, v5, v66
	v_add_u32_e32 v2, 0x5400, v65
	ds_write2_b32 v2, v0, v1 offset0:36 offset1:68
	v_mul_f32_e32 v0, v22, v64
	v_mul_f32_e32 v1, v6, v66
	ds_write2_b32 v2, v0, v1 offset0:168 offset1:200
	v_mul_f32_e32 v0, v23, v64
	v_mul_f32_e32 v1, v7, v66
	v_add_u32_e32 v2, 0x5800, v65
	ds_write2_b32 v2, v0, v1 offset0:44 offset1:76
	v_mul_f32_e32 v0, v24, v64
	v_mul_f32_e32 v1, v8, v66
	v_add_u32_e32 v2, 0x6000, v65
	ds_write2_b32 v2, v0, v1 offset0:192 offset1:224
	v_mul_f32_e32 v0, v25, v64
	v_mul_f32_e32 v1, v9, v66
	v_add_u32_e32 v2, 0x6400, v65
	ds_write2_b32 v2, v0, v1 offset0:68 offset1:100
	v_mul_f32_e32 v0, v26, v64
	v_mul_f32_e32 v1, v10, v66
	ds_write2_b32 v2, v0, v1 offset0:200 offset1:232
	v_mul_f32_e32 v0, v27, v64
	v_mul_f32_e32 v1, v11, v66
	v_add_u32_e32 v2, 0x6800, v65
	ds_write2_b32 v2, v0, v1 offset0:76 offset1:108
	v_mul_f32_e32 v0, v28, v64
	v_mul_f32_e32 v1, v12, v66
	v_add_u32_e32 v2, 0x7200, v65
	ds_write2_b32 v2, v0, v1 offset0:96 offset1:128
	v_mul_f32_e32 v0, v29, v64
	v_mul_f32_e32 v1, v13, v66
	v_add_u32_e32 v2, 0x7400, v65
	ds_write2_b32 v2, v0, v1 offset0:100 offset1:132
	v_mul_f32_e32 v0, v30, v64
	v_mul_f32_e32 v1, v14, v66
	v_add_u32_e32 v2, 0x7600, v65
	v_and_b32_e32 v12, 31, v68
	ds_write2_b32 v2, v0, v1 offset0:104 offset1:136
	v_mul_f32_e32 v0, v31, v64
	v_mul_f32_e32 v1, v15, v66
	v_add_u32_e32 v2, 0x7800, v65
	v_lshlrev_b32_e32 v8, 2, v12
	ds_write2_b32 v2, v0, v1 offset0:108 offset1:140
	v_or_b32_e32 v0, s23, v8
	v_ashrrev_i32_e32 v1, 31, v0
	v_lshlrev_b64 v[0:1], 2, v[0:1]
	v_lshl_add_u64 v[2:3], s[80:81], 0, v[0:1]
	v_lshl_add_u64 v[4:5], s[82:83], 0, v[0:1]
	s_waitcnt lgkmcnt(0)
	s_barrier
	global_load_dwordx4 v[0:3], v[2:3], off
	s_nop 0
	global_load_dwordx4 v[4:7], v[4:5], off
	v_and_b32_e32 v9, 64, v108
	v_add_u32_e32 v9, 64, v9
	v_xor_b32_e32 v10, 1, v108
	v_cmp_lt_i32_e32 vcc, v10, v9
	s_addc_u32 s23, s17, 0
	s_lshl_b64 s[0:1], s[0:1], 12
	v_cndmask_b32_e32 v10, v108, v10, vcc
	v_lshlrev_b32_e32 v32, 2, v10
	v_xor_b32_e32 v10, 2, v108
	v_cmp_lt_i32_e32 vcc, v10, v9
	s_add_u32 s58, s24, s0
	s_addc_u32 s59, s25, s1
	v_cndmask_b32_e32 v10, v108, v10, vcc
	v_lshlrev_b32_e32 v33, 2, v10
	v_xor_b32_e32 v10, 4, v108
	v_cmp_lt_i32_e32 vcc, v10, v9
	s_and_b64 s[0:1], s[4:5], exec
	v_ashrrev_i32_e32 v22, 5, v68
	v_cndmask_b32_e32 v10, v108, v10, vcc
	v_lshlrev_b32_e32 v34, 2, v10
	v_xor_b32_e32 v10, 8, v108
	s_cselect_b32 s59, s23, s59
	s_cselect_b32 s58, s8, s58
	v_cmp_lt_i32_e32 vcc, v10, v9
	s_add_i32 s8, s22, s35
	v_add_u32_e32 v16, s8, v22
	v_cndmask_b32_e32 v10, v108, v10, vcc
	s_add_i32 s8, s22, s36
	s_add_i32 s22, s22, s37
	v_lshlrev_b32_e32 v35, 2, v10
	v_xor_b32_e32 v10, 16, v108
	v_add_u32_e32 v20, s8, v22
	v_add_u32_e32 v24, s22, v22
	v_cmp_eq_u32_e64 s[0:1], 0, v12
	v_cmp_lt_i32_e32 vcc, v10, v9
	v_ashrrev_i32_e32 v23, 31, v22
	v_mul_lo_u32 v13, v22, s52
	v_lshlrev_b32_e32 v12, 4, v12
	v_add_u32_e32 v26, s21, v22
	v_ashrrev_i32_e32 v17, 31, v16
	v_ashrrev_i32_e32 v21, 31, v20
	v_ashrrev_i32_e32 v25, 31, v24
	v_cndmask_b32_e32 v9, v108, v10, vcc
	v_add_u32_e32 v8, s20, v8
	v_lshlrev_b64 v[10:11], 12, v[22:23]
	v_add3_u32 v37, v13, v12, 32
	v_lshlrev_b32_e32 v12, 1, v26
	v_lshlrev_b64 v[14:15], 12, v[16:17]
	v_lshlrev_b32_e32 v16, 1, v16
	v_lshlrev_b64 v[18:19], 12, v[20:21]
	v_lshlrev_b32_e32 v20, 1, v20
	v_lshlrev_b64 v[22:23], 12, v[24:25]
	v_lshlrev_b32_e32 v24, 1, v24
	v_ashrrev_i32_e32 v27, 31, v26
	v_lshlrev_b32_e32 v36, 2, v9
	v_ashrrev_i32_e32 v9, 31, v8
	v_ashrrev_i32_e32 v13, 31, v12
	v_ashrrev_i32_e32 v17, 31, v16
	v_ashrrev_i32_e32 v21, 31, v20
	v_ashrrev_i32_e32 v25, 31, v24
	v_lshlrev_b64 v[26:27], 12, v[26:27]
	v_lshlrev_b64 v[8:9], 2, v[8:9]
	v_lshl_add_u64 v[10:11], s[58:59], 0, v[10:11]
	v_lshl_add_u64 v[12:13], v[12:13], 2, s[30:31]
	v_lshl_add_u64 v[14:15], s[28:29], 0, v[14:15]
	v_lshl_add_u64 v[16:17], v[16:17], 2, s[30:31]
	v_lshl_add_u64 v[18:19], s[28:29], 0, v[18:19]
	v_lshl_add_u64 v[20:21], v[20:21], 2, s[30:31]
	v_lshl_add_u64 v[22:23], s[28:29], 0, v[22:23]
	v_lshl_add_u64 v[24:25], v[24:25], 2, s[30:31]
	v_lshl_add_u64 v[26:27], s[6:7], 0, v[26:27]
	s_mov_b64 s[20:21], 0
	s_branch .LBB0_2065

.LBB0_2186:
	s_setprio 1
	ds_read_b128 v[140:143], v103
	ds_read_b128 v[144:147], v104 offset:36864
	ds_read_b128 v[148:151], v104 offset:41472
	ds_read_b128 v[192:195], v103 offset:4608
	s_waitcnt lgkmcnt(2)
	v_mfma_f32_32x32x16_bf16 v[48:63], v[140:143], v[144:147], v[48:63]
	ds_read_b128 v[196:199], v103 offset:32
	ds_read_b128 v[200:203], v104 offset:36896
	global_load_dwordx4 v[108:111], v168, s[98:99] offset:3840
	global_load_dwordx4 v[112:115], v170, s[98:99] offset:3840
	s_waitcnt vmcnt(9)
	ds_write_b128 v105, v[68:71] offset:18432
	s_waitcnt lgkmcnt(4)
	v_mfma_f32_32x32x16_bf16 v[32:47], v[140:143], v[148:151], v[32:47]
	ds_read_b128 v[204:207], v104 offset:41504
	global_load_dwordx4 v[116:119], v172, s[98:99] offset:3840
	global_load_dwordx4 v[120:123], v174, s[98:99] offset:3840
	s_waitcnt lgkmcnt(4)
	v_mfma_f32_32x32x16_bf16 v[16:31], v[192:195], v[144:147], v[16:31]
	ds_read_b128 v[208:211], v103 offset:4640
	global_load_dwordx4 v[124:127], v176, s[98:99] offset:3840
	global_load_dwordx4 v[128:131], v178, s[98:99] offset:3840
	s_waitcnt vmcnt(11)
	ds_write_b128 v105, v[84:87] offset:23040
	v_mfma_f32_32x32x16_bf16 v[0:15], v[192:195], v[148:151], v[0:15]
	global_load_dwordx4 v[132:135], v180, s[98:99] offset:3840
	global_load_dwordx4 v[136:139], v182, s[98:99] offset:3840
	s_waitcnt lgkmcnt(4)
	v_mfma_f32_32x32x16_bf16 v[48:63], v[196:199], v[200:203], v[48:63]
	ds_read_b128 v[212:215], v103 offset:64
	ds_read_b128 v[216:219], v104 offset:36928
	s_waitcnt vmcnt(12)
	ds_write_b128 v105, v[88:91] offset:27648
	s_waitcnt lgkmcnt(5)
	v_mfma_f32_32x32x16_bf16 v[32:47], v[196:199], v[204:207], v[32:47]
	ds_read_b128 v[220:223], v104 offset:41536
	s_waitcnt lgkmcnt(5)
	v_mfma_f32_32x32x16_bf16 v[16:31], v[208:211], v[200:203], v[16:31]
	ds_read_b128 v[224:227], v103 offset:4672
	s_waitcnt vmcnt(11)
	ds_write_b128 v105, v[92:95] offset:32256
	v_mfma_f32_32x32x16_bf16 v[0:15], v[208:211], v[204:207], v[0:15]
	s_waitcnt lgkmcnt(4)
	v_mfma_f32_32x32x16_bf16 v[48:63], v[212:215], v[216:219], v[48:63]
	ds_read_b128 v[228:231], v103 offset:96
	ds_read_b128 v[140:143], v104 offset:36960
	ds_write_b128 v105, v[64:67] offset:55296
	s_waitcnt lgkmcnt(5)
	v_mfma_f32_32x32x16_bf16 v[32:47], v[212:215], v[220:223], v[32:47]
	ds_read_b128 v[144:147], v104 offset:41568
	s_waitcnt lgkmcnt(5)
	v_mfma_f32_32x32x16_bf16 v[16:31], v[224:227], v[216:219], v[16:31]
	ds_read_b128 v[148:151], v103 offset:4704
	s_waitcnt vmcnt(10)
	ds_write_b128 v105, v[72:75] offset:59904
	v_mfma_f32_32x32x16_bf16 v[0:15], v[224:227], v[220:223], v[0:15]
	s_waitcnt lgkmcnt(4)
	v_mfma_f32_32x32x16_bf16 v[48:63], v[228:231], v[140:143], v[48:63]
	s_waitcnt vmcnt(9)
	ds_write_b128 v105, v[76:79] offset:64512
	s_waitcnt lgkmcnt(3)
	v_mfma_f32_32x32x16_bf16 v[32:47], v[228:231], v[144:147], v[32:47]
	s_waitcnt lgkmcnt(2)
	v_mfma_f32_32x32x16_bf16 v[16:31], v[148:151], v[140:143], v[16:31]
	s_waitcnt vmcnt(8)
	ds_write_b128 v106, v[80:83] offset:13824
	v_mfma_f32_32x32x16_bf16 v[0:15], v[148:151], v[144:147], v[0:15]
	s_setprio 0
	s_waitcnt lgkmcnt(0)
	s_barrier
	s_setprio 1
	ds_read_b128 v[140:143], v103 offset:18432
	ds_read_b128 v[144:147], v104 offset:55296
	ds_read_b128 v[148:151], v104 offset:59904
	ds_read_b128 v[192:195], v103 offset:23040
	s_waitcnt lgkmcnt(2)
	v_mfma_f32_32x32x16_bf16 v[48:63], v[140:143], v[144:147], v[48:63]
	ds_read_b128 v[196:199], v103 offset:18464
	ds_read_b128 v[200:203], v104 offset:55328
	global_load_dwordx4 v[68:71], v168, s[98:99] offset:3968
	global_load_dwordx4 v[84:87], v170, s[98:99] offset:3968
	s_waitcnt vmcnt(9)
	ds_write_b128 v105, v[108:111]
	s_waitcnt lgkmcnt(4)
	v_mfma_f32_32x32x16_bf16 v[32:47], v[140:143], v[148:151], v[32:47]
	ds_read_b128 v[204:207], v104 offset:59936
	global_load_dwordx4 v[88:91], v172, s[98:99] offset:3968
	global_load_dwordx4 v[92:95], v174, s[98:99] offset:3968
	s_waitcnt lgkmcnt(4)
	v_mfma_f32_32x32x16_bf16 v[16:31], v[192:195], v[144:147], v[16:31]
	ds_read_b128 v[208:211], v103 offset:23072
	global_load_dwordx4 v[64:67], v176, s[98:99] offset:3968
	global_load_dwordx4 v[72:75], v178, s[98:99] offset:3968
	s_waitcnt vmcnt(12)
	ds_write_b128 v105, v[112:115] offset:4608
	v_mfma_f32_32x32x16_bf16 v[0:15], v[192:195], v[148:151], v[0:15]
	global_load_dwordx4 v[76:79], v180, s[98:99] offset:3968
	global_load_dwordx4 v[80:83], v182, s[98:99] offset:3968
	s_waitcnt lgkmcnt(4)
	v_mfma_f32_32x32x16_bf16 v[48:63], v[196:199], v[200:203], v[48:63]
	ds_read_b128 v[212:215], v103 offset:18496
	ds_read_b128 v[216:219], v104 offset:55360
	s_add_u32 s98, s98, 0x100
	s_addc_u32 s99, s99, 0
	s_add_i32 s4, s4, 2
	s_cmp_lt_u32 s4, 11
	s_waitcnt vmcnt(13)
	ds_write_b128 v105, v[116:119] offset:9216
	s_waitcnt lgkmcnt(5)
	v_mfma_f32_32x32x16_bf16 v[32:47], v[196:199], v[204:207], v[32:47]
	ds_read_b128 v[220:223], v104 offset:59968
	s_waitcnt lgkmcnt(5)
	v_mfma_f32_32x32x16_bf16 v[16:31], v[208:211], v[200:203], v[16:31]
	ds_read_b128 v[224:227], v103 offset:23104
	s_waitcnt vmcnt(12)
	ds_write_b128 v105, v[120:123] offset:13824
	v_mfma_f32_32x32x16_bf16 v[0:15], v[208:211], v[204:207], v[0:15]
	s_waitcnt lgkmcnt(4)
	v_mfma_f32_32x32x16_bf16 v[48:63], v[212:215], v[216:219], v[48:63]
	ds_read_b128 v[228:231], v103 offset:18528
	ds_read_b128 v[140:143], v104 offset:55392
	s_waitcnt vmcnt(11)
	ds_write_b128 v105, v[124:127] offset:36864
	s_waitcnt lgkmcnt(5)
	v_mfma_f32_32x32x16_bf16 v[32:47], v[212:215], v[220:223], v[32:47]
	ds_read_b128 v[144:147], v104 offset:60000
	s_waitcnt lgkmcnt(5)
	v_mfma_f32_32x32x16_bf16 v[16:31], v[224:227], v[216:219], v[16:31]
	ds_read_b128 v[148:151], v103 offset:23136
	s_waitcnt vmcnt(10)
	ds_write_b128 v105, v[128:131] offset:41472
	v_mfma_f32_32x32x16_bf16 v[0:15], v[224:227], v[220:223], v[0:15]
	s_waitcnt lgkmcnt(4)
	v_mfma_f32_32x32x16_bf16 v[48:63], v[228:231], v[140:143], v[48:63]
	s_waitcnt vmcnt(9)
	ds_write_b128 v105, v[132:135] offset:46080
	s_waitcnt lgkmcnt(3)
	v_mfma_f32_32x32x16_bf16 v[32:47], v[228:231], v[144:147], v[32:47]
	s_waitcnt lgkmcnt(2)
	v_mfma_f32_32x32x16_bf16 v[16:31], v[148:151], v[140:143], v[16:31]
	s_waitcnt vmcnt(8)
	ds_write_b128 v105, v[136:139] offset:50688
	v_mfma_f32_32x32x16_bf16 v[0:15], v[148:151], v[144:147], v[0:15]
	s_setprio 0
	s_waitcnt lgkmcnt(0)
	s_barrier
	s_cbranch_scc1 .LBB0_2186
	s_setprio 1
	ds_read_b128 v[98:101], v103
	ds_read_b128 v[108:111], v104 offset:36864
	ds_read_b128 v[112:115], v104 offset:41472
	ds_read_b128 v[192:195], v103 offset:4608
	s_waitcnt lgkmcnt(2)
	v_mfma_f32_32x32x16_bf16 v[48:63], v[98:101], v[108:111], v[48:63]
	ds_read_b128 v[196:199], v103 offset:32
	ds_read_b128 v[200:203], v104 offset:36896
	s_waitcnt vmcnt(7)
	ds_write_b128 v105, v[68:71] offset:18432
	s_waitcnt lgkmcnt(4)
	v_mfma_f32_32x32x16_bf16 v[32:47], v[98:101], v[112:115], v[32:47]
	ds_read_b128 v[204:207], v104 offset:41504
	s_waitcnt lgkmcnt(4)
	v_mfma_f32_32x32x16_bf16 v[16:31], v[192:195], v[108:111], v[16:31]
	ds_read_b128 v[208:211], v103 offset:4640
	s_waitcnt vmcnt(6)
	ds_write_b128 v105, v[84:87] offset:23040
	v_mfma_f32_32x32x16_bf16 v[0:15], v[192:195], v[112:115], v[0:15]
	s_waitcnt lgkmcnt(4)
	v_mfma_f32_32x32x16_bf16 v[48:63], v[196:199], v[200:203], v[48:63]
	ds_read_b128 v[212:215], v103 offset:64
	ds_read_b128 v[216:219], v104 offset:36928
	s_waitcnt vmcnt(5)
	ds_write_b128 v105, v[88:91] offset:27648
	s_waitcnt lgkmcnt(5)
	v_mfma_f32_32x32x16_bf16 v[32:47], v[196:199], v[204:207], v[32:47]
	ds_read_b128 v[220:223], v104 offset:41536
	s_waitcnt lgkmcnt(5)
	v_mfma_f32_32x32x16_bf16 v[16:31], v[208:211], v[200:203], v[16:31]
	ds_read_b128 v[224:227], v103 offset:4672
	s_waitcnt vmcnt(4)
	ds_write_b128 v105, v[92:95] offset:32256
	v_mfma_f32_32x32x16_bf16 v[0:15], v[208:211], v[204:207], v[0:15]
	s_waitcnt lgkmcnt(4)
	v_mfma_f32_32x32x16_bf16 v[48:63], v[212:215], v[216:219], v[48:63]
	ds_read_b128 v[228:231], v103 offset:96
	ds_read_b128 v[98:101], v104 offset:36960
	s_waitcnt vmcnt(3)
	ds_write_b128 v105, v[64:67] offset:55296
	s_waitcnt lgkmcnt(5)
	v_mfma_f32_32x32x16_bf16 v[32:47], v[212:215], v[220:223], v[32:47]
	ds_read_b128 v[108:111], v104 offset:41568
	s_waitcnt lgkmcnt(5)
	v_mfma_f32_32x32x16_bf16 v[16:31], v[224:227], v[216:219], v[16:31]
	ds_read_b128 v[112:115], v103 offset:4704
	s_waitcnt vmcnt(2)
	ds_write_b128 v105, v[72:75] offset:59904
	v_mfma_f32_32x32x16_bf16 v[0:15], v[224:227], v[220:223], v[0:15]
	s_waitcnt lgkmcnt(4)
	v_mfma_f32_32x32x16_bf16 v[48:63], v[228:231], v[98:101], v[48:63]
	s_waitcnt vmcnt(1)
	ds_write_b128 v105, v[76:79] offset:64512
	s_waitcnt lgkmcnt(3)
	v_mfma_f32_32x32x16_bf16 v[32:47], v[228:231], v[108:111], v[32:47]
	s_waitcnt lgkmcnt(2)
	v_mfma_f32_32x32x16_bf16 v[16:31], v[112:115], v[98:101], v[16:31]
	s_waitcnt vmcnt(0)
	ds_write_b128 v106, v[80:83] offset:13824
	v_mfma_f32_32x32x16_bf16 v[0:15], v[112:115], v[108:111], v[0:15]
	s_setprio 0
	s_waitcnt lgkmcnt(0)
	s_barrier
	s_setprio 1
	ds_read_b128 v[64:67], v103 offset:18432
	ds_read_b128 v[68:71], v104 offset:55296
	ds_read_b128 v[72:75], v104 offset:59904
	ds_read_b128 v[192:195], v103 offset:23040
	s_waitcnt lgkmcnt(2)
	v_mfma_f32_32x32x16_bf16 v[48:63], v[64:67], v[68:71], v[48:63]
	ds_read_b128 v[196:199], v103 offset:18464
	ds_read_b128 v[200:203], v104 offset:55328
	s_waitcnt lgkmcnt(3)
	v_mfma_f32_32x32x16_bf16 v[32:47], v[64:67], v[72:75], v[32:47]
	ds_read_b128 v[204:207], v104 offset:59936
	s_waitcnt lgkmcnt(3)
	v_mfma_f32_32x32x16_bf16 v[16:31], v[192:195], v[68:71], v[16:31]
	ds_read_b128 v[208:211], v103 offset:23072
	v_mfma_f32_32x32x16_bf16 v[0:15], v[192:195], v[72:75], v[0:15]
	s_waitcnt lgkmcnt(2)
	v_mfma_f32_32x32x16_bf16 v[48:63], v[196:199], v[200:203], v[48:63]
	ds_read_b128 v[212:215], v103 offset:18496
	ds_read_b128 v[216:219], v104 offset:55360
	s_waitcnt lgkmcnt(3)
	v_mfma_f32_32x32x16_bf16 v[32:47], v[196:199], v[204:207], v[32:47]
	ds_read_b128 v[220:223], v104 offset:59968
	s_waitcnt lgkmcnt(3)
	v_mfma_f32_32x32x16_bf16 v[16:31], v[208:211], v[200:203], v[16:31]
	ds_read_b128 v[224:227], v103 offset:23104
	v_mfma_f32_32x32x16_bf16 v[0:15], v[208:211], v[204:207], v[0:15]
	s_waitcnt lgkmcnt(2)
	v_mfma_f32_32x32x16_bf16 v[48:63], v[212:215], v[216:219], v[48:63]
	ds_read_b128 v[228:231], v103 offset:18528
	ds_read_b128 v[64:67], v104 offset:55392
	s_waitcnt lgkmcnt(3)
	v_mfma_f32_32x32x16_bf16 v[32:47], v[212:215], v[220:223], v[32:47]
	ds_read_b128 v[68:71], v104 offset:60000
	s_waitcnt lgkmcnt(3)
	v_mfma_f32_32x32x16_bf16 v[16:31], v[224:227], v[216:219], v[16:31]
	ds_read_b128 v[72:75], v103 offset:23136
	v_mfma_f32_32x32x16_bf16 v[0:15], v[224:227], v[220:223], v[0:15]
	s_waitcnt lgkmcnt(2)
	v_mfma_f32_32x32x16_bf16 v[48:63], v[228:231], v[64:67], v[48:63]
	s_waitcnt lgkmcnt(1)
	v_mfma_f32_32x32x16_bf16 v[32:47], v[228:231], v[68:71], v[32:47]
	s_waitcnt lgkmcnt(0)
	v_mfma_f32_32x32x16_bf16 v[16:31], v[72:75], v[64:67], v[16:31]
	v_mfma_f32_32x32x16_bf16 v[0:15], v[72:75], v[68:71], v[0:15]
	s_setprio 0
	s_cmpk_gt_u32 s22, 0xfff
	s_cselect_b64 s[10:11], -1, 0
	s_cmpk_lt_u32 s22, 0x1000
	s_cselect_b64 s[40:41], -1, 0
	s_ashr_i32 s61, s2, 2
	s_cmp_lt_i32 s61, 7
	s_barrier
	s_cbranch_scc1 .LBB0_2189
	s_cmp_lg_u32 s61, 7
	s_cselect_b64 s[4:5], -1, 0
	s_cbranch_execz .LBB0_2190
	s_branch .LBB0_2191

.LBB0_3734:
	s_setprio 1
	ds_read_b128 v[148:151], v112
	ds_read_b128 v[152:155], v113 offset:36864
	ds_read_b128 v[156:159], v113 offset:41472
	ds_read_b128 v[192:195], v112 offset:4608
	s_waitcnt lgkmcnt(2)
	v_mfma_f32_32x32x16_bf16 v[48:63], v[148:151], v[152:155], v[48:63]
	ds_read_b128 v[196:199], v112 offset:32
	ds_read_b128 v[200:203], v113 offset:36896
	global_load_dwordx4 v[116:119], v176, s[98:99] offset:256
	global_load_dwordx4 v[120:123], v180, s[98:99] offset:256
	s_waitcnt vmcnt(9)
	ds_write_b128 v114, v[64:67] offset:18432
	s_waitcnt lgkmcnt(4)
	v_mfma_f32_32x32x16_bf16 v[32:47], v[148:151], v[156:159], v[32:47]
	ds_read_b128 v[204:207], v113 offset:41504
	global_load_dwordx4 v[124:127], v182, s[98:99] offset:256
	global_load_dwordx4 v[128:131], v184, s[98:99] offset:256
	s_waitcnt lgkmcnt(4)
	v_mfma_f32_32x32x16_bf16 v[16:31], v[192:195], v[152:155], v[16:31]
	ds_read_b128 v[208:211], v112 offset:4640
	global_load_dwordx4 v[132:135], v178, s[98:99]
	global_load_dwordx4 v[136:139], v98, s[98:99]
	s_waitcnt vmcnt(12)
	ds_write_b128 v114, v[68:71] offset:23040
	v_mfma_f32_32x32x16_bf16 v[0:15], v[192:195], v[156:159], v[0:15]
	global_load_dwordx4 v[140:143], v186, s[98:99]
	global_load_dwordx4 v[144:147], v188, s[98:99] offset:-128
	s_waitcnt lgkmcnt(4)
	v_mfma_f32_32x32x16_bf16 v[48:63], v[196:199], v[200:203], v[48:63]
	ds_read_b128 v[212:215], v112 offset:64
	ds_read_b128 v[216:219], v113 offset:36928
	s_waitcnt vmcnt(13)
	ds_write_b128 v114, v[72:75] offset:27648
	s_waitcnt lgkmcnt(5)
	v_mfma_f32_32x32x16_bf16 v[32:47], v[196:199], v[204:207], v[32:47]
	ds_read_b128 v[220:223], v113 offset:41536
	s_waitcnt lgkmcnt(5)
	v_mfma_f32_32x32x16_bf16 v[16:31], v[208:211], v[200:203], v[16:31]
	ds_read_b128 v[224:227], v112 offset:4672
	s_waitcnt vmcnt(12)
	ds_write_b128 v114, v[76:79] offset:32256
	v_mfma_f32_32x32x16_bf16 v[0:15], v[208:211], v[204:207], v[0:15]
	s_waitcnt lgkmcnt(4)
	v_mfma_f32_32x32x16_bf16 v[48:63], v[212:215], v[216:219], v[48:63]
	ds_read_b128 v[228:231], v112 offset:96
	ds_read_b128 v[148:151], v113 offset:36960
	s_waitcnt vmcnt(11)
	ds_write_b128 v114, v[80:83] offset:55296
	s_waitcnt lgkmcnt(5)
	v_mfma_f32_32x32x16_bf16 v[32:47], v[212:215], v[220:223], v[32:47]
	ds_read_b128 v[152:155], v113 offset:41568
	s_waitcnt lgkmcnt(5)
	v_mfma_f32_32x32x16_bf16 v[16:31], v[224:227], v[216:219], v[16:31]
	ds_read_b128 v[156:159], v112 offset:4704
	s_waitcnt vmcnt(10)
	ds_write_b128 v114, v[84:87] offset:59904
	v_mfma_f32_32x32x16_bf16 v[0:15], v[224:227], v[220:223], v[0:15]
	s_waitcnt lgkmcnt(4)
	v_mfma_f32_32x32x16_bf16 v[48:63], v[228:231], v[148:151], v[48:63]
	s_waitcnt vmcnt(9)
	ds_write_b128 v114, v[88:91] offset:64512
	s_waitcnt lgkmcnt(3)
	v_mfma_f32_32x32x16_bf16 v[32:47], v[228:231], v[152:155], v[32:47]
	s_waitcnt lgkmcnt(2)
	v_mfma_f32_32x32x16_bf16 v[16:31], v[156:159], v[148:151], v[16:31]
	s_waitcnt vmcnt(8)
	ds_write_b128 v115, v[92:95] offset:13824
	v_mfma_f32_32x32x16_bf16 v[0:15], v[156:159], v[152:155], v[0:15]
	s_setprio 0
	s_waitcnt lgkmcnt(0)
	s_barrier
	s_setprio 1
	ds_read_b128 v[148:151], v112 offset:18432
	ds_read_b128 v[152:155], v113 offset:55296
	ds_read_b128 v[156:159], v113 offset:59904
	ds_read_b128 v[192:195], v112 offset:23040
	s_waitcnt lgkmcnt(2)
	v_mfma_f32_32x32x16_bf16 v[48:63], v[148:151], v[152:155], v[48:63]
	ds_read_b128 v[196:199], v112 offset:18464
	ds_read_b128 v[200:203], v113 offset:55328
	global_load_dwordx4 v[64:67], v176, s[98:99] offset:384
	global_load_dwordx4 v[68:71], v180, s[98:99] offset:384
	s_waitcnt vmcnt(9)
	ds_write_b128 v114, v[116:119]
	s_waitcnt lgkmcnt(4)
	v_mfma_f32_32x32x16_bf16 v[32:47], v[148:151], v[156:159], v[32:47]
	ds_read_b128 v[204:207], v113 offset:59936
	global_load_dwordx4 v[72:75], v182, s[98:99] offset:384
	global_load_dwordx4 v[76:79], v184, s[98:99] offset:384
	s_waitcnt lgkmcnt(4)
	v_mfma_f32_32x32x16_bf16 v[16:31], v[192:195], v[152:155], v[16:31]
	ds_read_b128 v[208:211], v112 offset:23072
	global_load_dwordx4 v[80:83], v178, s[98:99] offset:128
	global_load_dwordx4 v[84:87], v99, s[98:99]
	s_waitcnt vmcnt(12)
	ds_write_b128 v114, v[120:123] offset:4608
	v_mfma_f32_32x32x16_bf16 v[0:15], v[192:195], v[156:159], v[0:15]
	global_load_dwordx4 v[88:91], v186, s[98:99] offset:128
	global_load_dwordx4 v[92:95], v188, s[98:99]
	s_waitcnt lgkmcnt(4)
	v_mfma_f32_32x32x16_bf16 v[48:63], v[196:199], v[200:203], v[48:63]
	ds_read_b128 v[212:215], v112 offset:18496
	ds_read_b128 v[216:219], v113 offset:55360
	s_add_u32 s98, s98, 0x100
	s_addc_u32 s99, s99, 0
	s_add_i32 s0, s0, 2
	s_cmp_lt_u32 s0, 3
	s_waitcnt vmcnt(13)
	ds_write_b128 v114, v[124:127] offset:9216
	s_waitcnt lgkmcnt(5)
	v_mfma_f32_32x32x16_bf16 v[32:47], v[196:199], v[204:207], v[32:47]
	ds_read_b128 v[220:223], v113 offset:59968
	s_waitcnt lgkmcnt(5)
	v_mfma_f32_32x32x16_bf16 v[16:31], v[208:211], v[200:203], v[16:31]
	ds_read_b128 v[224:227], v112 offset:23104
	s_waitcnt vmcnt(12)
	ds_write_b128 v114, v[128:131] offset:13824
	v_mfma_f32_32x32x16_bf16 v[0:15], v[208:211], v[204:207], v[0:15]
	s_waitcnt lgkmcnt(4)
	v_mfma_f32_32x32x16_bf16 v[48:63], v[212:215], v[216:219], v[48:63]
	ds_read_b128 v[228:231], v112 offset:18528
	ds_read_b128 v[148:151], v113 offset:55392
	s_waitcnt vmcnt(11)
	ds_write_b128 v114, v[132:135] offset:36864
	s_waitcnt lgkmcnt(5)
	v_mfma_f32_32x32x16_bf16 v[32:47], v[212:215], v[220:223], v[32:47]
	ds_read_b128 v[152:155], v113 offset:60000
	s_waitcnt lgkmcnt(5)
	v_mfma_f32_32x32x16_bf16 v[16:31], v[224:227], v[216:219], v[16:31]
	ds_read_b128 v[156:159], v112 offset:23136
	s_waitcnt vmcnt(10)
	ds_write_b128 v114, v[136:139] offset:41472
	v_mfma_f32_32x32x16_bf16 v[0:15], v[224:227], v[220:223], v[0:15]
	s_waitcnt lgkmcnt(4)
	v_mfma_f32_32x32x16_bf16 v[48:63], v[228:231], v[148:151], v[48:63]
	s_waitcnt vmcnt(9)
	ds_write_b128 v114, v[140:143] offset:46080
	s_waitcnt lgkmcnt(3)
	v_mfma_f32_32x32x16_bf16 v[32:47], v[228:231], v[152:155], v[32:47]
	s_waitcnt lgkmcnt(2)
	v_mfma_f32_32x32x16_bf16 v[16:31], v[156:159], v[148:151], v[16:31]
	s_waitcnt vmcnt(8)
	ds_write_b128 v114, v[144:147] offset:50688
	v_mfma_f32_32x32x16_bf16 v[0:15], v[156:159], v[152:155], v[0:15]
	s_setprio 0
	s_waitcnt lgkmcnt(0)
	s_barrier
	s_cbranch_scc1 .LBB0_3734
	s_setprio 1
	ds_read_b128 v[98:101], v112
	ds_read_b128 v[102:105], v113 offset:36864
	ds_read_b128 v[106:109], v113 offset:41472
	ds_read_b128 v[192:195], v112 offset:4608
	s_waitcnt lgkmcnt(2)
	v_mfma_f32_32x32x16_bf16 v[48:63], v[98:101], v[102:105], v[48:63]
	ds_read_b128 v[196:199], v112 offset:32
	ds_read_b128 v[200:203], v113 offset:36896
	s_waitcnt vmcnt(7)
	ds_write_b128 v114, v[64:67] offset:18432
	s_waitcnt lgkmcnt(4)
	v_mfma_f32_32x32x16_bf16 v[32:47], v[98:101], v[106:109], v[32:47]
	ds_read_b128 v[204:207], v113 offset:41504
	s_waitcnt lgkmcnt(4)
	v_mfma_f32_32x32x16_bf16 v[16:31], v[192:195], v[102:105], v[16:31]
	ds_read_b128 v[208:211], v112 offset:4640
	s_waitcnt vmcnt(6)
	ds_write_b128 v114, v[68:71] offset:23040
	v_mfma_f32_32x32x16_bf16 v[0:15], v[192:195], v[106:109], v[0:15]
	s_waitcnt lgkmcnt(4)
	v_mfma_f32_32x32x16_bf16 v[48:63], v[196:199], v[200:203], v[48:63]
	ds_read_b128 v[212:215], v112 offset:64
	ds_read_b128 v[216:219], v113 offset:36928
	s_waitcnt vmcnt(5)
	ds_write_b128 v114, v[72:75] offset:27648
	s_waitcnt lgkmcnt(5)
	v_mfma_f32_32x32x16_bf16 v[32:47], v[196:199], v[204:207], v[32:47]
	ds_read_b128 v[220:223], v113 offset:41536
	s_waitcnt lgkmcnt(5)
	v_mfma_f32_32x32x16_bf16 v[16:31], v[208:211], v[200:203], v[16:31]
	ds_read_b128 v[224:227], v112 offset:4672
	s_waitcnt vmcnt(4)
	ds_write_b128 v114, v[76:79] offset:32256
	v_mfma_f32_32x32x16_bf16 v[0:15], v[208:211], v[204:207], v[0:15]
	s_waitcnt lgkmcnt(4)
	v_mfma_f32_32x32x16_bf16 v[48:63], v[212:215], v[216:219], v[48:63]
	ds_read_b128 v[228:231], v113 offset:36960
	ds_read_b128 v[98:101], v112 offset:4704
	s_waitcnt vmcnt(3)
	ds_write_b128 v114, v[80:83] offset:55296
	s_waitcnt lgkmcnt(5)
	v_mfma_f32_32x32x16_bf16 v[32:47], v[212:215], v[220:223], v[32:47]
	ds_read_b128 v[102:105], v113 offset:41568
	s_waitcnt lgkmcnt(5)
	v_mfma_f32_32x32x16_bf16 v[16:31], v[224:227], v[216:219], v[16:31]
	ds_read_b128 v[106:109], v112 offset:96
	s_waitcnt vmcnt(2)
	ds_write_b128 v114, v[84:87] offset:59904
	v_mfma_f32_32x32x16_bf16 v[0:15], v[224:227], v[220:223], v[0:15]
	s_waitcnt lgkmcnt(4)
	v_mfma_f32_32x32x16_bf16 v[16:31], v[98:101], v[228:231], v[16:31]
	s_waitcnt vmcnt(1)
	ds_write_b128 v114, v[88:91] offset:64512
	s_waitcnt lgkmcnt(3)
	v_mfma_f32_32x32x16_bf16 v[0:15], v[98:101], v[102:105], v[0:15]
	s_waitcnt lgkmcnt(2)
	v_mfma_f32_32x32x16_bf16 v[48:63], v[106:109], v[228:231], v[48:63]
	s_waitcnt vmcnt(0)
	ds_write_b128 v115, v[92:95] offset:13824
	v_mfma_f32_32x32x16_bf16 v[32:47], v[106:109], v[102:105], v[32:47]
	s_setprio 0
	s_waitcnt lgkmcnt(0)
	s_barrier
	s_setprio 1
	ds_read_b128 v[64:67], v112 offset:18432
	ds_read_b128 v[68:71], v113 offset:55296
	ds_read_b128 v[72:75], v113 offset:59904
	ds_read_b128 v[192:195], v112 offset:23040
	s_waitcnt lgkmcnt(2)
	v_mfma_f32_32x32x16_bf16 v[48:63], v[64:67], v[68:71], v[48:63]
	ds_read_b128 v[196:199], v112 offset:18464
	ds_read_b128 v[200:203], v113 offset:55328
	s_waitcnt lgkmcnt(3)
	v_mfma_f32_32x32x16_bf16 v[32:47], v[64:67], v[72:75], v[32:47]
	ds_read_b128 v[204:207], v113 offset:59936
	s_waitcnt lgkmcnt(3)
	v_mfma_f32_32x32x16_bf16 v[16:31], v[192:195], v[68:71], v[16:31]
	ds_read_b128 v[208:211], v112 offset:23072
	v_mfma_f32_32x32x16_bf16 v[0:15], v[192:195], v[72:75], v[0:15]
	s_waitcnt lgkmcnt(2)
	v_mfma_f32_32x32x16_bf16 v[48:63], v[196:199], v[200:203], v[48:63]
	ds_read_b128 v[212:215], v112 offset:18496
	ds_read_b128 v[216:219], v113 offset:55360
	s_waitcnt lgkmcnt(3)
	v_mfma_f32_32x32x16_bf16 v[32:47], v[196:199], v[204:207], v[32:47]
	ds_read_b128 v[220:223], v113 offset:59968
	s_waitcnt lgkmcnt(3)
	v_mfma_f32_32x32x16_bf16 v[16:31], v[208:211], v[200:203], v[16:31]
	ds_read_b128 v[224:227], v112 offset:23104
	v_mfma_f32_32x32x16_bf16 v[0:15], v[208:211], v[204:207], v[0:15]
	s_waitcnt lgkmcnt(2)
	v_mfma_f32_32x32x16_bf16 v[48:63], v[212:215], v[216:219], v[48:63]
	ds_read_b128 v[228:231], v113 offset:55392
	ds_read_b128 v[64:67], v112 offset:23136
	s_waitcnt lgkmcnt(3)
	v_mfma_f32_32x32x16_bf16 v[32:47], v[212:215], v[220:223], v[32:47]
	ds_read_b128 v[68:71], v113 offset:60000
	s_waitcnt lgkmcnt(3)
	v_mfma_f32_32x32x16_bf16 v[16:31], v[224:227], v[216:219], v[16:31]
	ds_read_b128 v[72:75], v112 offset:18528
	v_mfma_f32_32x32x16_bf16 v[0:15], v[224:227], v[220:223], v[0:15]
	s_waitcnt lgkmcnt(2)
	v_mfma_f32_32x32x16_bf16 v[16:31], v[64:67], v[228:231], v[16:31]
	s_waitcnt lgkmcnt(1)
	v_mfma_f32_32x32x16_bf16 v[0:15], v[64:67], v[68:71], v[0:15]
	s_waitcnt lgkmcnt(0)
	v_mfma_f32_32x32x16_bf16 v[48:63], v[72:75], v[228:231], v[48:63]
	v_mfma_f32_32x32x16_bf16 v[32:47], v[72:75], v[68:71], v[32:47]
	s_setprio 0
	s_nop 10
	v_cvt_pk_bf16_f32 v32, v32, s0
	v_cvt_pk_bf16_f32 v0, v0, s0
	s_barrier
	ds_write_b16 v111, v32 offset:64
	v_cvt_pk_bf16_f32 v32, v49, s0
	ds_write_b16 v111, v0 offset:8768
	v_cvt_pk_bf16_f32 v0, v17, s0
	ds_write_b16 v111, v32 offset:272
	v_cvt_pk_bf16_f32 v32, v33, s0
	ds_write_b16 v111, v0 offset:8976
	v_cvt_pk_bf16_f32 v0, v1, s0
	ds_write_b16 v111, v32 offset:336
	v_cvt_pk_bf16_f32 v32, v50, s0
	ds_write_b16 v111, v0 offset:9040
	v_cvt_pk_bf16_f32 v0, v18, s0
	ds_write_b16 v111, v32 offset:544
	v_cvt_pk_bf16_f32 v32, v34, s0
	ds_write_b16 v111, v0 offset:9248
	v_cvt_pk_bf16_f32 v0, v2, s0
	ds_write_b16 v111, v32 offset:608
	v_cvt_pk_bf16_f32 v32, v51, s0
	ds_write_b16 v111, v0 offset:9312
	v_cvt_pk_bf16_f32 v0, v19, s0
	ds_write_b16 v111, v32 offset:816
	v_cvt_pk_bf16_f32 v32, v35, s0
	ds_write_b16 v111, v0 offset:9520
	v_cvt_pk_bf16_f32 v0, v3, s0
	ds_write_b16 v111, v32 offset:880
	v_cvt_pk_bf16_f32 v32, v52, s0
	ds_write_b16 v111, v0 offset:9584
	v_cvt_pk_bf16_f32 v0, v20, s0
	ds_write_b16 v111, v32 offset:2176
	v_cvt_pk_bf16_f32 v32, v36, s0
	ds_write_b16 v111, v0 offset:10880
	v_cvt_pk_bf16_f32 v0, v4, s0
	ds_write_b16 v111, v32 offset:2240
	v_cvt_pk_bf16_f32 v32, v53, s0
	ds_write_b16 v111, v0 offset:10944
	v_cvt_pk_bf16_f32 v0, v21, s0
	ds_write_b16 v111, v32 offset:2448
	v_cvt_pk_bf16_f32 v32, v37, s0
	ds_write_b16 v111, v0 offset:11152
	v_cvt_pk_bf16_f32 v0, v5, s0
	ds_write_b16 v111, v32 offset:2512
	v_cvt_pk_bf16_f32 v32, v54, s0
	ds_write_b16 v111, v0 offset:11216
	v_cvt_pk_bf16_f32 v0, v22, s0
	ds_write_b16 v111, v32 offset:2720
	v_cvt_pk_bf16_f32 v32, v38, s0
	ds_write_b16 v111, v0 offset:11424
	v_cvt_pk_bf16_f32 v0, v6, s0
	ds_write_b16 v111, v32 offset:2784
	v_cvt_pk_bf16_f32 v32, v55, s0
	ds_write_b16 v111, v0 offset:11488
	v_cvt_pk_bf16_f32 v0, v23, s0
	ds_write_b16 v111, v32 offset:2992
	v_cvt_pk_bf16_f32 v32, v39, s0
	ds_write_b16 v111, v0 offset:11696
	v_cvt_pk_bf16_f32 v0, v7, s0
	ds_write_b16 v111, v32 offset:3056
	v_cvt_pk_bf16_f32 v32, v56, s0
	ds_write_b16 v111, v0 offset:11760
	v_cvt_pk_bf16_f32 v0, v24, s0
	ds_write_b16 v111, v32 offset:4352
	v_cvt_pk_bf16_f32 v32, v40, s0
	ds_write_b16 v111, v0 offset:13056
	v_cvt_pk_bf16_f32 v0, v8, s0
	ds_write_b16 v111, v32 offset:4416
	v_cvt_pk_bf16_f32 v32, v57, s0
	ds_write_b16 v111, v0 offset:13120
	v_cvt_pk_bf16_f32 v0, v25, s0
	ds_write_b16 v111, v32 offset:4624
	v_cvt_pk_bf16_f32 v32, v41, s0
	ds_write_b16 v111, v0 offset:13328
	v_cvt_pk_bf16_f32 v0, v9, s0
	ds_write_b16 v111, v32 offset:4688
	v_cvt_pk_bf16_f32 v32, v58, s0
	ds_write_b16 v111, v0 offset:13392
	v_cvt_pk_bf16_f32 v0, v26, s0
	ds_write_b16 v111, v32 offset:4896
	v_cvt_pk_bf16_f32 v32, v42, s0
	ds_write_b16 v111, v0 offset:13600
	v_cvt_pk_bf16_f32 v0, v10, s0
	ds_write_b16 v111, v32 offset:4960
	v_cvt_pk_bf16_f32 v32, v59, s0
	ds_write_b16 v111, v0 offset:13664
	v_cvt_pk_bf16_f32 v0, v27, s0
	ds_write_b16 v111, v32 offset:5168
	v_cvt_pk_bf16_f32 v32, v43, s0
	ds_write_b16 v111, v0 offset:13872
	v_cvt_pk_bf16_f32 v0, v11, s0
	ds_write_b16 v111, v32 offset:5232
	v_cvt_pk_bf16_f32 v32, v60, s0
	ds_write_b16 v111, v0 offset:13936
	v_cvt_pk_bf16_f32 v0, v28, s0
	ds_write_b16 v111, v32 offset:6528
	v_cvt_pk_bf16_f32 v32, v44, s0
	ds_write_b16 v111, v0 offset:15232
	v_cvt_pk_bf16_f32 v0, v12, s0
	ds_write_b16 v111, v32 offset:6592
	v_cvt_pk_bf16_f32 v32, v61, s0
	ds_write_b16 v111, v0 offset:15296
	v_cvt_pk_bf16_f32 v0, v29, s0
	ds_write_b16 v111, v32 offset:6800
	v_cvt_pk_bf16_f32 v32, v45, s0
	ds_write_b16 v111, v0 offset:15504
	v_cvt_pk_bf16_f32 v0, v13, s0
	ds_write_b16 v111, v32 offset:6864
	v_cvt_pk_bf16_f32 v32, v62, s0
	ds_write_b16 v111, v0 offset:15568
	v_cvt_pk_bf16_f32 v0, v30, s0
	ds_write_b16 v111, v32 offset:7072
	v_cvt_pk_bf16_f32 v32, v46, s0
	ds_write_b16 v111, v0 offset:15776
	v_cvt_pk_bf16_f32 v0, v14, s0
	ds_write_b16 v111, v32 offset:7136
	v_cvt_pk_bf16_f32 v32, v63, s0
	ds_write_b16 v111, v0 offset:15840
	v_cvt_pk_bf16_f32 v0, v31, s0
	v_cvt_pk_bf16_f32 v48, v48, s0
	ds_write_b16 v111, v32 offset:7344
	v_cvt_pk_bf16_f32 v32, v47, s0
	v_cvt_pk_bf16_f32 v16, v16, s0
	ds_write_b16 v111, v0 offset:16048
	v_cvt_pk_bf16_f32 v0, v15, s0
	v_mov_b32_e32 v15, v110
	ds_write_b16 v111, v48
	ds_write_b16 v111, v32 offset:7408
	ds_write_b16 v111, v16 offset:8704
	ds_write_b16 v111, v0 offset:16112
	s_waitcnt lgkmcnt(0)
	s_barrier
	v_mov_b64_e32 v[2:3], s[4:5]
	v_lshlrev_b32_e32 v0, 3, v15
	v_and_b32_e32 v0, 0x78, v0
	v_ashrrev_i32_e32 v1, 4, v15
	v_lshlrev_b32_e32 v96, 1, v0
	v_add_u32_e32 v0, s63, v1
	s_lshl_b32 s16, s26, 10
	v_mad_i64_i32 v[2:3], s[0:1], v0, s60, v[2:3]
	v_lshl_add_u64 v[2:3], s[16:17], 1, v[2:3]
	v_lshl_add_u64 v[2:3], s[22:23], 1, v[2:3]
	v_lshl_add_u64 v[2:3], v[2:3], 0, v[96:97]
	global_load_dwordx4 v[6:9], v[2:3], off
	v_add_co_u32_e32 v80, vcc, 0x18000, v2
	s_nop 1
	v_addc_co_u32_e32 v81, vcc, 0, v3, vcc
	global_load_dwordx4 v[24:27], v[80:81], off
	v_add_co_u32_e32 v80, vcc, 0x30000, v2
	s_nop 1
	v_addc_co_u32_e32 v81, vcc, 0, v3, vcc
	global_load_dwordx4 v[28:31], v[80:81], off
	v_add_co_u32_e32 v80, vcc, 0x48000, v2
	s_nop 1
	v_addc_co_u32_e32 v81, vcc, 0, v3, vcc
	global_load_dwordx4 v[32:35], v[80:81], off
	v_add_co_u32_e32 v80, vcc, 0x60000, v2
	s_nop 1
	v_addc_co_u32_e32 v81, vcc, 0, v3, vcc
	global_load_dwordx4 v[36:39], v[80:81], off
	v_add_co_u32_e32 v80, vcc, 0x78000, v2
	s_nop 1
	v_addc_co_u32_e32 v81, vcc, 0, v3, vcc
	global_load_dwordx4 v[40:43], v[80:81], off
	v_add_co_u32_e32 v80, vcc, 0x90000, v2
	s_nop 1
	v_addc_co_u32_e32 v81, vcc, 0, v3, vcc
	global_load_dwordx4 v[44:47], v[80:81], off
	v_add_co_u32_e32 v80, vcc, 0xa8000, v2
	s_nop 1
	v_addc_co_u32_e32 v81, vcc, 0, v3, vcc
	global_load_dwordx4 v[48:51], v[80:81], off
	v_add_u32_e32 v14, 32, v96
	v_mad_u64_u32 v[2:3], s[0:1], v1, s54, v[14:15]
	ds_read_b128 v[2:5], v2
	v_ashrrev_i32_e32 v1, 31, v0
	v_lshlrev_b64 v[0:1], 11, v[0:1]
	v_lshl_add_u64 v[0:1], s[24:25], 0, v[0:1]
	v_lshl_add_u64 v[16:17], v[0:1], 0, v[96:97]
	v_cndmask_b32_e64 v1, 0, 1, s[44:45]
	v_mov_b32_e32 v0, 0
	v_cmp_ne_u32_e64 s[0:1], 1, v1
	s_andn2_b64 vcc, exec, s[44:45]
	v_mov_b32_e32 v10, 0
	v_mov_b32_e32 v11, 0
	v_mov_b32_e32 v12, 0
	v_mov_b32_e32 v13, 0
	s_cbranch_vccnz .LBB0_3737
	global_load_dwordx4 v[10:13], v[16:17], off
	v_add_co_u32_e32 v80, vcc, 0x8000, v16
	s_nop 1
	v_addc_co_u32_e32 v81, vcc, 0, v17, vcc
	global_load_dwordx4 v[52:55], v[80:81], off
	v_add_co_u32_e32 v80, vcc, 0x10000, v16
	s_nop 1
	v_addc_co_u32_e32 v81, vcc, 0, v17, vcc
	global_load_dwordx4 v[56:59], v[80:81], off
	v_add_co_u32_e32 v80, vcc, 0x18000, v16
	s_nop 1
	v_addc_co_u32_e32 v81, vcc, 0, v17, vcc
	global_load_dwordx4 v[60:63], v[80:81], off
	v_add_co_u32_e32 v80, vcc, 0x20000, v16
	s_nop 1
	v_addc_co_u32_e32 v81, vcc, 0, v17, vcc
	global_load_dwordx4 v[64:67], v[80:81], off
	v_add_co_u32_e32 v80, vcc, 0x28000, v16
	s_nop 1
	v_addc_co_u32_e32 v81, vcc, 0, v17, vcc
	global_load_dwordx4 v[68:71], v[80:81], off
	v_add_co_u32_e32 v80, vcc, 0x30000, v16
	s_nop 1
	v_addc_co_u32_e32 v81, vcc, 0, v17, vcc
	global_load_dwordx4 v[72:75], v[80:81], off
	v_add_co_u32_e32 v80, vcc, 0x38000, v16
	s_nop 1
	v_addc_co_u32_e32 v81, vcc, 0, v17, vcc
	global_load_dwordx4 v[76:79], v[80:81], off

.LBB0_3806:
	s_setprio 1
	ds_read_b128 v[140:143], v103
	ds_read_b128 v[144:147], v104 offset:36864
	ds_read_b128 v[148:151], v104 offset:41472
	ds_read_b128 v[192:195], v103 offset:4608
	s_waitcnt lgkmcnt(2)
	v_mfma_f32_32x32x16_bf16 v[48:63], v[140:143], v[144:147], v[48:63]
	ds_read_b128 v[196:199], v103 offset:32
	ds_read_b128 v[200:203], v104 offset:36896
	global_load_dwordx4 v[108:111], v168, s[98:99] offset:3840
	global_load_dwordx4 v[112:115], v170, s[98:99] offset:3840
	s_waitcnt vmcnt(9)
	ds_write_b128 v105, v[68:71] offset:18432
	s_waitcnt lgkmcnt(4)
	v_mfma_f32_32x32x16_bf16 v[32:47], v[140:143], v[148:151], v[32:47]
	ds_read_b128 v[204:207], v104 offset:41504
	global_load_dwordx4 v[116:119], v172, s[98:99] offset:3840
	global_load_dwordx4 v[120:123], v174, s[98:99] offset:3840
	s_waitcnt lgkmcnt(4)
	v_mfma_f32_32x32x16_bf16 v[16:31], v[192:195], v[144:147], v[16:31]
	ds_read_b128 v[208:211], v103 offset:4640
	global_load_dwordx4 v[124:127], v176, s[98:99] offset:3840
	global_load_dwordx4 v[128:131], v178, s[98:99] offset:3840
	s_waitcnt vmcnt(11)
	ds_write_b128 v105, v[84:87] offset:23040
	v_mfma_f32_32x32x16_bf16 v[0:15], v[192:195], v[148:151], v[0:15]
	global_load_dwordx4 v[132:135], v180, s[98:99] offset:3840
	global_load_dwordx4 v[136:139], v182, s[98:99] offset:3840
	s_waitcnt lgkmcnt(4)
	v_mfma_f32_32x32x16_bf16 v[48:63], v[196:199], v[200:203], v[48:63]
	ds_read_b128 v[212:215], v103 offset:64
	ds_read_b128 v[216:219], v104 offset:36928
	s_waitcnt vmcnt(12)
	ds_write_b128 v105, v[88:91] offset:27648
	s_waitcnt lgkmcnt(5)
	v_mfma_f32_32x32x16_bf16 v[32:47], v[196:199], v[204:207], v[32:47]
	ds_read_b128 v[220:223], v104 offset:41536
	s_waitcnt lgkmcnt(5)
	v_mfma_f32_32x32x16_bf16 v[16:31], v[208:211], v[200:203], v[16:31]
	ds_read_b128 v[224:227], v103 offset:4672
	s_waitcnt vmcnt(11)
	ds_write_b128 v105, v[92:95] offset:32256
	v_mfma_f32_32x32x16_bf16 v[0:15], v[208:211], v[204:207], v[0:15]
	s_waitcnt lgkmcnt(4)
	v_mfma_f32_32x32x16_bf16 v[48:63], v[212:215], v[216:219], v[48:63]
	ds_read_b128 v[228:231], v103 offset:96
	ds_read_b128 v[140:143], v104 offset:36960
	ds_write_b128 v105, v[64:67] offset:55296
	s_waitcnt lgkmcnt(5)
	v_mfma_f32_32x32x16_bf16 v[32:47], v[212:215], v[220:223], v[32:47]
	ds_read_b128 v[144:147], v104 offset:41568
	s_waitcnt lgkmcnt(5)
	v_mfma_f32_32x32x16_bf16 v[16:31], v[224:227], v[216:219], v[16:31]
	ds_read_b128 v[148:151], v103 offset:4704
	s_waitcnt vmcnt(10)
	ds_write_b128 v105, v[72:75] offset:59904
	v_mfma_f32_32x32x16_bf16 v[0:15], v[224:227], v[220:223], v[0:15]
	s_waitcnt lgkmcnt(4)
	v_mfma_f32_32x32x16_bf16 v[48:63], v[228:231], v[140:143], v[48:63]
	s_waitcnt vmcnt(9)
	ds_write_b128 v105, v[76:79] offset:64512
	s_waitcnt lgkmcnt(3)
	v_mfma_f32_32x32x16_bf16 v[32:47], v[228:231], v[144:147], v[32:47]
	s_waitcnt lgkmcnt(2)
	v_mfma_f32_32x32x16_bf16 v[16:31], v[148:151], v[140:143], v[16:31]
	s_waitcnt vmcnt(8)
	ds_write_b128 v106, v[80:83] offset:13824
	v_mfma_f32_32x32x16_bf16 v[0:15], v[148:151], v[144:147], v[0:15]
	s_setprio 0
	s_waitcnt lgkmcnt(0)
	s_barrier
	s_setprio 1
	ds_read_b128 v[140:143], v103 offset:18432
	ds_read_b128 v[144:147], v104 offset:55296
	ds_read_b128 v[148:151], v104 offset:59904
	ds_read_b128 v[192:195], v103 offset:23040
	s_waitcnt lgkmcnt(2)
	v_mfma_f32_32x32x16_bf16 v[48:63], v[140:143], v[144:147], v[48:63]
	ds_read_b128 v[196:199], v103 offset:18464
	ds_read_b128 v[200:203], v104 offset:55328
	global_load_dwordx4 v[68:71], v168, s[98:99] offset:3968
	global_load_dwordx4 v[84:87], v170, s[98:99] offset:3968
	s_waitcnt vmcnt(9)
	ds_write_b128 v105, v[108:111]
	s_waitcnt lgkmcnt(4)
	v_mfma_f32_32x32x16_bf16 v[32:47], v[140:143], v[148:151], v[32:47]
	ds_read_b128 v[204:207], v104 offset:59936
	global_load_dwordx4 v[88:91], v172, s[98:99] offset:3968
	global_load_dwordx4 v[92:95], v174, s[98:99] offset:3968
	s_waitcnt lgkmcnt(4)
	v_mfma_f32_32x32x16_bf16 v[16:31], v[192:195], v[144:147], v[16:31]
	ds_read_b128 v[208:211], v103 offset:23072
	global_load_dwordx4 v[64:67], v176, s[98:99] offset:3968
	global_load_dwordx4 v[72:75], v178, s[98:99] offset:3968
	s_waitcnt vmcnt(12)
	ds_write_b128 v105, v[112:115] offset:4608
	v_mfma_f32_32x32x16_bf16 v[0:15], v[192:195], v[148:151], v[0:15]
	global_load_dwordx4 v[76:79], v180, s[98:99] offset:3968
	global_load_dwordx4 v[80:83], v182, s[98:99] offset:3968
	s_waitcnt lgkmcnt(4)
	v_mfma_f32_32x32x16_bf16 v[48:63], v[196:199], v[200:203], v[48:63]
	ds_read_b128 v[212:215], v103 offset:18496
	ds_read_b128 v[216:219], v104 offset:55360
	s_add_u32 s98, s98, 0x100
	s_addc_u32 s99, s99, 0
	s_add_i32 s10, s10, 2
	s_cmp_lt_u32 s10, 11
	s_waitcnt vmcnt(13)
	ds_write_b128 v105, v[116:119] offset:9216
	s_waitcnt lgkmcnt(5)
	v_mfma_f32_32x32x16_bf16 v[32:47], v[196:199], v[204:207], v[32:47]
	ds_read_b128 v[220:223], v104 offset:59968
	s_waitcnt lgkmcnt(5)
	v_mfma_f32_32x32x16_bf16 v[16:31], v[208:211], v[200:203], v[16:31]
	ds_read_b128 v[224:227], v103 offset:23104
	s_waitcnt vmcnt(12)
	ds_write_b128 v105, v[120:123] offset:13824
	v_mfma_f32_32x32x16_bf16 v[0:15], v[208:211], v[204:207], v[0:15]
	s_waitcnt lgkmcnt(4)
	v_mfma_f32_32x32x16_bf16 v[48:63], v[212:215], v[216:219], v[48:63]
	ds_read_b128 v[228:231], v103 offset:18528
	ds_read_b128 v[140:143], v104 offset:55392
	s_waitcnt vmcnt(11)
	ds_write_b128 v105, v[124:127] offset:36864
	s_waitcnt lgkmcnt(5)
	v_mfma_f32_32x32x16_bf16 v[32:47], v[212:215], v[220:223], v[32:47]
	ds_read_b128 v[144:147], v104 offset:60000
	s_waitcnt lgkmcnt(5)
	v_mfma_f32_32x32x16_bf16 v[16:31], v[224:227], v[216:219], v[16:31]
	ds_read_b128 v[148:151], v103 offset:23136
	s_waitcnt vmcnt(10)
	ds_write_b128 v105, v[128:131] offset:41472
	v_mfma_f32_32x32x16_bf16 v[0:15], v[224:227], v[220:223], v[0:15]
	s_waitcnt lgkmcnt(4)
	v_mfma_f32_32x32x16_bf16 v[48:63], v[228:231], v[140:143], v[48:63]
	s_waitcnt vmcnt(9)
	ds_write_b128 v105, v[132:135] offset:46080
	s_waitcnt lgkmcnt(3)
	v_mfma_f32_32x32x16_bf16 v[32:47], v[228:231], v[144:147], v[32:47]
	s_waitcnt lgkmcnt(2)
	v_mfma_f32_32x32x16_bf16 v[16:31], v[148:151], v[140:143], v[16:31]
	s_waitcnt vmcnt(8)
	ds_write_b128 v105, v[136:139] offset:50688
	v_mfma_f32_32x32x16_bf16 v[0:15], v[148:151], v[144:147], v[0:15]
	s_setprio 0
	s_waitcnt lgkmcnt(0)
	s_barrier
	s_cbranch_scc1 .LBB0_3806
	s_setprio 1
	ds_read_b128 v[98:101], v103
	ds_read_b128 v[108:111], v104 offset:36864
	ds_read_b128 v[112:115], v104 offset:41472
	ds_read_b128 v[192:195], v103 offset:4608
	s_waitcnt lgkmcnt(2)
	v_mfma_f32_32x32x16_bf16 v[48:63], v[98:101], v[108:111], v[48:63]
	ds_read_b128 v[196:199], v103 offset:32
	ds_read_b128 v[200:203], v104 offset:36896
	s_waitcnt vmcnt(7)
	ds_write_b128 v105, v[68:71] offset:18432
	s_waitcnt lgkmcnt(4)
	v_mfma_f32_32x32x16_bf16 v[32:47], v[98:101], v[112:115], v[32:47]
	ds_read_b128 v[204:207], v104 offset:41504
	s_waitcnt lgkmcnt(4)
	v_mfma_f32_32x32x16_bf16 v[16:31], v[192:195], v[108:111], v[16:31]
	ds_read_b128 v[208:211], v103 offset:4640
	s_waitcnt vmcnt(6)
	ds_write_b128 v105, v[84:87] offset:23040
	v_mfma_f32_32x32x16_bf16 v[0:15], v[192:195], v[112:115], v[0:15]
	s_waitcnt lgkmcnt(4)
	v_mfma_f32_32x32x16_bf16 v[48:63], v[196:199], v[200:203], v[48:63]
	ds_read_b128 v[212:215], v103 offset:64
	ds_read_b128 v[216:219], v104 offset:36928
	s_waitcnt vmcnt(5)
	ds_write_b128 v105, v[88:91] offset:27648
	s_waitcnt lgkmcnt(5)
	v_mfma_f32_32x32x16_bf16 v[32:47], v[196:199], v[204:207], v[32:47]
	ds_read_b128 v[220:223], v104 offset:41536
	s_waitcnt lgkmcnt(5)
	v_mfma_f32_32x32x16_bf16 v[16:31], v[208:211], v[200:203], v[16:31]
	ds_read_b128 v[224:227], v103 offset:4672
	s_waitcnt vmcnt(4)
	ds_write_b128 v105, v[92:95] offset:32256
	v_mfma_f32_32x32x16_bf16 v[0:15], v[208:211], v[204:207], v[0:15]
	s_waitcnt lgkmcnt(4)
	v_mfma_f32_32x32x16_bf16 v[48:63], v[212:215], v[216:219], v[48:63]
	ds_read_b128 v[228:231], v103 offset:96
	ds_read_b128 v[98:101], v104 offset:41568
	s_waitcnt vmcnt(3)
	ds_write_b128 v105, v[64:67] offset:55296
	s_waitcnt lgkmcnt(5)
	v_mfma_f32_32x32x16_bf16 v[32:47], v[212:215], v[220:223], v[32:47]
	ds_read_b128 v[108:111], v104 offset:36960
	ds_read_b128 v[112:115], v103 offset:4704
	s_waitcnt lgkmcnt(6)
	v_mfma_f32_32x32x16_bf16 v[16:31], v[224:227], v[216:219], v[16:31]
	s_waitcnt vmcnt(2)
	ds_write_b128 v105, v[72:75] offset:59904
	v_mfma_f32_32x32x16_bf16 v[0:15], v[224:227], v[220:223], v[0:15]
	s_waitcnt lgkmcnt(4)
	v_mfma_f32_32x32x16_bf16 v[32:47], v[228:231], v[98:101], v[32:47]
	s_waitcnt vmcnt(1)
	ds_write_b128 v105, v[76:79] offset:64512
	s_waitcnt lgkmcnt(2)
	v_mfma_f32_32x32x16_bf16 v[16:31], v[112:115], v[108:111], v[16:31]
	v_mfma_f32_32x32x16_bf16 v[0:15], v[112:115], v[98:101], v[0:15]
	s_waitcnt vmcnt(0)
	ds_write_b128 v106, v[80:83] offset:13824
	v_mfma_f32_32x32x16_bf16 v[48:63], v[228:231], v[108:111], v[48:63]
	s_setprio 0
	s_waitcnt lgkmcnt(0)
	s_barrier
	s_setprio 1
	ds_read_b128 v[64:67], v103 offset:18432
	ds_read_b128 v[68:71], v104 offset:55296
	ds_read_b128 v[72:75], v104 offset:59904
	ds_read_b128 v[192:195], v103 offset:23040
	s_waitcnt lgkmcnt(2)
	v_mfma_f32_32x32x16_bf16 v[48:63], v[64:67], v[68:71], v[48:63]
	ds_read_b128 v[196:199], v103 offset:18464
	ds_read_b128 v[200:203], v104 offset:55328
	s_waitcnt lgkmcnt(3)
	v_mfma_f32_32x32x16_bf16 v[32:47], v[64:67], v[72:75], v[32:47]
	ds_read_b128 v[204:207], v104 offset:59936
	s_waitcnt lgkmcnt(3)
	v_mfma_f32_32x32x16_bf16 v[16:31], v[192:195], v[68:71], v[16:31]
	ds_read_b128 v[208:211], v103 offset:23072
	v_mfma_f32_32x32x16_bf16 v[0:15], v[192:195], v[72:75], v[0:15]
	s_waitcnt lgkmcnt(2)
	v_mfma_f32_32x32x16_bf16 v[48:63], v[196:199], v[200:203], v[48:63]
	ds_read_b128 v[212:215], v103 offset:18496
	ds_read_b128 v[216:219], v104 offset:55360
	s_waitcnt lgkmcnt(3)
	v_mfma_f32_32x32x16_bf16 v[32:47], v[196:199], v[204:207], v[32:47]
	ds_read_b128 v[220:223], v104 offset:59968
	s_waitcnt lgkmcnt(3)
	v_mfma_f32_32x32x16_bf16 v[16:31], v[208:211], v[200:203], v[16:31]
	ds_read_b128 v[224:227], v103 offset:23104
	v_mfma_f32_32x32x16_bf16 v[0:15], v[208:211], v[204:207], v[0:15]
	s_waitcnt lgkmcnt(2)
	v_mfma_f32_32x32x16_bf16 v[48:63], v[212:215], v[216:219], v[48:63]
	ds_read_b128 v[228:231], v103 offset:18528
	ds_read_b128 v[64:67], v104 offset:60000
	s_waitcnt lgkmcnt(3)
	v_mfma_f32_32x32x16_bf16 v[32:47], v[212:215], v[220:223], v[32:47]
	ds_read_b128 v[68:71], v104 offset:55392
	ds_read_b128 v[72:75], v103 offset:23136
	s_waitcnt lgkmcnt(4)
	v_mfma_f32_32x32x16_bf16 v[16:31], v[224:227], v[216:219], v[16:31]
	v_mfma_f32_32x32x16_bf16 v[0:15], v[224:227], v[220:223], v[0:15]
	s_waitcnt lgkmcnt(2)
	v_mfma_f32_32x32x16_bf16 v[32:47], v[228:231], v[64:67], v[32:47]
	s_waitcnt lgkmcnt(0)
	v_mfma_f32_32x32x16_bf16 v[16:31], v[72:75], v[68:71], v[16:31]
	v_mfma_f32_32x32x16_bf16 v[0:15], v[72:75], v[64:67], v[0:15]
	v_mfma_f32_32x32x16_bf16 v[48:63], v[228:231], v[68:71], v[48:63]
	s_setprio 0
	s_addk_i32 s0, 0xf000
	s_lshr_b32 s10, s0, 10
	s_mulk_i32 s10, 0x1800
	s_add_i32 s10, s10, 0x9000
	s_and_b64 s[58:59], s[8:9], exec
	s_cselect_b32 s10, 0x7800, s10
	v_mov_b32_e32 v68, v234
	s_barrier
	s_lshl_b64 s[58:59], s[10:11], 2
	s_add_u32 s58, s30, s58
	v_and_b32_e32 v69, 0x5f, v68
	v_or_b32_e32 v64, s25, v69
	s_addc_u32 s59, s31, s59
	v_ashrrev_i32_e32 v65, 31, v64
	v_lshl_add_u64 v[64:65], v[64:65], 2, s[58:59]
	v_lshl_add_u64 v[66:67], v[64:65], 0, s[14:15]
	v_add_co_u32_e32 v64, vcc, s51, v64
	v_lshlrev_b32_e32 v69, 2, v69
	s_nop 0
	v_addc_co_u32_e32 v65, vcc, 0, v65, vcc
	global_load_dword v64, v[64:65], off
	s_nop 0
	global_load_dword v65, v[66:67], off offset:128
	v_lshrrev_b32_e32 v67, 3, v68
	v_lshrrev_b32_e32 v66, 1, v68
	v_and_b32_e32 v67, 4, v67
	v_and_or_b32 v66, v66, s42, v67
	v_mul_lo_u32 v66, v66, s52
	v_add3_u32 v66, 32, v69, v66
	v_add_u32_e32 v67, 0x400, v66
	v_add_u32_e32 v69, 0x1000, v66
	v_add_u32_e32 v70, 0x1400, v66
	v_add_u32_e32 v71, 0x2000, v66
	v_add_u32_e32 v72, 0x2400, v66
	v_add_u32_e32 v73, 0x3000, v66
	v_add_u32_e32 v74, 0x3200, v66
	v_add_u32_e32 v75, 0x3400, v66
	v_add_u32_e32 v76, 0x3600, v66
	v_add_u32_e32 v77, 0x4000, v66
	v_readlane_b32 s80, v250, 6
	v_readlane_b32 s81, v250, 7
	v_readlane_b32 s82, v250, 8
	v_readlane_b32 s83, v250, 9
	v_readlane_b32 s92, v250, 18
	v_readlane_b32 s93, v250, 19
	v_readlane_b32 s94, v250, 20
	v_readlane_b32 s95, v250, 21
	s_mov_b64 s[80:81], s[92:93]
	s_mov_b64 s[82:83], s[94:95]
	s_lshl_b32 s1, s1, 19
	s_add_u32 s10, s28, s1
	s_mov_b32 s1, s11
	v_readlane_b32 s84, v250, 10
	v_readlane_b32 s85, v250, 11
	v_readlane_b32 s86, v250, 12
	v_readlane_b32 s87, v250, 13
	v_readlane_b32 s88, v250, 14
	v_readlane_b32 s89, v250, 15
	v_readlane_b32 s90, v250, 16
	v_readlane_b32 s91, v250, 17
	s_waitcnt vmcnt(1)
	v_mul_f32_e32 v48, v48, v64
	s_waitcnt vmcnt(0)
	v_mul_f32_e32 v32, v32, v65
	v_mul_f32_e32 v16, v16, v64
	v_mul_f32_e32 v0, v0, v65
	v_mul_f32_e32 v49, v49, v64
	v_mul_f32_e32 v33, v33, v65
	v_mul_f32_e32 v50, v50, v64
	v_mul_f32_e32 v34, v34, v65
	v_mul_f32_e32 v51, v51, v64
	v_mul_f32_e32 v35, v35, v65
	v_mul_f32_e32 v52, v52, v64
	v_mul_f32_e32 v36, v36, v65
	v_mul_f32_e32 v53, v53, v64
	v_mul_f32_e32 v37, v37, v65
	v_mul_f32_e32 v54, v54, v64
	v_mul_f32_e32 v38, v38, v65
	v_mul_f32_e32 v55, v55, v64
	v_mul_f32_e32 v39, v39, v65
	v_mul_f32_e32 v56, v56, v64
	v_mul_f32_e32 v40, v40, v65
	v_mul_f32_e32 v57, v57, v64
	v_mul_f32_e32 v41, v41, v65
	v_mul_f32_e32 v58, v58, v64
	v_mul_f32_e32 v42, v42, v65
	v_mul_f32_e32 v59, v59, v64
	v_mul_f32_e32 v43, v43, v65
	v_mul_f32_e32 v60, v60, v64
	v_mul_f32_e32 v44, v44, v65
	v_mul_f32_e32 v61, v61, v64
	v_mul_f32_e32 v45, v45, v65
	v_mul_f32_e32 v62, v62, v64
	v_mul_f32_e32 v46, v46, v65
	v_mul_f32_e32 v63, v63, v64
	v_mul_f32_e32 v47, v47, v65
	ds_write2_b32 v66, v48, v32 offset1:32
	ds_write2_b32 v66, v49, v33 offset0:132 offset1:164
	ds_write2_b32 v67, v50, v34 offset0:8 offset1:40
	ds_write2_b32 v67, v51, v35 offset0:140 offset1:172
	ds_write2_b32 v69, v52, v36 offset0:32 offset1:64
	ds_write2_b32 v69, v53, v37 offset0:164 offset1:196
	ds_write2_b32 v70, v54, v38 offset0:40 offset1:72
	ds_write2_b32 v70, v55, v39 offset0:172 offset1:204
	ds_write2_b32 v71, v56, v40 offset0:64 offset1:96
	ds_write2_b32 v71, v57, v41 offset0:196 offset1:228
	ds_write2_b32 v72, v58, v42 offset0:72 offset1:104
	ds_write2_b32 v72, v59, v43 offset0:204 offset1:236
	ds_write2_b32 v73, v60, v44 offset0:96 offset1:128
	ds_write2_b32 v74, v61, v45 offset0:100 offset1:132
	ds_write2_b32 v75, v62, v46 offset0:104 offset1:136
	ds_write2_b32 v76, v63, v47 offset0:108 offset1:140
	ds_write2_b32 v77, v16, v0 offset0:128 offset1:160
	v_mul_f32_e32 v0, v17, v64
	v_mul_f32_e32 v1, v1, v65
	v_add_u32_e32 v16, 0x4400, v66
	ds_write2_b32 v16, v0, v1 offset0:4 offset1:36
	v_mul_f32_e32 v0, v18, v64
	v_mul_f32_e32 v1, v2, v65
	ds_write2_b32 v16, v0, v1 offset0:136 offset1:168
	v_mul_f32_e32 v0, v19, v64
	v_mul_f32_e32 v1, v3, v65
	v_add_u32_e32 v2, 0x4800, v66
	ds_write2_b32 v2, v0, v1 offset0:12 offset1:44
	v_mul_f32_e32 v0, v20, v64
	v_mul_f32_e32 v1, v4, v65
	v_add_u32_e32 v2, 0x5000, v66
	ds_write2_b32 v2, v0, v1 offset0:160 offset1:192
	v_mul_f32_e32 v0, v21, v64
	v_mul_f32_e32 v1, v5, v65
	v_add_u32_e32 v2, 0x5400, v66
	ds_write2_b32 v2, v0, v1 offset0:36 offset1:68
	v_mul_f32_e32 v0, v22, v64
	v_mul_f32_e32 v1, v6, v65
	ds_write2_b32 v2, v0, v1 offset0:168 offset1:200
	v_mul_f32_e32 v0, v23, v64
	v_mul_f32_e32 v1, v7, v65
	v_add_u32_e32 v2, 0x5800, v66
	ds_write2_b32 v2, v0, v1 offset0:44 offset1:76
	v_mul_f32_e32 v0, v24, v64
	v_mul_f32_e32 v1, v8, v65
	v_add_u32_e32 v2, 0x6000, v66
	ds_write2_b32 v2, v0, v1 offset0:192 offset1:224
	v_mul_f32_e32 v0, v25, v64
	v_mul_f32_e32 v1, v9, v65
	v_add_u32_e32 v2, 0x6400, v66
	ds_write2_b32 v2, v0, v1 offset0:68 offset1:100
	v_mul_f32_e32 v0, v26, v64
	v_mul_f32_e32 v1, v10, v65
	ds_write2_b32 v2, v0, v1 offset0:200 offset1:232
	v_mul_f32_e32 v0, v27, v64
	v_mul_f32_e32 v1, v11, v65
	v_add_u32_e32 v2, 0x6800, v66
	ds_write2_b32 v2, v0, v1 offset0:76 offset1:108
	v_mul_f32_e32 v0, v28, v64
	v_mul_f32_e32 v1, v12, v65
	v_add_u32_e32 v2, 0x7200, v66
	ds_write2_b32 v2, v0, v1 offset0:96 offset1:128
	v_mul_f32_e32 v0, v29, v64
	v_mul_f32_e32 v1, v13, v65
	v_add_u32_e32 v2, 0x7400, v66
	ds_write2_b32 v2, v0, v1 offset0:100 offset1:132
	v_mul_f32_e32 v0, v30, v64
	v_mul_f32_e32 v1, v14, v65
	v_add_u32_e32 v2, 0x7600, v66
	v_and_b32_e32 v12, 31, v68
	ds_write2_b32 v2, v0, v1 offset0:104 offset1:136
	v_mul_f32_e32 v0, v31, v64
	v_mul_f32_e32 v1, v15, v65
	v_add_u32_e32 v2, 0x7800, v66
	v_lshlrev_b32_e32 v10, 2, v12
	ds_write2_b32 v2, v0, v1 offset0:108 offset1:140
	v_or_b32_e32 v0, s25, v10
	v_ashrrev_i32_e32 v1, 31, v0
	v_lshlrev_b64 v[0:1], 2, v[0:1]
	v_lshl_add_u64 v[2:3], s[80:81], 0, v[0:1]
	v_lshl_add_u64 v[4:5], s[82:83], 0, v[0:1]
	s_waitcnt lgkmcnt(0)
	s_barrier
	global_load_dwordx4 v[0:3], v[2:3], off
	s_nop 0
	global_load_dwordx4 v[4:7], v[4:5], off
	v_and_b32_e32 v8, 64, v102
	v_add_u32_e32 v8, 64, v8
	v_xor_b32_e32 v9, 1, v102
	v_cmp_lt_i32_e32 vcc, v9, v8
	s_addc_u32 s25, s29, 0
	s_lshl_b64 s[0:1], s[0:1], 12
	v_cndmask_b32_e32 v9, v102, v9, vcc
	v_lshlrev_b32_e32 v30, 2, v9
	v_xor_b32_e32 v9, 2, v102
	v_cmp_lt_i32_e32 vcc, v9, v8
	s_add_u32 s58, s17, s0
	s_addc_u32 s59, s19, s1
	v_cndmask_b32_e32 v9, v102, v9, vcc
	v_lshlrev_b32_e32 v31, 2, v9
	v_xor_b32_e32 v9, 4, v102
	v_cmp_lt_i32_e32 vcc, v9, v8
	s_and_b64 s[0:1], s[8:9], exec
	v_add_u32_e32 v10, s22, v10
	v_cndmask_b32_e32 v9, v102, v9, vcc
	v_lshlrev_b32_e32 v32, 2, v9
	v_xor_b32_e32 v9, 8, v102
	v_cmp_lt_i32_e32 vcc, v9, v8
	v_ashrrev_i32_e32 v22, 5, v68
	s_cselect_b32 s59, s25, s59
	s_cselect_b32 s58, s10, s58
	v_cndmask_b32_e32 v9, v102, v9, vcc
	v_ashrrev_i32_e32 v11, 31, v10
	s_add_i32 s10, s24, s35
	v_cmp_eq_u32_e64 s[0:1], 0, v12
	v_lshlrev_b32_e32 v33, 2, v9
	v_xor_b32_e32 v9, 16, v102
	v_lshlrev_b64 v[24:25], 2, v[10:11]
	v_lshlrev_b32_e32 v11, 4, v12
	v_add_u32_e32 v12, s10, v22
	s_add_i32 s10, s24, s36
	s_add_i32 s24, s24, s37
	v_cmp_lt_i32_e32 vcc, v9, v8
	v_add_u32_e32 v16, s10, v22
	v_add_u32_e32 v20, s24, v22
	v_cndmask_b32_e32 v8, v102, v9, vcc
	v_ashrrev_i32_e32 v23, 31, v22
	v_mul_lo_u32 v10, v22, s52
	v_ashrrev_i32_e32 v13, 31, v12
	v_ashrrev_i32_e32 v17, 31, v16
	v_ashrrev_i32_e32 v21, 31, v20
	v_add_u32_e32 v26, s23, v22
	v_lshlrev_b32_e32 v34, 2, v8
	v_lshlrev_b64 v[8:9], 12, v[22:23]
	v_add3_u32 v35, v10, v11, 32
	v_lshlrev_b64 v[10:11], 12, v[12:13]
	v_lshlrev_b32_e32 v12, 1, v12
	v_lshlrev_b64 v[14:15], 12, v[16:17]
	v_lshlrev_b32_e32 v16, 1, v16
	v_lshlrev_b64 v[18:19], 12, v[20:21]
	v_lshlrev_b32_e32 v20, 1, v20
	v_lshlrev_b32_e32 v22, 1, v26
	v_ashrrev_i32_e32 v27, 31, v26
	v_lshl_add_u64 v[8:9], v[8:9], 0, v[24:25]
	v_ashrrev_i32_e32 v13, 31, v12
	v_ashrrev_i32_e32 v17, 31, v16
	v_ashrrev_i32_e32 v21, 31, v20
	v_ashrrev_i32_e32 v23, 31, v22
	v_lshlrev_b64 v[26:27], 12, v[26:27]
	v_lshl_add_u64 v[8:9], s[58:59], 0, v[8:9]
	v_lshl_add_u64 v[10:11], v[10:11], 0, v[24:25]
	v_lshlrev_b64 v[12:13], 2, v[12:13]
	v_lshl_add_u64 v[14:15], v[14:15], 0, v[24:25]
	v_lshlrev_b64 v[16:17], 2, v[16:17]
	v_lshl_add_u64 v[18:19], v[18:19], 0, v[24:25]
	v_lshlrev_b64 v[20:21], 2, v[20:21]
	v_lshlrev_b64 v[22:23], 2, v[22:23]
	v_lshl_add_u64 v[24:25], v[26:27], 0, v[24:25]
	s_mov_b64 s[22:23], 0
	s_branch .LBB0_3809

.LBB0_3929:
	s_setprio 1
	ds_read_b128 v[140:143], v103
	ds_read_b128 v[144:147], v104 offset:36864
	ds_read_b128 v[148:151], v104 offset:41472
	ds_read_b128 v[192:195], v103 offset:4608
	s_waitcnt lgkmcnt(2)
	v_mfma_f32_32x32x16_bf16 v[48:63], v[140:143], v[144:147], v[48:63]
	ds_read_b128 v[196:199], v103 offset:32
	ds_read_b128 v[200:203], v104 offset:36896
	global_load_dwordx4 v[108:111], v168, s[98:99] offset:3840
	global_load_dwordx4 v[112:115], v170, s[98:99] offset:3840
	s_waitcnt vmcnt(9)
	ds_write_b128 v105, v[68:71] offset:18432
	s_waitcnt lgkmcnt(4)
	v_mfma_f32_32x32x16_bf16 v[32:47], v[140:143], v[148:151], v[32:47]
	ds_read_b128 v[204:207], v104 offset:41504
	global_load_dwordx4 v[116:119], v172, s[98:99] offset:3840
	global_load_dwordx4 v[120:123], v174, s[98:99] offset:3840
	s_waitcnt lgkmcnt(4)
	v_mfma_f32_32x32x16_bf16 v[16:31], v[192:195], v[144:147], v[16:31]
	ds_read_b128 v[208:211], v103 offset:4640
	global_load_dwordx4 v[124:127], v176, s[98:99] offset:3840
	global_load_dwordx4 v[128:131], v178, s[98:99] offset:3840
	s_waitcnt vmcnt(11)
	ds_write_b128 v105, v[84:87] offset:23040
	v_mfma_f32_32x32x16_bf16 v[0:15], v[192:195], v[148:151], v[0:15]
	global_load_dwordx4 v[132:135], v180, s[98:99] offset:3840
	global_load_dwordx4 v[136:139], v182, s[98:99] offset:3840
	s_waitcnt lgkmcnt(4)
	v_mfma_f32_32x32x16_bf16 v[48:63], v[196:199], v[200:203], v[48:63]
	ds_read_b128 v[212:215], v103 offset:64
	ds_read_b128 v[216:219], v104 offset:36928
	s_waitcnt vmcnt(12)
	ds_write_b128 v105, v[88:91] offset:27648
	s_waitcnt lgkmcnt(5)
	v_mfma_f32_32x32x16_bf16 v[32:47], v[196:199], v[204:207], v[32:47]
	ds_read_b128 v[220:223], v104 offset:41536
	s_waitcnt lgkmcnt(5)
	v_mfma_f32_32x32x16_bf16 v[16:31], v[208:211], v[200:203], v[16:31]
	ds_read_b128 v[224:227], v103 offset:4672
	s_waitcnt vmcnt(11)
	ds_write_b128 v105, v[92:95] offset:32256
	v_mfma_f32_32x32x16_bf16 v[0:15], v[208:211], v[204:207], v[0:15]
	s_waitcnt lgkmcnt(4)
	v_mfma_f32_32x32x16_bf16 v[48:63], v[212:215], v[216:219], v[48:63]
	ds_read_b128 v[228:231], v103 offset:96
	ds_read_b128 v[140:143], v104 offset:36960
	ds_write_b128 v105, v[64:67] offset:55296
	s_waitcnt lgkmcnt(5)
	v_mfma_f32_32x32x16_bf16 v[32:47], v[212:215], v[220:223], v[32:47]
	ds_read_b128 v[144:147], v104 offset:41568
	s_waitcnt lgkmcnt(5)
	v_mfma_f32_32x32x16_bf16 v[16:31], v[224:227], v[216:219], v[16:31]
	ds_read_b128 v[148:151], v103 offset:4704
	s_waitcnt vmcnt(10)
	ds_write_b128 v105, v[72:75] offset:59904
	v_mfma_f32_32x32x16_bf16 v[0:15], v[224:227], v[220:223], v[0:15]
	s_waitcnt lgkmcnt(4)
	v_mfma_f32_32x32x16_bf16 v[48:63], v[228:231], v[140:143], v[48:63]
	s_waitcnt vmcnt(9)
	ds_write_b128 v105, v[76:79] offset:64512
	s_waitcnt lgkmcnt(3)
	v_mfma_f32_32x32x16_bf16 v[32:47], v[228:231], v[144:147], v[32:47]
	s_waitcnt lgkmcnt(2)
	v_mfma_f32_32x32x16_bf16 v[16:31], v[148:151], v[140:143], v[16:31]
	s_waitcnt vmcnt(8)
	ds_write_b128 v106, v[80:83] offset:13824
	v_mfma_f32_32x32x16_bf16 v[0:15], v[148:151], v[144:147], v[0:15]
	s_setprio 0
	s_waitcnt lgkmcnt(0)
	s_barrier
	s_setprio 1
	ds_read_b128 v[140:143], v103 offset:18432
	ds_read_b128 v[144:147], v104 offset:55296
	ds_read_b128 v[148:151], v104 offset:59904
	ds_read_b128 v[192:195], v103 offset:23040
	s_waitcnt lgkmcnt(2)
	v_mfma_f32_32x32x16_bf16 v[48:63], v[140:143], v[144:147], v[48:63]
	ds_read_b128 v[196:199], v103 offset:18464
	ds_read_b128 v[200:203], v104 offset:55328
	global_load_dwordx4 v[68:71], v168, s[98:99] offset:3968
	global_load_dwordx4 v[84:87], v170, s[98:99] offset:3968
	s_waitcnt vmcnt(9)
	ds_write_b128 v105, v[108:111]
	s_waitcnt lgkmcnt(4)
	v_mfma_f32_32x32x16_bf16 v[32:47], v[140:143], v[148:151], v[32:47]
	ds_read_b128 v[204:207], v104 offset:59936
	global_load_dwordx4 v[88:91], v172, s[98:99] offset:3968
	global_load_dwordx4 v[92:95], v174, s[98:99] offset:3968
	s_waitcnt lgkmcnt(4)
	v_mfma_f32_32x32x16_bf16 v[16:31], v[192:195], v[144:147], v[16:31]
	ds_read_b128 v[208:211], v103 offset:23072
	global_load_dwordx4 v[64:67], v176, s[98:99] offset:3968
	global_load_dwordx4 v[72:75], v178, s[98:99] offset:3968
	s_waitcnt vmcnt(12)
	ds_write_b128 v105, v[112:115] offset:4608
	v_mfma_f32_32x32x16_bf16 v[0:15], v[192:195], v[148:151], v[0:15]
	global_load_dwordx4 v[76:79], v180, s[98:99] offset:3968
	global_load_dwordx4 v[80:83], v182, s[98:99] offset:3968
	s_waitcnt lgkmcnt(4)
	v_mfma_f32_32x32x16_bf16 v[48:63], v[196:199], v[200:203], v[48:63]
	ds_read_b128 v[212:215], v103 offset:18496
	ds_read_b128 v[216:219], v104 offset:55360
	s_add_u32 s98, s98, 0x100
	s_addc_u32 s99, s99, 0
	s_add_i32 s41, s41, 2
	s_cmp_lt_u32 s41, 11
	s_waitcnt vmcnt(13)
	ds_write_b128 v105, v[116:119] offset:9216
	s_waitcnt lgkmcnt(5)
	v_mfma_f32_32x32x16_bf16 v[32:47], v[196:199], v[204:207], v[32:47]
	ds_read_b128 v[220:223], v104 offset:59968
	s_waitcnt lgkmcnt(5)
	v_mfma_f32_32x32x16_bf16 v[16:31], v[208:211], v[200:203], v[16:31]
	ds_read_b128 v[224:227], v103 offset:23104
	s_waitcnt vmcnt(12)
	ds_write_b128 v105, v[120:123] offset:13824
	v_mfma_f32_32x32x16_bf16 v[0:15], v[208:211], v[204:207], v[0:15]
	s_waitcnt lgkmcnt(4)
	v_mfma_f32_32x32x16_bf16 v[48:63], v[212:215], v[216:219], v[48:63]
	ds_read_b128 v[228:231], v103 offset:18528
	ds_read_b128 v[140:143], v104 offset:55392
	s_waitcnt vmcnt(11)
	ds_write_b128 v105, v[124:127] offset:36864
	s_waitcnt lgkmcnt(5)
	v_mfma_f32_32x32x16_bf16 v[32:47], v[212:215], v[220:223], v[32:47]
	ds_read_b128 v[144:147], v104 offset:60000
	s_waitcnt lgkmcnt(5)
	v_mfma_f32_32x32x16_bf16 v[16:31], v[224:227], v[216:219], v[16:31]
	ds_read_b128 v[148:151], v103 offset:23136
	s_waitcnt vmcnt(10)
	ds_write_b128 v105, v[128:131] offset:41472
	v_mfma_f32_32x32x16_bf16 v[0:15], v[224:227], v[220:223], v[0:15]
	s_waitcnt lgkmcnt(4)
	v_mfma_f32_32x32x16_bf16 v[48:63], v[228:231], v[140:143], v[48:63]
	s_waitcnt vmcnt(9)
	ds_write_b128 v105, v[132:135] offset:46080
	s_waitcnt lgkmcnt(3)
	v_mfma_f32_32x32x16_bf16 v[32:47], v[228:231], v[144:147], v[32:47]
	s_waitcnt lgkmcnt(2)
	v_mfma_f32_32x32x16_bf16 v[16:31], v[148:151], v[140:143], v[16:31]
	s_waitcnt vmcnt(8)
	ds_write_b128 v105, v[136:139] offset:50688
	v_mfma_f32_32x32x16_bf16 v[0:15], v[148:151], v[144:147], v[0:15]
	s_setprio 0
	s_waitcnt lgkmcnt(0)
	s_barrier
	s_cbranch_scc1 .LBB0_3929
	s_setprio 1
	ds_read_b128 v[98:101], v103
	ds_read_b128 v[108:111], v104 offset:36864
	ds_read_b128 v[112:115], v104 offset:41472
	ds_read_b128 v[192:195], v103 offset:4608
	s_waitcnt lgkmcnt(2)
	v_mfma_f32_32x32x16_bf16 v[48:63], v[98:101], v[108:111], v[48:63]
	ds_read_b128 v[196:199], v103 offset:32
	ds_read_b128 v[200:203], v104 offset:36896
	s_waitcnt vmcnt(7)
	ds_write_b128 v105, v[68:71] offset:18432
	s_waitcnt lgkmcnt(4)
	v_mfma_f32_32x32x16_bf16 v[32:47], v[98:101], v[112:115], v[32:47]
	ds_read_b128 v[204:207], v104 offset:41504
	s_waitcnt lgkmcnt(4)
	v_mfma_f32_32x32x16_bf16 v[16:31], v[192:195], v[108:111], v[16:31]
	ds_read_b128 v[208:211], v103 offset:4640
	s_waitcnt vmcnt(6)
	ds_write_b128 v105, v[84:87] offset:23040
	v_mfma_f32_32x32x16_bf16 v[0:15], v[192:195], v[112:115], v[0:15]
	s_waitcnt lgkmcnt(4)
	v_mfma_f32_32x32x16_bf16 v[48:63], v[196:199], v[200:203], v[48:63]
	ds_read_b128 v[212:215], v103 offset:64
	ds_read_b128 v[216:219], v104 offset:36928
	s_waitcnt vmcnt(5)
	ds_write_b128 v105, v[88:91] offset:27648
	s_waitcnt lgkmcnt(5)
	v_mfma_f32_32x32x16_bf16 v[32:47], v[196:199], v[204:207], v[32:47]
	ds_read_b128 v[220:223], v104 offset:41536
	s_waitcnt lgkmcnt(5)
	v_mfma_f32_32x32x16_bf16 v[16:31], v[208:211], v[200:203], v[16:31]
	ds_read_b128 v[224:227], v103 offset:4672
	s_waitcnt vmcnt(4)
	ds_write_b128 v105, v[92:95] offset:32256
	v_mfma_f32_32x32x16_bf16 v[0:15], v[208:211], v[204:207], v[0:15]
	s_waitcnt lgkmcnt(4)
	v_mfma_f32_32x32x16_bf16 v[48:63], v[212:215], v[216:219], v[48:63]
	ds_read_b128 v[228:231], v103 offset:96
	ds_read_b128 v[98:101], v104 offset:36960
	s_waitcnt vmcnt(3)
	ds_write_b128 v105, v[64:67] offset:55296
	s_waitcnt lgkmcnt(5)
	v_mfma_f32_32x32x16_bf16 v[32:47], v[212:215], v[220:223], v[32:47]
	ds_read_b128 v[108:111], v104 offset:41568
	s_waitcnt lgkmcnt(5)
	v_mfma_f32_32x32x16_bf16 v[16:31], v[224:227], v[216:219], v[16:31]
	ds_read_b128 v[112:115], v103 offset:4704
	s_waitcnt vmcnt(2)
	ds_write_b128 v105, v[72:75] offset:59904
	v_mfma_f32_32x32x16_bf16 v[0:15], v[224:227], v[220:223], v[0:15]
	s_waitcnt lgkmcnt(4)
	v_mfma_f32_32x32x16_bf16 v[48:63], v[228:231], v[98:101], v[48:63]
	s_waitcnt vmcnt(1)
	ds_write_b128 v105, v[76:79] offset:64512
	s_waitcnt lgkmcnt(3)
	v_mfma_f32_32x32x16_bf16 v[32:47], v[228:231], v[108:111], v[32:47]
	s_waitcnt lgkmcnt(2)
	v_mfma_f32_32x32x16_bf16 v[16:31], v[112:115], v[98:101], v[16:31]
	s_waitcnt vmcnt(0)
	ds_write_b128 v106, v[80:83] offset:13824
	v_mfma_f32_32x32x16_bf16 v[0:15], v[112:115], v[108:111], v[0:15]
	s_setprio 0
	s_waitcnt lgkmcnt(0)
	s_barrier
	s_setprio 1
	ds_read_b128 v[64:67], v103 offset:18432
	ds_read_b128 v[68:71], v104 offset:55296
	ds_read_b128 v[72:75], v104 offset:59904
	ds_read_b128 v[192:195], v103 offset:23040
	s_waitcnt lgkmcnt(2)
	v_mfma_f32_32x32x16_bf16 v[48:63], v[64:67], v[68:71], v[48:63]
	ds_read_b128 v[196:199], v103 offset:18464
	ds_read_b128 v[200:203], v104 offset:55328
	s_waitcnt lgkmcnt(3)
	v_mfma_f32_32x32x16_bf16 v[32:47], v[64:67], v[72:75], v[32:47]
	ds_read_b128 v[204:207], v104 offset:59936
	s_waitcnt lgkmcnt(3)
	v_mfma_f32_32x32x16_bf16 v[16:31], v[192:195], v[68:71], v[16:31]
	ds_read_b128 v[208:211], v103 offset:23072
	v_mfma_f32_32x32x16_bf16 v[0:15], v[192:195], v[72:75], v[0:15]
	s_waitcnt lgkmcnt(2)
	v_mfma_f32_32x32x16_bf16 v[48:63], v[196:199], v[200:203], v[48:63]
	ds_read_b128 v[212:215], v103 offset:18496
	ds_read_b128 v[216:219], v104 offset:55360
	s_waitcnt lgkmcnt(3)
	v_mfma_f32_32x32x16_bf16 v[32:47], v[196:199], v[204:207], v[32:47]
	ds_read_b128 v[220:223], v104 offset:59968
	s_waitcnt lgkmcnt(3)
	v_mfma_f32_32x32x16_bf16 v[16:31], v[208:211], v[200:203], v[16:31]
	ds_read_b128 v[224:227], v103 offset:23104
	v_mfma_f32_32x32x16_bf16 v[0:15], v[208:211], v[204:207], v[0:15]
	s_waitcnt lgkmcnt(2)
	v_mfma_f32_32x32x16_bf16 v[48:63], v[212:215], v[216:219], v[48:63]
	ds_read_b128 v[228:231], v103 offset:18528
	ds_read_b128 v[64:67], v104 offset:55392
	s_waitcnt lgkmcnt(3)
	v_mfma_f32_32x32x16_bf16 v[32:47], v[212:215], v[220:223], v[32:47]
	ds_read_b128 v[68:71], v104 offset:60000
	s_waitcnt lgkmcnt(3)
	v_mfma_f32_32x32x16_bf16 v[16:31], v[224:227], v[216:219], v[16:31]
	ds_read_b128 v[72:75], v103 offset:23136
	v_mfma_f32_32x32x16_bf16 v[0:15], v[224:227], v[220:223], v[0:15]
	s_waitcnt lgkmcnt(2)
	v_mfma_f32_32x32x16_bf16 v[48:63], v[228:231], v[64:67], v[48:63]
	s_waitcnt lgkmcnt(1)
	v_mfma_f32_32x32x16_bf16 v[32:47], v[228:231], v[68:71], v[32:47]
	s_waitcnt lgkmcnt(0)
	v_mfma_f32_32x32x16_bf16 v[16:31], v[72:75], v[64:67], v[16:31]
	v_mfma_f32_32x32x16_bf16 v[0:15], v[72:75], v[68:71], v[0:15]
	s_setprio 0
	v_lshrrev_b32_e32 v65, 3, v102
	v_lshrrev_b32_e32 v64, 1, v102
	v_and_b32_e32 v65, 4, v65
	v_and_or_b32 v64, v64, s22, v65
	v_and_b32_e32 v65, 0x5f, v102
	v_lshlrev_b32_e32 v65, 1, v65
	v_mul_lo_u32 v64, v64, s36
	v_add3_u32 v64, 32, v65, v64
	s_nop 2
	v_cvt_pk_bf16_f32 v0, v0, s0
	s_barrier
	ds_write_b16 v64, v0 offset:8768
	v_cvt_pk_bf16_f32 v0, v17, s0
	ds_write_b16 v64, v0 offset:8976
	v_cvt_pk_bf16_f32 v0, v1, s0
	ds_write_b16 v64, v0 offset:9040
	v_cvt_pk_bf16_f32 v0, v18, s0
	v_cvt_pk_bf16_f32 v32, v32, s0
	ds_write_b16 v64, v0 offset:9248
	v_cvt_pk_bf16_f32 v0, v2, s0
	ds_write_b16 v64, v32 offset:64
	v_cvt_pk_bf16_f32 v32, v49, s0
	ds_write_b16 v64, v0 offset:9312
	v_cvt_pk_bf16_f32 v0, v19, s0
	ds_write_b16 v64, v32 offset:272
	v_cvt_pk_bf16_f32 v32, v33, s0
	ds_write_b16 v64, v0 offset:9520
	v_cvt_pk_bf16_f32 v0, v3, s0
	ds_write_b16 v64, v32 offset:336
	v_cvt_pk_bf16_f32 v32, v50, s0
	ds_write_b16 v64, v0 offset:9584
	v_cvt_pk_bf16_f32 v0, v20, s0
	ds_write_b16 v64, v32 offset:544
	v_cvt_pk_bf16_f32 v32, v34, s0
	ds_write_b16 v64, v0 offset:10880
	v_cvt_pk_bf16_f32 v0, v4, s0
	ds_write_b16 v64, v32 offset:608
	v_cvt_pk_bf16_f32 v32, v51, s0
	ds_write_b16 v64, v0 offset:10944
	v_cvt_pk_bf16_f32 v0, v21, s0
	ds_write_b16 v64, v32 offset:816
	v_cvt_pk_bf16_f32 v32, v35, s0
	ds_write_b16 v64, v0 offset:11152
	v_cvt_pk_bf16_f32 v0, v5, s0
	ds_write_b16 v64, v32 offset:880
	v_cvt_pk_bf16_f32 v32, v52, s0
	ds_write_b16 v64, v0 offset:11216
	v_cvt_pk_bf16_f32 v0, v22, s0
	ds_write_b16 v64, v32 offset:2176
	v_cvt_pk_bf16_f32 v32, v36, s0
	ds_write_b16 v64, v0 offset:11424
	v_cvt_pk_bf16_f32 v0, v6, s0
	ds_write_b16 v64, v32 offset:2240
	v_cvt_pk_bf16_f32 v32, v53, s0
	ds_write_b16 v64, v0 offset:11488
	v_cvt_pk_bf16_f32 v0, v23, s0
	ds_write_b16 v64, v32 offset:2448
	v_cvt_pk_bf16_f32 v32, v37, s0
	ds_write_b16 v64, v0 offset:11696
	v_cvt_pk_bf16_f32 v0, v7, s0
	ds_write_b16 v64, v32 offset:2512
	v_cvt_pk_bf16_f32 v32, v54, s0
	ds_write_b16 v64, v0 offset:11760
	v_cvt_pk_bf16_f32 v0, v24, s0
	ds_write_b16 v64, v32 offset:2720
	v_cvt_pk_bf16_f32 v32, v38, s0
	ds_write_b16 v64, v0 offset:13056
	v_cvt_pk_bf16_f32 v0, v8, s0
	ds_write_b16 v64, v32 offset:2784
	v_cvt_pk_bf16_f32 v32, v55, s0
	ds_write_b16 v64, v0 offset:13120
	v_cvt_pk_bf16_f32 v0, v25, s0
	ds_write_b16 v64, v32 offset:2992
	v_cvt_pk_bf16_f32 v32, v39, s0
	ds_write_b16 v64, v0 offset:13328
	v_cvt_pk_bf16_f32 v0, v9, s0
	ds_write_b16 v64, v32 offset:3056
	v_cvt_pk_bf16_f32 v32, v56, s0
	ds_write_b16 v64, v0 offset:13392
	v_cvt_pk_bf16_f32 v0, v26, s0
	ds_write_b16 v64, v32 offset:4352
	v_cvt_pk_bf16_f32 v32, v40, s0
	ds_write_b16 v64, v0 offset:13600
	v_cvt_pk_bf16_f32 v0, v10, s0
	ds_write_b16 v64, v32 offset:4416
	v_cvt_pk_bf16_f32 v32, v57, s0
	ds_write_b16 v64, v0 offset:13664
	v_cvt_pk_bf16_f32 v0, v27, s0
	ds_write_b16 v64, v32 offset:4624
	v_cvt_pk_bf16_f32 v32, v41, s0
	ds_write_b16 v64, v0 offset:13872
	v_cvt_pk_bf16_f32 v0, v11, s0
	ds_write_b16 v64, v32 offset:4688
	v_cvt_pk_bf16_f32 v32, v58, s0
	ds_write_b16 v64, v0 offset:13936
	v_cvt_pk_bf16_f32 v0, v28, s0
	ds_write_b16 v64, v32 offset:4896
	v_cvt_pk_bf16_f32 v32, v42, s0
	ds_write_b16 v64, v0 offset:15232
	v_cvt_pk_bf16_f32 v0, v12, s0
	ds_write_b16 v64, v32 offset:4960
	v_cvt_pk_bf16_f32 v32, v59, s0
	ds_write_b16 v64, v0 offset:15296
	v_cvt_pk_bf16_f32 v0, v29, s0
	ds_write_b16 v64, v32 offset:5168
	v_cvt_pk_bf16_f32 v32, v43, s0
	ds_write_b16 v64, v0 offset:15504
	v_cvt_pk_bf16_f32 v0, v13, s0
	ds_write_b16 v64, v32 offset:5232
	v_cvt_pk_bf16_f32 v32, v60, s0
	ds_write_b16 v64, v0 offset:15568
	v_cvt_pk_bf16_f32 v0, v30, s0
	ds_write_b16 v64, v32 offset:6528
	v_cvt_pk_bf16_f32 v32, v44, s0
	ds_write_b16 v64, v0 offset:15776
	v_cvt_pk_bf16_f32 v0, v14, s0
	s_mul_i32 s11, s11, 0x160000
	ds_write_b16 v64, v32 offset:6592
	v_cvt_pk_bf16_f32 v32, v61, s0
	ds_write_b16 v64, v0 offset:15840
	v_cvt_pk_bf16_f32 v0, v31, s0
	s_add_u32 s41, s13, s11
	ds_write_b16 v64, v32 offset:6800
	v_cvt_pk_bf16_f32 v32, v45, s0
	ds_write_b16 v64, v0 offset:16048
	v_cvt_pk_bf16_f32 v0, v15, s0
	s_addc_u32 s42, s14, 0
	s_ashr_i32 s11, s10, 31
	ds_write_b16 v64, v32 offset:6864
	v_cvt_pk_bf16_f32 v32, v62, s0
	ds_write_b16 v64, v0 offset:16112
	s_lshl_b64 s[10:11], s[10:11], 1
	v_lshlrev_b32_e32 v0, 4, v102
	ds_write_b16 v64, v32 offset:7072
	v_cvt_pk_bf16_f32 v32, v46, s0
	s_add_u32 s10, s41, s10
	v_and_b32_e32 v96, 0xf0, v0
	ds_write_b16 v64, v32 offset:7136
	v_cvt_pk_bf16_f32 v32, v63, s0
	s_addc_u32 s11, s42, s11
	v_add_u32_e32 v8, 32, v96
	v_ashrrev_i32_e32 v9, 4, v102
	v_add_u32_e32 v4, 0x100, v102
	v_cvt_pk_bf16_f32 v48, v48, s0
	ds_write_b16 v64, v32 offset:7344
	v_cvt_pk_bf16_f32 v32, v47, s0
	v_cvt_pk_bf16_f32 v16, v16, s0
	v_lshl_add_u64 v[10:11], s[10:11], 0, v[96:97]
	v_mad_u64_u32 v[0:1], s[10:11], v9, s36, v[8:9]
	v_ashrrev_i32_e32 v14, 4, v4
	ds_write_b16 v64, v48
	ds_write_b16 v64, v32 offset:7408
	ds_write_b16 v64, v16 offset:8704
	s_waitcnt lgkmcnt(0)
	s_barrier
	ds_read_b128 v[0:3], v0
	v_mad_u64_u32 v[4:5], s[10:11], v14, s36, v[8:9]
	ds_read_b128 v[4:7], v4
	v_mad_i64_i32 v[12:13], s[10:11], v9, s37, v[10:11]
	s_waitcnt lgkmcnt(1)
	global_store_dwordx4 v[12:13], v[0:3], off
	s_nop 1
	v_mad_i64_i32 v[0:1], s[10:11], v14, s37, v[10:11]
	s_waitcnt lgkmcnt(0)
	global_store_dwordx4 v[0:1], v[4:7], off
	v_add_u32_e32 v0, 0x200, v102
	v_ashrrev_i32_e32 v9, 4, v0
	v_add_u32_e32 v4, 0x300, v102
	v_mad_u64_u32 v[0:1], s[10:11], v9, s36, v[8:9]
	v_ashrrev_i32_e32 v14, 4, v4
	ds_read_b128 v[0:3], v0
	v_mad_u64_u32 v[4:5], s[10:11], v14, s36, v[8:9]
	ds_read_b128 v[4:7], v4
	v_mad_i64_i32 v[12:13], s[10:11], v9, s37, v[10:11]
	s_waitcnt lgkmcnt(1)
	global_store_dwordx4 v[12:13], v[0:3], off
	s_nop 1
	v_mad_i64_i32 v[0:1], s[10:11], v14, s37, v[10:11]
	s_waitcnt lgkmcnt(0)
	global_store_dwordx4 v[0:1], v[4:7], off
	v_add_u32_e32 v0, 0x400, v102
	v_ashrrev_i32_e32 v9, 4, v0
	v_add_u32_e32 v4, 0x500, v102
	v_mad_u64_u32 v[0:1], s[10:11], v9, s36, v[8:9]
	v_ashrrev_i32_e32 v14, 4, v4
	ds_read_b128 v[0:3], v0
	v_mad_u64_u32 v[4:5], s[10:11], v14, s36, v[8:9]
	ds_read_b128 v[4:7], v4
	v_mad_i64_i32 v[12:13], s[10:11], v9, s37, v[10:11]
	s_waitcnt lgkmcnt(1)
	global_store_dwordx4 v[12:13], v[0:3], off
	s_nop 1
	v_mad_i64_i32 v[0:1], s[10:11], v14, s37, v[10:11]
	s_waitcnt lgkmcnt(0)
	global_store_dwordx4 v[0:1], v[4:7], off
	v_add_u32_e32 v0, 0x600, v102
	v_ashrrev_i32_e32 v9, 4, v0
	v_add_u32_e32 v4, 0x700, v102
	v_mad_u64_u32 v[0:1], s[10:11], v9, s36, v[8:9]
	v_ashrrev_i32_e32 v12, 4, v4
	ds_read_b128 v[0:3], v0
	v_mad_u64_u32 v[4:5], s[10:11], v12, s36, v[8:9]
	ds_read_b128 v[4:7], v4
	v_mad_i64_i32 v[8:9], s[10:11], v9, s37, v[10:11]
	s_waitcnt lgkmcnt(1)
	global_store_dwordx4 v[8:9], v[0:3], off
	s_nop 1
	v_mad_i64_i32 v[0:1], s[10:11], v12, s37, v[10:11]
	s_waitcnt lgkmcnt(0)
	global_store_dwordx4 v[0:1], v[4:7], off
	s_branch .LBB0_3926

.LBB0_4051:
	s_setprio 1
	ds_read_b128 v[146:149], v109
	ds_read_b128 v[150:153], v110 offset:36864
	ds_read_b128 v[154:157], v110 offset:41472
	ds_read_b128 v[192:195], v109 offset:4608
	s_waitcnt lgkmcnt(2)
	v_mfma_f32_32x32x16_bf16 v[48:63], v[146:149], v[150:153], v[48:63]
	ds_read_b128 v[196:199], v109 offset:32
	ds_read_b128 v[200:203], v110 offset:36896
	global_load_dwordx4 v[114:117], v174, s[98:99] offset:3840
	global_load_dwordx4 v[118:121], v176, s[98:99] offset:3840
	s_waitcnt vmcnt(9)
	ds_write_b128 v111, v[68:71] offset:18432
	s_waitcnt lgkmcnt(4)
	v_mfma_f32_32x32x16_bf16 v[32:47], v[146:149], v[154:157], v[32:47]
	ds_read_b128 v[204:207], v110 offset:41504
	global_load_dwordx4 v[122:125], v178, s[98:99] offset:3840
	global_load_dwordx4 v[126:129], v180, s[98:99] offset:3840
	s_waitcnt lgkmcnt(4)
	v_mfma_f32_32x32x16_bf16 v[16:31], v[192:195], v[150:153], v[16:31]
	ds_read_b128 v[208:211], v109 offset:4640
	global_load_dwordx4 v[130:133], v182, s[98:99] offset:3840
	global_load_dwordx4 v[134:137], v184, s[98:99] offset:3840
	s_waitcnt vmcnt(11)
	ds_write_b128 v111, v[84:87] offset:23040
	v_mfma_f32_32x32x16_bf16 v[0:15], v[192:195], v[154:157], v[0:15]
	global_load_dwordx4 v[138:141], v186, s[98:99] offset:3840
	global_load_dwordx4 v[142:145], v188, s[98:99] offset:3840
	s_waitcnt lgkmcnt(4)
	v_mfma_f32_32x32x16_bf16 v[48:63], v[196:199], v[200:203], v[48:63]
	ds_read_b128 v[212:215], v109 offset:64
	ds_read_b128 v[216:219], v110 offset:36928
	s_waitcnt vmcnt(12)
	ds_write_b128 v111, v[88:91] offset:27648
	s_waitcnt lgkmcnt(5)
	v_mfma_f32_32x32x16_bf16 v[32:47], v[196:199], v[204:207], v[32:47]
	ds_read_b128 v[220:223], v110 offset:41536
	s_waitcnt lgkmcnt(5)
	v_mfma_f32_32x32x16_bf16 v[16:31], v[208:211], v[200:203], v[16:31]
	ds_read_b128 v[224:227], v109 offset:4672
	s_waitcnt vmcnt(11)
	ds_write_b128 v111, v[92:95] offset:32256
	v_mfma_f32_32x32x16_bf16 v[0:15], v[208:211], v[204:207], v[0:15]
	s_waitcnt lgkmcnt(4)
	v_mfma_f32_32x32x16_bf16 v[48:63], v[212:215], v[216:219], v[48:63]
	ds_read_b128 v[228:231], v109 offset:96
	ds_read_b128 v[146:149], v110 offset:36960
	ds_write_b128 v111, v[64:67] offset:55296
	s_waitcnt lgkmcnt(5)
	v_mfma_f32_32x32x16_bf16 v[32:47], v[212:215], v[220:223], v[32:47]
	ds_read_b128 v[150:153], v110 offset:41568
	s_waitcnt lgkmcnt(5)
	v_mfma_f32_32x32x16_bf16 v[16:31], v[224:227], v[216:219], v[16:31]
	ds_read_b128 v[154:157], v109 offset:4704
	s_waitcnt vmcnt(10)
	ds_write_b128 v111, v[72:75] offset:59904
	v_mfma_f32_32x32x16_bf16 v[0:15], v[224:227], v[220:223], v[0:15]
	s_waitcnt lgkmcnt(4)
	v_mfma_f32_32x32x16_bf16 v[48:63], v[228:231], v[146:149], v[48:63]
	s_waitcnt vmcnt(9)
	ds_write_b128 v111, v[76:79] offset:64512
	s_waitcnt lgkmcnt(3)
	v_mfma_f32_32x32x16_bf16 v[32:47], v[228:231], v[150:153], v[32:47]
	s_waitcnt lgkmcnt(2)
	v_mfma_f32_32x32x16_bf16 v[16:31], v[154:157], v[146:149], v[16:31]
	s_waitcnt vmcnt(8)
	ds_write_b128 v112, v[80:83] offset:13824
	v_mfma_f32_32x32x16_bf16 v[0:15], v[154:157], v[150:153], v[0:15]
	s_setprio 0
	s_waitcnt lgkmcnt(0)
	s_barrier
	s_setprio 1
	ds_read_b128 v[146:149], v109 offset:18432
	ds_read_b128 v[150:153], v110 offset:55296
	ds_read_b128 v[154:157], v110 offset:59904
	ds_read_b128 v[192:195], v109 offset:23040
	s_waitcnt lgkmcnt(2)
	v_mfma_f32_32x32x16_bf16 v[48:63], v[146:149], v[150:153], v[48:63]
	ds_read_b128 v[196:199], v109 offset:18464
	ds_read_b128 v[200:203], v110 offset:55328
	global_load_dwordx4 v[68:71], v174, s[98:99] offset:3968
	global_load_dwordx4 v[84:87], v176, s[98:99] offset:3968
	s_waitcnt vmcnt(9)
	ds_write_b128 v111, v[114:117]
	s_waitcnt lgkmcnt(4)
	v_mfma_f32_32x32x16_bf16 v[32:47], v[146:149], v[154:157], v[32:47]
	ds_read_b128 v[204:207], v110 offset:59936
	global_load_dwordx4 v[88:91], v178, s[98:99] offset:3968
	global_load_dwordx4 v[92:95], v180, s[98:99] offset:3968
	s_waitcnt lgkmcnt(4)
	v_mfma_f32_32x32x16_bf16 v[16:31], v[192:195], v[150:153], v[16:31]
	ds_read_b128 v[208:211], v109 offset:23072
	global_load_dwordx4 v[64:67], v182, s[98:99] offset:3968
	global_load_dwordx4 v[72:75], v184, s[98:99] offset:3968
	s_waitcnt vmcnt(12)
	ds_write_b128 v111, v[118:121] offset:4608
	v_mfma_f32_32x32x16_bf16 v[0:15], v[192:195], v[154:157], v[0:15]
	global_load_dwordx4 v[76:79], v186, s[98:99] offset:3968
	global_load_dwordx4 v[80:83], v188, s[98:99] offset:3968
	s_waitcnt lgkmcnt(4)
	v_mfma_f32_32x32x16_bf16 v[48:63], v[196:199], v[200:203], v[48:63]
	ds_read_b128 v[212:215], v109 offset:18496
	ds_read_b128 v[216:219], v110 offset:55360
	s_add_u32 s98, s98, 0x100
	s_addc_u32 s99, s99, 0
	s_add_i32 s12, s12, 2
	s_cmp_lt_u32 s12, 39
	s_waitcnt vmcnt(13)
	ds_write_b128 v111, v[122:125] offset:9216
	s_waitcnt lgkmcnt(5)
	v_mfma_f32_32x32x16_bf16 v[32:47], v[196:199], v[204:207], v[32:47]
	ds_read_b128 v[220:223], v110 offset:59968
	s_waitcnt lgkmcnt(5)
	v_mfma_f32_32x32x16_bf16 v[16:31], v[208:211], v[200:203], v[16:31]
	ds_read_b128 v[224:227], v109 offset:23104
	s_waitcnt vmcnt(12)
	ds_write_b128 v111, v[126:129] offset:13824
	v_mfma_f32_32x32x16_bf16 v[0:15], v[208:211], v[204:207], v[0:15]
	s_waitcnt lgkmcnt(4)
	v_mfma_f32_32x32x16_bf16 v[48:63], v[212:215], v[216:219], v[48:63]
	ds_read_b128 v[228:231], v109 offset:18528
	ds_read_b128 v[146:149], v110 offset:55392
	s_waitcnt vmcnt(11)
	ds_write_b128 v111, v[130:133] offset:36864
	s_waitcnt lgkmcnt(5)
	v_mfma_f32_32x32x16_bf16 v[32:47], v[212:215], v[220:223], v[32:47]
	ds_read_b128 v[150:153], v110 offset:60000
	s_waitcnt lgkmcnt(5)
	v_mfma_f32_32x32x16_bf16 v[16:31], v[224:227], v[216:219], v[16:31]
	ds_read_b128 v[154:157], v109 offset:23136
	s_waitcnt vmcnt(10)
	ds_write_b128 v111, v[134:137] offset:41472
	v_mfma_f32_32x32x16_bf16 v[0:15], v[224:227], v[220:223], v[0:15]
	s_waitcnt lgkmcnt(4)
	v_mfma_f32_32x32x16_bf16 v[48:63], v[228:231], v[146:149], v[48:63]
	s_waitcnt vmcnt(9)
	ds_write_b128 v111, v[138:141] offset:46080
	s_waitcnt lgkmcnt(3)
	v_mfma_f32_32x32x16_bf16 v[32:47], v[228:231], v[150:153], v[32:47]
	s_waitcnt lgkmcnt(2)
	v_mfma_f32_32x32x16_bf16 v[16:31], v[154:157], v[146:149], v[16:31]
	s_waitcnt vmcnt(8)
	ds_write_b128 v111, v[142:145] offset:50688
	v_mfma_f32_32x32x16_bf16 v[0:15], v[154:157], v[150:153], v[0:15]
	s_setprio 0
	s_waitcnt lgkmcnt(0)
	s_barrier
	s_cbranch_scc1 .LBB0_4051
	s_setprio 1
	ds_read_b128 v[104:107], v109
	ds_read_b128 v[114:117], v110 offset:36864
	ds_read_b128 v[118:121], v110 offset:41472
	ds_read_b128 v[192:195], v109 offset:4608
	s_waitcnt lgkmcnt(2)
	v_mfma_f32_32x32x16_bf16 v[48:63], v[104:107], v[114:117], v[48:63]
	ds_read_b128 v[196:199], v109 offset:32
	ds_read_b128 v[200:203], v110 offset:36896
	s_waitcnt vmcnt(7)
	ds_write_b128 v111, v[68:71] offset:18432
	s_waitcnt lgkmcnt(4)
	v_mfma_f32_32x32x16_bf16 v[32:47], v[104:107], v[118:121], v[32:47]
	ds_read_b128 v[204:207], v110 offset:41504
	s_waitcnt lgkmcnt(4)
	v_mfma_f32_32x32x16_bf16 v[16:31], v[192:195], v[114:117], v[16:31]
	ds_read_b128 v[208:211], v109 offset:4640
	s_waitcnt vmcnt(6)
	ds_write_b128 v111, v[84:87] offset:23040
	v_mfma_f32_32x32x16_bf16 v[0:15], v[192:195], v[118:121], v[0:15]
	s_waitcnt lgkmcnt(4)
	v_mfma_f32_32x32x16_bf16 v[48:63], v[196:199], v[200:203], v[48:63]
	ds_read_b128 v[212:215], v109 offset:64
	ds_read_b128 v[216:219], v110 offset:36928
	s_waitcnt vmcnt(5)
	ds_write_b128 v111, v[88:91] offset:27648
	s_waitcnt lgkmcnt(5)
	v_mfma_f32_32x32x16_bf16 v[32:47], v[196:199], v[204:207], v[32:47]
	ds_read_b128 v[220:223], v110 offset:41536
	s_waitcnt lgkmcnt(5)
	v_mfma_f32_32x32x16_bf16 v[16:31], v[208:211], v[200:203], v[16:31]
	ds_read_b128 v[224:227], v109 offset:4672
	s_waitcnt vmcnt(4)
	ds_write_b128 v111, v[92:95] offset:32256
	v_mfma_f32_32x32x16_bf16 v[0:15], v[208:211], v[204:207], v[0:15]
	s_waitcnt lgkmcnt(4)
	v_mfma_f32_32x32x16_bf16 v[48:63], v[212:215], v[216:219], v[48:63]
	ds_read_b128 v[228:231], v109 offset:96
	ds_read_b128 v[104:107], v110 offset:41568
	s_waitcnt vmcnt(3)
	ds_write_b128 v111, v[64:67] offset:55296
	s_waitcnt lgkmcnt(5)
	v_mfma_f32_32x32x16_bf16 v[32:47], v[212:215], v[220:223], v[32:47]
	ds_read_b128 v[114:117], v110 offset:36960
	ds_read_b128 v[118:121], v109 offset:4704
	s_waitcnt lgkmcnt(6)
	v_mfma_f32_32x32x16_bf16 v[16:31], v[224:227], v[216:219], v[16:31]
	s_waitcnt vmcnt(2)
	ds_write_b128 v111, v[72:75] offset:59904
	v_mfma_f32_32x32x16_bf16 v[0:15], v[224:227], v[220:223], v[0:15]
	s_waitcnt lgkmcnt(4)
	v_mfma_f32_32x32x16_bf16 v[32:47], v[228:231], v[104:107], v[32:47]
	s_waitcnt vmcnt(1)
	ds_write_b128 v111, v[76:79] offset:64512
	s_waitcnt lgkmcnt(2)
	v_mfma_f32_32x32x16_bf16 v[16:31], v[118:121], v[114:117], v[16:31]
	v_mfma_f32_32x32x16_bf16 v[0:15], v[118:121], v[104:107], v[0:15]
	s_waitcnt vmcnt(0)
	ds_write_b128 v112, v[80:83] offset:13824
	v_mfma_f32_32x32x16_bf16 v[48:63], v[228:231], v[114:117], v[48:63]
	s_setprio 0
	s_waitcnt lgkmcnt(0)
	s_barrier
	s_setprio 1
	ds_read_b128 v[64:67], v109 offset:18432
	ds_read_b128 v[68:71], v110 offset:55296
	ds_read_b128 v[72:75], v110 offset:59904
	ds_read_b128 v[192:195], v109 offset:23040
	s_waitcnt lgkmcnt(2)
	v_mfma_f32_32x32x16_bf16 v[48:63], v[64:67], v[68:71], v[48:63]
	ds_read_b128 v[196:199], v109 offset:18464
	ds_read_b128 v[200:203], v110 offset:55328
	s_waitcnt lgkmcnt(3)
	v_mfma_f32_32x32x16_bf16 v[32:47], v[64:67], v[72:75], v[32:47]
	ds_read_b128 v[204:207], v110 offset:59936
	s_waitcnt lgkmcnt(3)
	v_mfma_f32_32x32x16_bf16 v[16:31], v[192:195], v[68:71], v[16:31]
	ds_read_b128 v[208:211], v109 offset:23072
	v_mfma_f32_32x32x16_bf16 v[0:15], v[192:195], v[72:75], v[0:15]
	s_waitcnt lgkmcnt(2)
	v_mfma_f32_32x32x16_bf16 v[48:63], v[196:199], v[200:203], v[48:63]
	ds_read_b128 v[212:215], v109 offset:18496
	ds_read_b128 v[216:219], v110 offset:55360
	s_waitcnt lgkmcnt(3)
	v_mfma_f32_32x32x16_bf16 v[32:47], v[196:199], v[204:207], v[32:47]
	ds_read_b128 v[220:223], v110 offset:59968
	s_waitcnt lgkmcnt(3)
	v_mfma_f32_32x32x16_bf16 v[16:31], v[208:211], v[200:203], v[16:31]
	ds_read_b128 v[224:227], v109 offset:23104
	v_mfma_f32_32x32x16_bf16 v[0:15], v[208:211], v[204:207], v[0:15]
	s_waitcnt lgkmcnt(2)
	v_mfma_f32_32x32x16_bf16 v[48:63], v[212:215], v[216:219], v[48:63]
	ds_read_b128 v[228:231], v109 offset:18528
	ds_read_b128 v[64:67], v110 offset:60000
	s_waitcnt lgkmcnt(3)
	v_mfma_f32_32x32x16_bf16 v[32:47], v[212:215], v[220:223], v[32:47]
	ds_read_b128 v[68:71], v110 offset:55392
	ds_read_b128 v[72:75], v109 offset:23136
	s_waitcnt lgkmcnt(4)
	v_mfma_f32_32x32x16_bf16 v[16:31], v[224:227], v[216:219], v[16:31]
	v_mfma_f32_32x32x16_bf16 v[0:15], v[224:227], v[220:223], v[0:15]
	s_waitcnt lgkmcnt(2)
	v_mfma_f32_32x32x16_bf16 v[32:47], v[228:231], v[64:67], v[32:47]
	s_waitcnt lgkmcnt(0)
	v_mfma_f32_32x32x16_bf16 v[16:31], v[72:75], v[68:71], v[16:31]
	v_mfma_f32_32x32x16_bf16 v[0:15], v[72:75], v[64:67], v[0:15]
	v_mfma_f32_32x32x16_bf16 v[48:63], v[228:231], v[68:71], v[48:63]
	s_setprio 0
	s_addk_i32 s0, 0xf000
	s_lshr_b32 s12, s0, 10
	s_mulk_i32 s12, 0x1800
	s_add_i32 s12, s12, 0x9000
	s_and_b64 s[66:67], s[4:5], exec
	s_cselect_b32 s12, 0x7800, s12
	v_mov_b32_e32 v68, v234
	s_barrier
	s_lshl_b64 s[66:67], s[12:13], 2
	s_add_u32 s66, s30, s66
	v_and_b32_e32 v69, 0x5f, v68
	v_or_b32_e32 v64, s27, v69
	s_addc_u32 s67, s31, s67
	v_ashrrev_i32_e32 v65, 31, v64
	v_lshl_add_u64 v[64:65], v[64:65], 2, s[66:67]
	v_lshl_add_u64 v[66:67], v[64:65], 0, s[16:17]
	v_add_co_u32_e32 v64, vcc, s56, v64
	v_lshlrev_b32_e32 v69, 2, v69
	s_nop 0
	v_addc_co_u32_e32 v65, vcc, 0, v65, vcc
	global_load_dword v64, v[64:65], off
	s_nop 0
	global_load_dword v65, v[66:67], off offset:128
	v_lshrrev_b32_e32 v67, 3, v68
	v_lshrrev_b32_e32 v66, 1, v68
	v_and_b32_e32 v67, 4, v67
	v_and_or_b32 v66, v66, s47, v67
	v_mul_lo_u32 v66, v66, s57
	v_add3_u32 v66, 32, v69, v66
	v_add_u32_e32 v67, 0x400, v66
	v_add_u32_e32 v69, 0x1000, v66
	v_add_u32_e32 v70, 0x1400, v66
	v_add_u32_e32 v71, 0x2000, v66
	v_add_u32_e32 v72, 0x2400, v66
	v_add_u32_e32 v73, 0x3000, v66
	v_add_u32_e32 v74, 0x3200, v66
	v_add_u32_e32 v75, 0x3400, v66
	v_add_u32_e32 v76, 0x3600, v66
	v_add_u32_e32 v77, 0x4000, v66
	s_lshl_b32 s1, s1, 19
	s_add_u32 s12, s19, s1
	s_mov_b32 s1, s13
	s_waitcnt vmcnt(1)
	v_mul_f32_e32 v48, v48, v64
	s_waitcnt vmcnt(0)
	v_mul_f32_e32 v32, v32, v65
	v_mul_f32_e32 v16, v16, v64
	v_mul_f32_e32 v0, v0, v65
	v_mul_f32_e32 v49, v49, v64
	v_mul_f32_e32 v33, v33, v65
	v_mul_f32_e32 v50, v50, v64
	v_mul_f32_e32 v34, v34, v65
	v_mul_f32_e32 v51, v51, v64
	v_mul_f32_e32 v35, v35, v65
	v_mul_f32_e32 v52, v52, v64
	v_mul_f32_e32 v36, v36, v65
	v_mul_f32_e32 v53, v53, v64
	v_mul_f32_e32 v37, v37, v65
	v_mul_f32_e32 v54, v54, v64
	v_mul_f32_e32 v38, v38, v65
	v_mul_f32_e32 v55, v55, v64
	v_mul_f32_e32 v39, v39, v65
	v_mul_f32_e32 v56, v56, v64
	v_mul_f32_e32 v40, v40, v65
	v_mul_f32_e32 v57, v57, v64
	v_mul_f32_e32 v41, v41, v65
	v_mul_f32_e32 v58, v58, v64
	v_mul_f32_e32 v42, v42, v65
	v_mul_f32_e32 v59, v59, v64
	v_mul_f32_e32 v43, v43, v65
	v_mul_f32_e32 v60, v60, v64
	v_mul_f32_e32 v44, v44, v65
	v_mul_f32_e32 v61, v61, v64
	v_mul_f32_e32 v45, v45, v65
	v_mul_f32_e32 v62, v62, v64
	v_mul_f32_e32 v46, v46, v65
	v_mul_f32_e32 v63, v63, v64
	v_mul_f32_e32 v47, v47, v65
	ds_write2_b32 v66, v48, v32 offset1:32
	ds_write2_b32 v66, v49, v33 offset0:132 offset1:164
	ds_write2_b32 v67, v50, v34 offset0:8 offset1:40
	ds_write2_b32 v67, v51, v35 offset0:140 offset1:172
	ds_write2_b32 v69, v52, v36 offset0:32 offset1:64
	ds_write2_b32 v69, v53, v37 offset0:164 offset1:196
	ds_write2_b32 v70, v54, v38 offset0:40 offset1:72
	ds_write2_b32 v70, v55, v39 offset0:172 offset1:204
	ds_write2_b32 v71, v56, v40 offset0:64 offset1:96
	ds_write2_b32 v71, v57, v41 offset0:196 offset1:228
	ds_write2_b32 v72, v58, v42 offset0:72 offset1:104
	ds_write2_b32 v72, v59, v43 offset0:204 offset1:236
	ds_write2_b32 v73, v60, v44 offset0:96 offset1:128
	ds_write2_b32 v74, v61, v45 offset0:100 offset1:132
	ds_write2_b32 v75, v62, v46 offset0:104 offset1:136
	ds_write2_b32 v76, v63, v47 offset0:108 offset1:140
	ds_write2_b32 v77, v16, v0 offset0:128 offset1:160
	v_mul_f32_e32 v0, v17, v64
	v_mul_f32_e32 v1, v1, v65
	v_add_u32_e32 v16, 0x4400, v66
	ds_write2_b32 v16, v0, v1 offset0:4 offset1:36
	v_mul_f32_e32 v0, v18, v64
	v_mul_f32_e32 v1, v2, v65
	ds_write2_b32 v16, v0, v1 offset0:136 offset1:168
	v_mul_f32_e32 v0, v19, v64
	v_mul_f32_e32 v1, v3, v65
	v_add_u32_e32 v2, 0x4800, v66
	ds_write2_b32 v2, v0, v1 offset0:12 offset1:44
	v_mul_f32_e32 v0, v20, v64
	v_mul_f32_e32 v1, v4, v65
	v_add_u32_e32 v2, 0x5000, v66
	ds_write2_b32 v2, v0, v1 offset0:160 offset1:192
	v_mul_f32_e32 v0, v21, v64
	v_mul_f32_e32 v1, v5, v65
	v_add_u32_e32 v2, 0x5400, v66
	ds_write2_b32 v2, v0, v1 offset0:36 offset1:68
	v_mul_f32_e32 v0, v22, v64
	v_mul_f32_e32 v1, v6, v65
	ds_write2_b32 v2, v0, v1 offset0:168 offset1:200
	v_mul_f32_e32 v0, v23, v64
	v_mul_f32_e32 v1, v7, v65
	v_add_u32_e32 v2, 0x5800, v66
	ds_write2_b32 v2, v0, v1 offset0:44 offset1:76
	v_mul_f32_e32 v0, v24, v64
	v_mul_f32_e32 v1, v8, v65
	v_add_u32_e32 v2, 0x6000, v66
	ds_write2_b32 v2, v0, v1 offset0:192 offset1:224
	v_mul_f32_e32 v0, v25, v64
	v_mul_f32_e32 v1, v9, v65
	v_add_u32_e32 v2, 0x6400, v66
	ds_write2_b32 v2, v0, v1 offset0:68 offset1:100
	v_mul_f32_e32 v0, v26, v64
	v_mul_f32_e32 v1, v10, v65
	ds_write2_b32 v2, v0, v1 offset0:200 offset1:232
	v_mul_f32_e32 v0, v27, v64
	v_mul_f32_e32 v1, v11, v65
	v_add_u32_e32 v2, 0x6800, v66
	ds_write2_b32 v2, v0, v1 offset0:76 offset1:108
	v_mul_f32_e32 v0, v28, v64
	v_mul_f32_e32 v1, v12, v65
	v_add_u32_e32 v2, 0x7200, v66
	ds_write2_b32 v2, v0, v1 offset0:96 offset1:128
	v_mul_f32_e32 v0, v29, v64
	v_mul_f32_e32 v1, v13, v65
	v_add_u32_e32 v2, 0x7400, v66
	ds_write2_b32 v2, v0, v1 offset0:100 offset1:132
	v_mul_f32_e32 v0, v30, v64
	v_mul_f32_e32 v1, v14, v65
	v_add_u32_e32 v2, 0x7600, v66
	v_and_b32_e32 v12, 31, v68
	ds_write2_b32 v2, v0, v1 offset0:104 offset1:136
	v_mul_f32_e32 v0, v31, v64
	v_mul_f32_e32 v1, v15, v65
	v_add_u32_e32 v2, 0x7800, v66
	v_lshlrev_b32_e32 v8, 2, v12
	ds_write2_b32 v2, v0, v1 offset0:108 offset1:140
	v_or_b32_e32 v0, s27, v8
	v_ashrrev_i32_e32 v1, 31, v0
	v_lshlrev_b64 v[0:1], 2, v[0:1]
	v_lshl_add_u64 v[2:3], s[6:7], 0, v[0:1]
	v_lshl_add_u64 v[4:5], s[8:9], 0, v[0:1]
	s_waitcnt lgkmcnt(0)
	s_barrier
	global_load_dwordx4 v[0:3], v[2:3], off
	s_nop 0
	global_load_dwordx4 v[4:7], v[4:5], off
	v_and_b32_e32 v9, 64, v108
	v_add_u32_e32 v9, 64, v9
	v_xor_b32_e32 v10, 1, v108
	v_cmp_lt_i32_e32 vcc, v10, v9
	s_addc_u32 s27, s21, 0
	s_lshl_b64 s[0:1], s[0:1], 12
	v_cndmask_b32_e32 v10, v108, v10, vcc
	v_lshlrev_b32_e32 v32, 2, v10
	v_xor_b32_e32 v10, 2, v108
	v_cmp_lt_i32_e32 vcc, v10, v9
	s_add_u32 s63, s33, s0
	s_addc_u32 s65, s34, s1
	v_cndmask_b32_e32 v10, v108, v10, vcc
	v_lshlrev_b32_e32 v33, 2, v10
	v_xor_b32_e32 v10, 4, v108
	v_cmp_lt_i32_e32 vcc, v10, v9
	s_and_b64 s[0:1], s[4:5], exec
	v_ashrrev_i32_e32 v22, 5, v68
	v_cndmask_b32_e32 v10, v108, v10, vcc
	v_lshlrev_b32_e32 v34, 2, v10
	v_xor_b32_e32 v10, 8, v108
	s_cselect_b32 s67, s27, s65
	s_cselect_b32 s66, s12, s63
	v_cmp_lt_i32_e32 vcc, v10, v9
	s_add_i32 s12, s26, s39
	v_add_u32_e32 v16, s12, v22
	v_cndmask_b32_e32 v10, v108, v10, vcc
	s_add_i32 s12, s26, s40
	s_add_i32 s26, s26, s41
	v_lshlrev_b32_e32 v35, 2, v10
	v_xor_b32_e32 v10, 16, v108
	v_add_u32_e32 v20, s12, v22
	v_add_u32_e32 v24, s26, v22
	v_cmp_eq_u32_e64 s[0:1], 0, v12
	v_cmp_lt_i32_e32 vcc, v10, v9
	v_ashrrev_i32_e32 v23, 31, v22
	v_mul_lo_u32 v13, v22, s57
	v_lshlrev_b32_e32 v12, 4, v12
	v_add_u32_e32 v26, s25, v22
	v_ashrrev_i32_e32 v17, 31, v16
	v_ashrrev_i32_e32 v21, 31, v20
	v_ashrrev_i32_e32 v25, 31, v24
	v_cndmask_b32_e32 v9, v108, v10, vcc
	v_add_u32_e32 v8, s24, v8
	v_lshlrev_b64 v[10:11], 12, v[22:23]
	v_add3_u32 v37, v13, v12, 32
	v_lshlrev_b32_e32 v12, 1, v26
	v_lshlrev_b64 v[14:15], 12, v[16:17]
	v_lshlrev_b32_e32 v16, 1, v16
	v_lshlrev_b64 v[18:19], 12, v[20:21]
	v_lshlrev_b32_e32 v20, 1, v20
	v_lshlrev_b64 v[22:23], 12, v[24:25]
	v_lshlrev_b32_e32 v24, 1, v24
	v_ashrrev_i32_e32 v27, 31, v26
	v_lshlrev_b32_e32 v36, 2, v9
	v_ashrrev_i32_e32 v9, 31, v8
	v_ashrrev_i32_e32 v13, 31, v12
	v_ashrrev_i32_e32 v17, 31, v16
	v_ashrrev_i32_e32 v21, 31, v20
	v_ashrrev_i32_e32 v25, 31, v24
	v_lshlrev_b64 v[26:27], 12, v[26:27]
	v_lshlrev_b64 v[8:9], 2, v[8:9]
	v_lshl_add_u64 v[10:11], s[66:67], 0, v[10:11]
	v_lshl_add_u64 v[12:13], v[12:13], 2, s[30:31]
	v_lshl_add_u64 v[14:15], s[28:29], 0, v[14:15]
	v_lshl_add_u64 v[16:17], v[16:17], 2, s[30:31]
	v_lshl_add_u64 v[18:19], s[28:29], 0, v[18:19]
	v_lshl_add_u64 v[20:21], v[20:21], 2, s[30:31]
	v_lshl_add_u64 v[22:23], s[28:29], 0, v[22:23]
	v_lshl_add_u64 v[24:25], v[24:25], 2, s[30:31]
	v_lshl_add_u64 v[26:27], s[10:11], 0, v[26:27]
	s_mov_b64 s[24:25], 0
	s_branch .LBB0_4054
